# v32 without the per-phase s_setprio flips (stagger only)
# baseline (speedup 1.0000x reference)
; #define LAS __attribute__((address_space(3)))
; DI void expsum(f32x16& p, float& l_reg, bf16x8& pa0, bf16x8& pa1) {
; #pragma unroll
;     for (int r = 0; r < 16; ++r) p[r] = __builtin_amdgcn_exp2f(p[r]);
;     float ps = 0.f;
; #pragma unroll
;     for (int r = 0; r < 16; ++r) ps += p[r];
;     l_reg += ps; asm volatile("" : "+v"(l_reg));
;     ...
;     ATT_PK4(p, 0, pa0); ATT_PK4(p, 8, pa1);
;     ...
; }
; DI int v_rd_base(int lane) { return ((lane & 3) << 3) | (((lane >> 2) & 3) << 6) | (((lane >> 4) & 1) << 5) | (((lane >> 5) & 1) << 8); }
; template <int OFF> DI s16x4 tr_read(int vb) { s16x4 r; asm volatile("ds_read_b64_tr_b16 %0, %1 offset:%2" : "=&v"(r) : "v"(vb), "i"(OFF) : "memory"); return r; }
; template <int H> DI void v_reads(s16x4* vf, int vb) {
;     vf[0] = tr_read<v_rd_off(0, 2 * H, 0)>(vb); vf[1] = tr_read<v_rd_off(0, 2 * H, 1)>(vb); vf[2] = tr_read<v_rd_off(0, 2 * H + 1, 0)>(vb); vf[3] = tr_read<v_rd_off(0, 2 * H + 1, 1)>(vb);
;     vf[4] = tr_read<v_rd_off(1, 2 * H, 0)>(vb); vf[5] = tr_read<v_rd_off(1, 2 * H, 1)>(vb); vf[6] = tr_read<v_rd_off(1, 2 * H + 1, 0)>(vb); vf[7] = tr_read<v_rd_off(1, 2 * H + 1, 1)>(vb);
;     vf[8] = tr_read<v_rd_off(2, 2 * H, 0)>(vb); vf[9] = tr_read<v_rd_off(2, 2 * H, 1)>(vb); vf[10] = tr_read<v_rd_off(2, 2 * H + 1, 0)>(vb); vf[11] = tr_read<v_rd_off(2, 2 * H + 1, 1)>(vb);
;     vf[12] = tr_read<v_rd_off(3, 2 * H, 0)>(vb); vf[13] = tr_read<v_rd_off(3, 2 * H, 1)>(vb); vf[14] = tr_read<v_rd_off(3, 2 * H + 1, 0)>(vb); vf[15] = tr_read<v_rd_off(3, 2 * H + 1, 1)>(vb);
; }
; DI void pv_mma(f32x16* o, const s16x4* vf, bf16x8 pa0, bf16x8 pa1) {
;     ...
; #pragma unroll
;     for (int d0 = 0; d0 < 4; ++d0) {
;         o[d0] = __builtin_amdgcn_mfma_f32_32x32x16_bf16(pa0, ATT_PK(vf[4 * d0], vf[4 * d0 + 1]), o[d0], 0, 0, 0);
;         o[d0] = __builtin_amdgcn_mfma_f32_32x32x16_bf16(pa1, ATT_PK(vf[4 * d0 + 2], vf[4 * d0 + 3]), o[d0], 0, 0, 0); }
;     ...
; }
; template <int DQK, int D0A, int D0B> DI void k_reads(bf16x8* kf, const LAS unsigned char* Ks, int half, int r32, int hi) {
; #pragma unroll
;     for (int d0 = D0A; d0 < D0B; ++d0) kf[d0 - D0A] = *(const LAS bf16x8*)(Ks + half * (32 * DQK * 2) + kswz<DQK>(r32, (d0 * 16 + hi * 8) * 2));
; }
; template <int D0A, int D0B> DI void qk_mma(f32x16& p, const bf16x8* kf, const bf16x8* qr) {
; #pragma unroll
;     for (int d0 = D0A; d0 < D0B; ++d0) {
.LBB0_1922:
	s_add_i32 s3, s0, -1
	s_add_i32 s2, s22, 0xffffa000
	s_and_b32 s2, s2, 0x6000
	v_add_u32_e32 v121, s2, v114
	v_add_u32_e32 v122, v121, v115
	v_add_u32_e32 v126, v121, v116
	ds_read_b128 v[122:125], v122 offset:4096
	ds_read_b128 v[132:135], v126 offset:4096
	v_add_u32_e32 v126, v121, v117
	v_add_u32_e32 v121, v121, v118
	s_lshl_b32 s2, s1, 14
	ds_read_b128 v[136:139], v126 offset:4096
	ds_read_b128 v[140:143], v121 offset:4096
	v_add_u32_e32 v121, s2, v106
	ds_read_b64_tr_b16 v[144:145], v121 offset:0
	ds_read_b64_tr_b16 v[146:147], v121 offset:0x800
	ds_read_b64_tr_b16 v[148:149], v121 offset:0x1000
	ds_read_b64_tr_b16 v[150:151], v121 offset:0x1800
	ds_read_b64_tr_b16 v[152:153], v121 offset:0x200
	ds_read_b64_tr_b16 v[154:155], v121 offset:0xa00
	ds_read_b64_tr_b16 v[156:157], v121 offset:0x1200
	ds_read_b64_tr_b16 v[158:159], v121 offset:0x1a00
	ds_read_b64_tr_b16 v[162:163], v121 offset:0x400
	ds_read_b64_tr_b16 v[164:165], v121 offset:0xc00
	ds_read_b64_tr_b16 v[166:167], v121 offset:0x1400
	ds_read_b64_tr_b16 v[168:169], v121 offset:0x1c00
	ds_read_b64_tr_b16 v[170:171], v121 offset:0x600
	ds_read_b64_tr_b16 v[172:173], v121 offset:0xe00
	ds_read_b64_tr_b16 v[174:175], v121 offset:0x1600
	ds_read_b64_tr_b16 v[176:177], v121 offset:0x1e00
	v_exp_f32_e32 v64, v64
	v_exp_f32_e32 v65, v65
	v_exp_f32_e32 v66, v66
	v_exp_f32_e32 v67, v67
	v_exp_f32_e32 v68, v68
	v_add_f32_e32 v126, 0, v64
	v_exp_f32_e32 v69, v69
	v_add_f32_e32 v126, v65, v126
	v_exp_f32_e32 v70, v70
	v_add_f32_e32 v126, v66, v126
	v_exp_f32_e32 v71, v71
	v_add_f32_e32 v126, v67, v126
	v_exp_f32_e32 v72, v72
	v_add_f32_e32 v126, v68, v126
	v_exp_f32_e32 v73, v73
	v_add_f32_e32 v126, v69, v126
	v_exp_f32_e32 v74, v74
	v_add_f32_e32 v126, v70, v126
	v_exp_f32_e32 v75, v75
	v_add_f32_e32 v126, v71, v126
	v_exp_f32_e32 v76, v76
	v_add_f32_e32 v126, v72, v126
	v_exp_f32_e32 v77, v77
	v_add_f32_e32 v126, v73, v126
	v_exp_f32_e32 v78, v78
	v_add_f32_e32 v126, v74, v126
	v_exp_f32_e32 v79, v79
	v_add_f32_e32 v126, v75, v126
	v_add_f32_e32 v126, v76, v126
	v_add_f32_e32 v126, v77, v126
	v_add_f32_e32 v126, v78, v126
	v_add_f32_e32 v126, v79, v126
	v_add_f32_e32 v120, v126, v120
	v_cvt_pk_bf16_f32 v64, v64, v65
	v_cvt_pk_bf16_f32 v65, v66, v67
	v_cvt_pk_bf16_f32 v66, v68, v69
	v_cvt_pk_bf16_f32 v67, v70, v71
	v_cvt_pk_bf16_f32 v68, v72, v73
	v_cvt_pk_bf16_f32 v69, v74, v75
	v_cvt_pk_bf16_f32 v70, v76, v77
	v_cvt_pk_bf16_f32 v71, v78, v79
	s_nop 0
	v_permlane32_swap_b32_e32 v64, v66
	v_permlane32_swap_b32_e32 v65, v67
	v_permlane32_swap_b32_e32 v68, v70
	v_permlane32_swap_b32_e32 v69, v71
	s_waitcnt lgkmcnt(0)
	v_mfma_f32_32x32x16_bf16 v[0:15], v[64:67], v[144:147], v[0:15]
	s_cmp_lt_i32 s3, s55
	s_cselect_b64 vcc, -1, 0
	s_cmp_ge_i32 s3, s97
	s_cselect_b64 s[74:75], -1, 0
	s_or_b64 s[74:75], vcc, s[74:75]
	s_and_b64 vcc, exec, s[74:75]
	v_mfma_f32_32x32x16_bf16 v[48:63], v[64:67], v[152:155], v[48:63]
	v_mfma_f32_32x32x16_bf16 v[32:47], v[64:67], v[162:165], v[32:47]
	v_mfma_f32_32x32x16_bf16 v[16:31], v[64:67], v[170:173], v[16:31]
	v_mfma_f32_32x32x16_bf16 v[0:15], v[68:71], v[148:151], v[0:15]
	v_mfma_f32_32x32x16_bf16 v[48:63], v[68:71], v[156:159], v[48:63]
	v_mfma_f32_32x32x16_bf16 v[32:47], v[68:71], v[166:169], v[32:47]
	v_mfma_f32_32x32x16_bf16 v[16:31], v[68:71], v[174:177], v[16:31]
	v_mfma_f32_32x32x16_bf16 v[64:79], v[122:125], v[92:95], 0
	v_mfma_f32_32x32x16_bf16 v[64:79], v[132:135], v[88:91], v[64:79]
	v_mfma_f32_32x32x16_bf16 v[64:79], v[136:139], v[84:87], v[64:79]
	v_mfma_f32_32x32x16_bf16 v[64:79], v[140:143], v[80:83], v[64:79]
	v_add_u32_e32 v122, s7, v119
	s_cbranch_vccnz .LBB0_1924
	v_add_u32_e32 v138, 0x28908, v122
	v_add_u32_e32 v140, 0x28920, v122
	v_add_u32_e32 v142, 0x28928, v122
	v_add_u32_e32 v124, 0x28940, v122
	v_add_u32_e32 v126, 0x28948, v122
	v_add_u32_e32 v132, 0x28960, v122
	v_add_u32_e32 v134, 0x28968, v122
	v_add_u32_e32 v123, 0x28900, v122
	ds_read2_b32 v[124:125], v124 offset1:1
	ds_read2_b32 v[126:127], v126 offset1:1
	ds_read2_b32 v[132:133], v132 offset1:1
	ds_read2_b32 v[134:135], v134 offset1:1
	ds_read2_b32 v[136:137], v123 offset1:1
	ds_read2_b32 v[138:139], v138 offset1:1
	ds_read2_b32 v[140:141], v140 offset1:1
	ds_read2_b32 v[142:143], v142 offset1:1
	s_waitcnt lgkmcnt(0)
	v_pk_add_f32 v[78:79], v[78:79], v[134:135]
	v_pk_add_f32 v[76:77], v[76:77], v[132:133]
	v_pk_add_f32 v[74:75], v[74:75], v[126:127]
	v_pk_add_f32 v[72:73], v[72:73], v[124:125]
	v_pk_add_f32 v[70:71], v[70:71], v[142:143]
	v_pk_add_f32 v[68:69], v[68:69], v[140:141]
	v_pk_add_f32 v[66:67], v[66:67], v[138:139]
	v_pk_add_f32 v[64:65], v[64:65], v[136:137]
; #define LAS __attribute__((address_space(3)))
; DI void expsum(f32x16& p, float& l_reg, bf16x8& pa0, bf16x8& pa1) {
; #pragma unroll
;     for (int r = 0; r < 16; ++r) p[r] = __builtin_amdgcn_exp2f(p[r]);
;     float ps = 0.f;
; #pragma unroll
;     for (int r = 0; r < 16; ++r) ps += p[r];
;     l_reg += ps; asm volatile("" : "+v"(l_reg));
;     ...
;     ATT_PK4(p, 0, pa0); ATT_PK4(p, 8, pa1);
;     ...
; }
; DI int v_rd_base(int lane) { return ((lane & 3) << 3) | (((lane >> 2) & 3) << 6) | (((lane >> 4) & 1) << 5) | (((lane >> 5) & 1) << 8); }
; template <int OFF> DI s16x4 tr_read(int vb) { s16x4 r; asm volatile("ds_read_b64_tr_b16 %0, %1 offset:%2" : "=&v"(r) : "v"(vb), "i"(OFF) : "memory"); return r; }
; template <int H> DI void v_reads(s16x4* vf, int vb) {
;     vf[0] = tr_read<v_rd_off(0, 2 * H, 0)>(vb); vf[1] = tr_read<v_rd_off(0, 2 * H, 1)>(vb); vf[2] = tr_read<v_rd_off(0, 2 * H + 1, 0)>(vb); vf[3] = tr_read<v_rd_off(0, 2 * H + 1, 1)>(vb);
;     vf[4] = tr_read<v_rd_off(1, 2 * H, 0)>(vb); vf[5] = tr_read<v_rd_off(1, 2 * H, 1)>(vb); vf[6] = tr_read<v_rd_off(1, 2 * H + 1, 0)>(vb); vf[7] = tr_read<v_rd_off(1, 2 * H + 1, 1)>(vb);
;     vf[8] = tr_read<v_rd_off(2, 2 * H, 0)>(vb); vf[9] = tr_read<v_rd_off(2, 2 * H, 1)>(vb); vf[10] = tr_read<v_rd_off(2, 2 * H + 1, 0)>(vb); vf[11] = tr_read<v_rd_off(2, 2 * H + 1, 1)>(vb);
;     vf[12] = tr_read<v_rd_off(3, 2 * H, 0)>(vb); vf[13] = tr_read<v_rd_off(3, 2 * H, 1)>(vb); vf[14] = tr_read<v_rd_off(3, 2 * H + 1, 0)>(vb); vf[15] = tr_read<v_rd_off(3, 2 * H + 1, 1)>(vb);
; }
; DI void pv_mma(f32x16* o, const s16x4* vf, bf16x8 pa0, bf16x8 pa1) {
;     ...
; #pragma unroll
;     for (int d0 = 0; d0 < 4; ++d0) {
;         o[d0] = __builtin_amdgcn_mfma_f32_32x32x16_bf16(pa0, ATT_PK(vf[4 * d0], vf[4 * d0 + 1]), o[d0], 0, 0, 0);
;         o[d0] = __builtin_amdgcn_mfma_f32_32x32x16_bf16(pa1, ATT_PK(vf[4 * d0 + 2], vf[4 * d0 + 3]), o[d0], 0, 0, 0); }
;     ...
; }
; template <int DQK, int D0A, int D0B> DI void k_reads(bf16x8* kf, const LAS unsigned char* Ks, int half, int r32, int hi) {
; #pragma unroll
;     for (int d0 = D0A; d0 < D0B; ++d0) kf[d0 - D0A] = *(const LAS bf16x8*)(Ks + half * (32 * DQK * 2) + kswz<DQK>(r32, (d0 * 16 + hi * 8) * 2));
; }
; template <int D0A, int D0B> DI void qk_mma(f32x16& p, const bf16x8* kf, const bf16x8* qr) {
; #pragma unroll
;     for (int d0 = D0A; d0 < D0B; ++d0) {
.LBB0_1924:
	s_add_i32 s3, s22, 0xffffc000
	s_and_b32 s3, s3, 0x6000
	v_add_u32_e32 v123, s3, v114
	v_add_u32_e32 v140, v123, v118
	v_add_u32_e32 v136, v123, v117
	v_add_u32_e32 v132, v123, v116
	v_add_u32_e32 v123, v123, v115
	ds_read_b128 v[124:127], v123
	ds_read_b128 v[132:135], v132
	ds_read_b128 v[136:139], v136
	ds_read_b128 v[140:143], v140
	ds_read_b64_tr_b16 v[144:145], v121 offset:0x2000
	ds_read_b64_tr_b16 v[146:147], v121 offset:0x2800
	ds_read_b64_tr_b16 v[148:149], v121 offset:0x3000
	ds_read_b64_tr_b16 v[150:151], v121 offset:0x3800
	ds_read_b64_tr_b16 v[152:153], v121 offset:0x2200
	ds_read_b64_tr_b16 v[154:155], v121 offset:0x2a00
	ds_read_b64_tr_b16 v[156:157], v121 offset:0x3200
	ds_read_b64_tr_b16 v[158:159], v121 offset:0x3a00
	ds_read_b64_tr_b16 v[162:163], v121 offset:0x2400
	ds_read_b64_tr_b16 v[164:165], v121 offset:0x2c00
	ds_read_b64_tr_b16 v[166:167], v121 offset:0x3400
	ds_read_b64_tr_b16 v[168:169], v121 offset:0x3c00
	ds_read_b64_tr_b16 v[170:171], v121 offset:0x2600
	ds_read_b64_tr_b16 v[172:173], v121 offset:0x2e00
	ds_read_b64_tr_b16 v[174:175], v121 offset:0x3600
	ds_read_b64_tr_b16 v[176:177], v121 offset:0x3e00
	v_exp_f32_e32 v64, v64
	v_exp_f32_e32 v65, v65
	v_exp_f32_e32 v66, v66
	v_exp_f32_e32 v67, v67
	v_exp_f32_e32 v68, v68
	v_add_f32_e32 v121, 0, v64
	v_exp_f32_e32 v69, v69
	v_add_f32_e32 v121, v65, v121
	v_exp_f32_e32 v70, v70
	v_add_f32_e32 v121, v66, v121
	v_exp_f32_e32 v71, v71
	v_add_f32_e32 v121, v67, v121
	v_exp_f32_e32 v72, v72
	v_add_f32_e32 v121, v68, v121
	v_exp_f32_e32 v73, v73
	v_add_f32_e32 v121, v69, v121
	v_exp_f32_e32 v74, v74
	v_add_f32_e32 v121, v70, v121
	v_exp_f32_e32 v75, v75
	v_add_f32_e32 v121, v71, v121
	v_exp_f32_e32 v76, v76
	v_add_f32_e32 v121, v72, v121
	v_exp_f32_e32 v77, v77
	v_add_f32_e32 v121, v73, v121
	v_exp_f32_e32 v78, v78
	v_add_f32_e32 v121, v74, v121
	v_exp_f32_e32 v79, v79
	v_add_f32_e32 v121, v75, v121
	v_add_f32_e32 v121, v76, v121
	v_add_f32_e32 v121, v77, v121
	v_add_f32_e32 v121, v78, v121
	v_add_f32_e32 v121, v79, v121
	v_add_f32_e32 v120, v120, v121
	v_cvt_pk_bf16_f32 v64, v64, v65
	v_cvt_pk_bf16_f32 v65, v66, v67
	v_cvt_pk_bf16_f32 v66, v68, v69
	v_cvt_pk_bf16_f32 v67, v70, v71
	v_cvt_pk_bf16_f32 v68, v72, v73
	v_cvt_pk_bf16_f32 v69, v74, v75
	v_cvt_pk_bf16_f32 v70, v76, v77
	v_cvt_pk_bf16_f32 v71, v78, v79
	s_nop 0
	v_permlane32_swap_b32_e32 v64, v66
	v_permlane32_swap_b32_e32 v65, v67
	v_permlane32_swap_b32_e32 v68, v70
	v_permlane32_swap_b32_e32 v69, v71
	s_waitcnt lgkmcnt(0)
	s_cmp_lt_u32 s33, 0x100
	s_cbranch_scc1 .Lstg_d0_mid_11
	s_waitcnt vmcnt(3)
	s_barrier

; #define LAS __attribute__((address_space(3)))
; DI void expsum(f32x16& p, float& l_reg, bf16x8& pa0, bf16x8& pa1) {
; #pragma unroll
;     for (int r = 0; r < 16; ++r) p[r] = __builtin_amdgcn_exp2f(p[r]);
;     float ps = 0.f;
; #pragma unroll
;     for (int r = 0; r < 16; ++r) ps += p[r];
;     l_reg += ps; asm volatile("" : "+v"(l_reg));
;     ...
;     ATT_PK4(p, 0, pa0); ATT_PK4(p, 8, pa1);
;     ...
; }
; DI int v_rd_base(int lane) { return ((lane & 3) << 3) | (((lane >> 2) & 3) << 6) | (((lane >> 4) & 1) << 5) | (((lane >> 5) & 1) << 8); }
; template <int OFF> DI s16x4 tr_read(int vb) { s16x4 r; asm volatile("ds_read_b64_tr_b16 %0, %1 offset:%2" : "=&v"(r) : "v"(vb), "i"(OFF) : "memory"); return r; }
; template <int H> DI void v_reads(s16x4* vf, int vb) {
;     vf[0] = tr_read<v_rd_off(0, 2 * H, 0)>(vb); vf[1] = tr_read<v_rd_off(0, 2 * H, 1)>(vb); vf[2] = tr_read<v_rd_off(0, 2 * H + 1, 0)>(vb); vf[3] = tr_read<v_rd_off(0, 2 * H + 1, 1)>(vb);
;     vf[4] = tr_read<v_rd_off(1, 2 * H, 0)>(vb); vf[5] = tr_read<v_rd_off(1, 2 * H, 1)>(vb); vf[6] = tr_read<v_rd_off(1, 2 * H + 1, 0)>(vb); vf[7] = tr_read<v_rd_off(1, 2 * H + 1, 1)>(vb);
;     vf[8] = tr_read<v_rd_off(2, 2 * H, 0)>(vb); vf[9] = tr_read<v_rd_off(2, 2 * H, 1)>(vb); vf[10] = tr_read<v_rd_off(2, 2 * H + 1, 0)>(vb); vf[11] = tr_read<v_rd_off(2, 2 * H + 1, 1)>(vb);
;     vf[12] = tr_read<v_rd_off(3, 2 * H, 0)>(vb); vf[13] = tr_read<v_rd_off(3, 2 * H, 1)>(vb); vf[14] = tr_read<v_rd_off(3, 2 * H + 1, 0)>(vb); vf[15] = tr_read<v_rd_off(3, 2 * H + 1, 1)>(vb);
; }
; DI void pv_mma(f32x16* o, const s16x4* vf, bf16x8 pa0, bf16x8 pa1) {
;     ...
; #pragma unroll
;     for (int d0 = 0; d0 < 4; ++d0) {
;         o[d0] = __builtin_amdgcn_mfma_f32_32x32x16_bf16(pa0, ATT_PK(vf[4 * d0], vf[4 * d0 + 1]), o[d0], 0, 0, 0);
;         o[d0] = __builtin_amdgcn_mfma_f32_32x32x16_bf16(pa1, ATT_PK(vf[4 * d0 + 2], vf[4 * d0 + 3]), o[d0], 0, 0, 0); }
;     ...
; }
; template <int DQK, int D0A, int D0B> DI void k_reads(bf16x8* kf, const LAS unsigned char* Ks, int half, int r32, int hi) {
; #pragma unroll
;     for (int d0 = D0A; d0 < D0B; ++d0) kf[d0 - D0A] = *(const LAS bf16x8*)(Ks + half * (32 * DQK * 2) + kswz<DQK>(r32, (d0 * 16 + hi * 8) * 2));
; }
; template <int D0A, int D0B> DI void qk_mma(f32x16& p, const bf16x8* kf, const bf16x8* qr) {
; #pragma unroll
;     for (int d0 = D0A; d0 < D0B; ++d0) {
.LBB0_1930:
	s_mov_b64 s[96:97], 0xc00
	ds_read_b128 v[98:101], v107 offset:12288
	ds_read_b128 v[102:105], v108 offset:12288
	ds_read_b128 v[114:117], v109 offset:12288
	ds_read_b128 v[122:125], v110 offset:12288
	v_lshl_add_u32 v96, s64, 14, v106
	ds_read_b64_tr_b16 v[132:133], v96 offset:0
	ds_read_b64_tr_b16 v[134:135], v96 offset:0x800
	ds_read_b64_tr_b16 v[136:137], v96 offset:0x1000
	ds_read_b64_tr_b16 v[138:139], v96 offset:0x1800
	ds_read_b64_tr_b16 v[140:141], v96 offset:0x200
	ds_read_b64_tr_b16 v[142:143], v96 offset:0xa00
	ds_read_b64_tr_b16 v[144:145], v96 offset:0x1200
	ds_read_b64_tr_b16 v[146:147], v96 offset:0x1a00
	ds_read_b64_tr_b16 v[148:149], v96 offset:0x400
	ds_read_b64_tr_b16 v[150:151], v96 offset:0xc00
	ds_read_b64_tr_b16 v[152:153], v96 offset:0x1400
	ds_read_b64_tr_b16 v[154:155], v96 offset:0x1c00
	ds_read_b64_tr_b16 v[156:157], v96 offset:0x600
	ds_read_b64_tr_b16 v[158:159], v96 offset:0xe00
	ds_read_b64_tr_b16 v[162:163], v96 offset:0x1600
	ds_read_b64_tr_b16 v[164:165], v96 offset:0x1e00
	v_exp_f32_e32 v64, v64
	v_exp_f32_e32 v65, v65
	v_exp_f32_e32 v66, v66
	v_exp_f32_e32 v67, v67
	v_exp_f32_e32 v68, v68
	v_add_f32_e32 v97, 0, v64
	v_exp_f32_e32 v69, v69
	v_add_f32_e32 v97, v65, v97
	v_exp_f32_e32 v70, v70
	v_add_f32_e32 v97, v66, v97
	v_exp_f32_e32 v71, v71
	v_add_f32_e32 v97, v67, v97
	v_exp_f32_e32 v72, v72
	v_add_f32_e32 v97, v68, v97
	v_exp_f32_e32 v73, v73
	v_add_f32_e32 v97, v69, v97
	v_exp_f32_e32 v74, v74
	v_add_f32_e32 v97, v70, v97
	v_exp_f32_e32 v75, v75
	v_add_f32_e32 v97, v71, v97
	v_exp_f32_e32 v76, v76
	v_add_f32_e32 v97, v72, v97
	v_exp_f32_e32 v77, v77
	v_add_f32_e32 v97, v73, v97
	v_exp_f32_e32 v78, v78
	v_add_f32_e32 v97, v74, v97
	v_exp_f32_e32 v79, v79
	v_add_f32_e32 v97, v75, v97
	v_add_f32_e32 v97, v76, v97
	v_add_f32_e32 v97, v77, v97
	v_add_f32_e32 v97, v78, v97
	v_add_f32_e32 v97, v79, v97
	v_add_f32_e32 v97, v97, v120
	v_cvt_pk_bf16_f32 v64, v64, v65
	v_cvt_pk_bf16_f32 v65, v66, v67
	v_cvt_pk_bf16_f32 v66, v68, v69
	v_cvt_pk_bf16_f32 v67, v70, v71
	v_cvt_pk_bf16_f32 v68, v72, v73
	v_cvt_pk_bf16_f32 v69, v74, v75
	v_cvt_pk_bf16_f32 v70, v76, v77
	v_cvt_pk_bf16_f32 v71, v78, v79
	s_nop 0
	v_permlane32_swap_b32_e32 v64, v66
	v_permlane32_swap_b32_e32 v65, v67
	v_permlane32_swap_b32_e32 v68, v70
	v_permlane32_swap_b32_e32 v69, v71
	s_waitcnt lgkmcnt(0)
	v_mfma_f32_32x32x16_bf16 v[0:15], v[64:67], v[132:135], v[0:15]
	s_cmp_gt_i32 s55, 61
	s_cselect_b64 s[0:1], -1, 0
	s_cmp_lt_i32 s58, 62
	s_cselect_b64 s[2:3], -1, 0
	s_or_b64 s[0:1], s[0:1], s[2:3]
	s_and_b64 vcc, exec, s[0:1]
	v_mfma_f32_32x32x16_bf16 v[48:63], v[64:67], v[140:143], v[48:63]
	v_mfma_f32_32x32x16_bf16 v[32:47], v[64:67], v[148:151], v[32:47]
	v_mfma_f32_32x32x16_bf16 v[16:31], v[64:67], v[156:159], v[16:31]
	v_mfma_f32_32x32x16_bf16 v[0:15], v[68:71], v[136:139], v[0:15]
	v_mfma_f32_32x32x16_bf16 v[48:63], v[68:71], v[144:147], v[48:63]
	v_mfma_f32_32x32x16_bf16 v[32:47], v[68:71], v[152:155], v[32:47]
	v_mfma_f32_32x32x16_bf16 v[16:31], v[68:71], v[162:165], v[16:31]
	s_waitcnt lgkmcnt(0)
	v_mfma_f32_32x32x16_bf16 v[64:79], v[98:101], v[92:95], 0
	v_mfma_f32_32x32x16_bf16 v[64:79], v[102:105], v[88:91], v[64:79]
	v_mfma_f32_32x32x16_bf16 v[64:79], v[114:117], v[84:87], v[64:79]
	v_mfma_f32_32x32x16_bf16 v[64:79], v[122:125], v[80:83], v[64:79]
	s_cbranch_vccnz .LBB0_1932
	v_sub_u32_e32 v98, 0xf40, v111
	v_lshlrev_b32_e32 v98, 2, v98
	v_add3_u32 v98, s88, v98, v130
	v_add_u32_e32 v114, 0x400, v98
	v_add_u32_e32 v116, 0x408, v98
	v_add_u32_e32 v118, 0x420, v98
	v_add_u32_e32 v120, 0x428, v98
	v_add_u32_e32 v99, 0x440, v98
	v_add_u32_e32 v100, 0x448, v98
	v_add_u32_e32 v102, 0x460, v98
	v_add_u32_e32 v104, 0x468, v98
	ds_read2_b32 v[98:99], v99 offset1:1
	ds_read2_b32 v[100:101], v100 offset1:1
	ds_read2_b32 v[102:103], v102 offset1:1
	ds_read2_b32 v[104:105], v104 offset1:1
	ds_read2_b32 v[114:115], v114 offset1:1
	ds_read2_b32 v[116:117], v116 offset1:1
	ds_read2_b32 v[118:119], v118 offset1:1
	ds_read2_b32 v[120:121], v120 offset1:1
	s_waitcnt lgkmcnt(0)
	v_pk_add_f32 v[78:79], v[78:79], v[104:105]
	v_pk_add_f32 v[76:77], v[76:77], v[102:103]
	v_pk_add_f32 v[74:75], v[74:75], v[100:101]
	v_pk_add_f32 v[72:73], v[72:73], v[98:99]
	v_pk_add_f32 v[70:71], v[70:71], v[120:121]
	v_pk_add_f32 v[68:69], v[68:69], v[118:119]
	v_pk_add_f32 v[66:67], v[66:67], v[116:117]
	v_pk_add_f32 v[64:65], v[64:65], v[114:115]
.LBB0_1932:
	s_movk_i32 s64, 0x70
	ds_read_b128 v[98:101], v107 offset:16384
	ds_read_b128 v[102:105], v108 offset:16384
	ds_read_b128 v[114:117], v109 offset:16384
	ds_read_b128 v[118:121], v110 offset:16384
	ds_read_b64_tr_b16 v[122:123], v96 offset:0x2000
	ds_read_b64_tr_b16 v[124:125], v96 offset:0x2800
	ds_read_b64_tr_b16 v[132:133], v96 offset:0x3000
	ds_read_b64_tr_b16 v[134:135], v96 offset:0x3800
	ds_read_b64_tr_b16 v[136:137], v96 offset:0x2200
	ds_read_b64_tr_b16 v[138:139], v96 offset:0x2a00
	ds_read_b64_tr_b16 v[140:141], v96 offset:0x3200
	ds_read_b64_tr_b16 v[142:143], v96 offset:0x3a00
	ds_read_b64_tr_b16 v[144:145], v96 offset:0x2400
	ds_read_b64_tr_b16 v[146:147], v96 offset:0x2c00
	ds_read_b64_tr_b16 v[148:149], v96 offset:0x3400
	ds_read_b64_tr_b16 v[150:151], v96 offset:0x3c00
	ds_read_b64_tr_b16 v[152:153], v96 offset:0x2600
	ds_read_b64_tr_b16 v[154:155], v96 offset:0x2e00
	ds_read_b64_tr_b16 v[156:157], v96 offset:0x3600
	ds_read_b64_tr_b16 v[158:159], v96 offset:0x3e00
	s_nop 5
	v_exp_f32_e32 v64, v64
	v_exp_f32_e32 v65, v65
	v_exp_f32_e32 v66, v66
	v_exp_f32_e32 v67, v67
	v_exp_f32_e32 v68, v68
	v_add_f32_e32 v96, 0, v64
	v_exp_f32_e32 v69, v69
	v_add_f32_e32 v96, v65, v96
	v_exp_f32_e32 v70, v70
	v_add_f32_e32 v96, v66, v96
	v_exp_f32_e32 v71, v71
	v_add_f32_e32 v96, v67, v96
	v_exp_f32_e32 v72, v72
	v_add_f32_e32 v96, v68, v96
	v_exp_f32_e32 v73, v73
	v_add_f32_e32 v96, v69, v96
	v_exp_f32_e32 v74, v74
	v_add_f32_e32 v96, v70, v96
	v_exp_f32_e32 v75, v75
	v_add_f32_e32 v96, v71, v96
	v_exp_f32_e32 v76, v76
	v_add_f32_e32 v96, v72, v96
	v_exp_f32_e32 v77, v77
	v_add_f32_e32 v96, v73, v96
	v_exp_f32_e32 v78, v78
	v_add_f32_e32 v96, v74, v96
	v_exp_f32_e32 v79, v79
	v_add_f32_e32 v96, v75, v96
	v_add_f32_e32 v96, v76, v96
	v_add_f32_e32 v96, v77, v96
	v_add_f32_e32 v96, v78, v96
	v_add_f32_e32 v96, v79, v96
	v_add_f32_e32 v96, v97, v96
	v_cvt_pk_bf16_f32 v64, v64, v65
	v_cvt_pk_bf16_f32 v65, v66, v67
	v_cvt_pk_bf16_f32 v66, v68, v69
	v_cvt_pk_bf16_f32 v67, v70, v71
	v_cvt_pk_bf16_f32 v68, v72, v73
	v_cvt_pk_bf16_f32 v69, v74, v75
	v_cvt_pk_bf16_f32 v70, v76, v77
	v_cvt_pk_bf16_f32 v71, v78, v79
	s_nop 0
	v_permlane32_swap_b32_e32 v64, v66
	v_permlane32_swap_b32_e32 v65, v67
	v_permlane32_swap_b32_e32 v68, v70
	v_permlane32_swap_b32_e32 v69, v71
	s_waitcnt lgkmcnt(0)
	s_cmp_lt_u32 s33, 0x100
	s_cbranch_scc1 .Lstg_d0_m61_13
	s_waitcnt vmcnt(0)
	s_barrier

; #define LAS __attribute__((address_space(3)))
; DI void expsum(f32x16& p, float& l_reg, bf16x8& pa0, bf16x8& pa1) {
; #pragma unroll
;     for (int r = 0; r < 16; ++r) p[r] = __builtin_amdgcn_exp2f(p[r]);
;     float ps = 0.f;
; #pragma unroll
;     for (int r = 0; r < 16; ++r) ps += p[r];
;     l_reg += ps; asm volatile("" : "+v"(l_reg));
;     ...
;     ATT_PK4(p, 0, pa0); ATT_PK4(p, 8, pa1);
;     ...
; }
; DI int v_rd_base(int lane) { return ((lane & 3) << 3) | (((lane >> 2) & 3) << 6) | (((lane >> 4) & 1) << 5) | (((lane >> 5) & 1) << 8); }
; template <int OFF> DI s16x4 tr_read(int vb) { s16x4 r; asm volatile("ds_read_b64_tr_b16 %0, %1 offset:%2" : "=&v"(r) : "v"(vb), "i"(OFF) : "memory"); return r; }
; template <int H> DI void v_reads(s16x4* vf, int vb) {
;     vf[0] = tr_read<v_rd_off(0, 2 * H, 0)>(vb); vf[1] = tr_read<v_rd_off(0, 2 * H, 1)>(vb); vf[2] = tr_read<v_rd_off(0, 2 * H + 1, 0)>(vb); vf[3] = tr_read<v_rd_off(0, 2 * H + 1, 1)>(vb);
;     vf[4] = tr_read<v_rd_off(1, 2 * H, 0)>(vb); vf[5] = tr_read<v_rd_off(1, 2 * H, 1)>(vb); vf[6] = tr_read<v_rd_off(1, 2 * H + 1, 0)>(vb); vf[7] = tr_read<v_rd_off(1, 2 * H + 1, 1)>(vb);
;     vf[8] = tr_read<v_rd_off(2, 2 * H, 0)>(vb); vf[9] = tr_read<v_rd_off(2, 2 * H, 1)>(vb); vf[10] = tr_read<v_rd_off(2, 2 * H + 1, 0)>(vb); vf[11] = tr_read<v_rd_off(2, 2 * H + 1, 1)>(vb);
;     vf[12] = tr_read<v_rd_off(3, 2 * H, 0)>(vb); vf[13] = tr_read<v_rd_off(3, 2 * H, 1)>(vb); vf[14] = tr_read<v_rd_off(3, 2 * H + 1, 0)>(vb); vf[15] = tr_read<v_rd_off(3, 2 * H + 1, 1)>(vb);
; }
; DI void pv_mma(f32x16* o, const s16x4* vf, bf16x8 pa0, bf16x8 pa1) {
;     ...
; #pragma unroll
;     for (int d0 = 0; d0 < 4; ++d0) {
;         o[d0] = __builtin_amdgcn_mfma_f32_32x32x16_bf16(pa0, ATT_PK(vf[4 * d0], vf[4 * d0 + 1]), o[d0], 0, 0, 0);
;         o[d0] = __builtin_amdgcn_mfma_f32_32x32x16_bf16(pa1, ATT_PK(vf[4 * d0 + 2], vf[4 * d0 + 3]), o[d0], 0, 0, 0); }
;     ...
; }
; template <int DQK, int D0A, int D0B> DI void k_reads(bf16x8* kf, const LAS unsigned char* Ks, int half, int r32, int hi) {
; #pragma unroll
;     for (int d0 = D0A; d0 < D0B; ++d0) kf[d0 - D0A] = *(const LAS bf16x8*)(Ks + half * (32 * DQK * 2) + kswz<DQK>(r32, (d0 * 16 + hi * 8) * 2));
; }
; template <int D0A, int D0B> DI void qk_mma(f32x16& p, const bf16x8* kf, const bf16x8* qr) {
; #pragma unroll
;     for (int d0 = D0A; d0 < D0B; ++d0) {
.LBB0_1936:
	ds_read_b128 v[100:103], v107 offset:20480
	ds_read_b128 v[114:117], v108 offset:20480
	ds_read_b128 v[118:121], v109 offset:20480
	ds_read_b128 v[122:125], v110 offset:20480
	v_add_u32_e32 v98, 0x8000, v106
	ds_read_b64_tr_b16 v[132:133], v98 offset:0
	ds_read_b64_tr_b16 v[134:135], v98 offset:0x800
	ds_read_b64_tr_b16 v[136:137], v98 offset:0x1000
	ds_read_b64_tr_b16 v[138:139], v98 offset:0x1800
	ds_read_b64_tr_b16 v[140:141], v98 offset:0x200
	ds_read_b64_tr_b16 v[142:143], v98 offset:0xa00
	ds_read_b64_tr_b16 v[144:145], v98 offset:0x1200
	ds_read_b64_tr_b16 v[146:147], v98 offset:0x1a00
	ds_read_b64_tr_b16 v[148:149], v98 offset:0x400
	ds_read_b64_tr_b16 v[150:151], v98 offset:0xc00
	ds_read_b64_tr_b16 v[152:153], v98 offset:0x1400
	ds_read_b64_tr_b16 v[154:155], v98 offset:0x1c00
	ds_read_b64_tr_b16 v[156:157], v98 offset:0x600
	ds_read_b64_tr_b16 v[158:159], v98 offset:0xe00
	ds_read_b64_tr_b16 v[162:163], v98 offset:0x1600
	ds_read_b64_tr_b16 v[164:165], v98 offset:0x1e00
	v_exp_f32_e32 v64, v64
	v_exp_f32_e32 v65, v65
	v_exp_f32_e32 v66, v66
	v_exp_f32_e32 v67, v67
	v_exp_f32_e32 v68, v68
	v_add_f32_e32 v99, 0, v64
	v_exp_f32_e32 v69, v69
	v_add_f32_e32 v99, v65, v99
	v_exp_f32_e32 v70, v70
	v_add_f32_e32 v99, v66, v99
	v_exp_f32_e32 v71, v71
	v_add_f32_e32 v99, v67, v99
	v_exp_f32_e32 v72, v72
	v_add_f32_e32 v99, v68, v99
	v_exp_f32_e32 v73, v73
	v_add_f32_e32 v99, v69, v99
	v_exp_f32_e32 v74, v74
	v_add_f32_e32 v99, v70, v99
	v_exp_f32_e32 v75, v75
	v_add_f32_e32 v99, v71, v99
	v_exp_f32_e32 v76, v76
	v_add_f32_e32 v99, v72, v99
	v_exp_f32_e32 v77, v77
	v_add_f32_e32 v99, v73, v99
	v_exp_f32_e32 v78, v78
	v_add_f32_e32 v99, v74, v99
	v_exp_f32_e32 v79, v79
	v_add_f32_e32 v99, v75, v99
	v_add_f32_e32 v99, v76, v99
	v_add_f32_e32 v99, v77, v99
	v_add_f32_e32 v99, v78, v99
	v_add_f32_e32 v99, v79, v99
	v_add_f32_e32 v96, v99, v96
	v_cvt_pk_bf16_f32 v64, v64, v65
	v_cvt_pk_bf16_f32 v65, v66, v67
	v_cvt_pk_bf16_f32 v66, v68, v69
	v_cvt_pk_bf16_f32 v67, v70, v71
	v_cvt_pk_bf16_f32 v68, v72, v73
	v_cvt_pk_bf16_f32 v69, v74, v75
	v_cvt_pk_bf16_f32 v70, v76, v77
	v_cvt_pk_bf16_f32 v71, v78, v79
	s_nop 0
	v_permlane32_swap_b32_e32 v64, v66
	v_permlane32_swap_b32_e32 v65, v67
	v_permlane32_swap_b32_e32 v68, v70
	v_permlane32_swap_b32_e32 v69, v71
	s_waitcnt lgkmcnt(0)
	v_mfma_f32_32x32x16_bf16 v[0:15], v[64:67], v[132:135], v[0:15]
	s_and_b64 vcc, exec, s[2:3]
	v_mfma_f32_32x32x16_bf16 v[48:63], v[64:67], v[140:143], v[48:63]
	v_mfma_f32_32x32x16_bf16 v[32:47], v[64:67], v[148:151], v[32:47]
	v_mfma_f32_32x32x16_bf16 v[16:31], v[64:67], v[156:159], v[16:31]
	v_mfma_f32_32x32x16_bf16 v[0:15], v[68:71], v[136:139], v[0:15]
	v_mfma_f32_32x32x16_bf16 v[48:63], v[68:71], v[144:147], v[48:63]
	v_mfma_f32_32x32x16_bf16 v[32:47], v[68:71], v[152:155], v[32:47]
	v_mfma_f32_32x32x16_bf16 v[16:31], v[68:71], v[162:165], v[16:31]
	s_waitcnt lgkmcnt(0)
	v_mfma_f32_32x32x16_bf16 v[64:79], v[100:103], v[92:95], 0
	v_mfma_f32_32x32x16_bf16 v[64:79], v[114:117], v[88:91], v[64:79]
	v_mfma_f32_32x32x16_bf16 v[64:79], v[118:121], v[84:87], v[64:79]
	v_mfma_f32_32x32x16_bf16 v[64:79], v[122:125], v[80:83], v[64:79]
	s_cbranch_vccnz .LBB0_1938
	v_add3_u32 v97, s88, v97, v130
	v_add_u32_e32 v118, 0x408, v97
	v_add_u32_e32 v120, 0x420, v97
	v_add_u32_e32 v122, 0x428, v97
	v_add_u32_e32 v100, 0x440, v97
	v_add_u32_e32 v102, 0x448, v97
	v_add_u32_e32 v104, 0x460, v97
	v_add_u32_e32 v99, 0x400, v97
	v_add_u32_e32 v97, 0x468, v97
	ds_read2_b32 v[100:101], v100 offset1:1
	ds_read2_b32 v[102:103], v102 offset1:1
	ds_read2_b32 v[104:105], v104 offset1:1
	ds_read2_b32 v[114:115], v97 offset1:1
	ds_read2_b32 v[116:117], v99 offset1:1
	ds_read2_b32 v[118:119], v118 offset1:1
	ds_read2_b32 v[120:121], v120 offset1:1
	ds_read2_b32 v[122:123], v122 offset1:1
	s_waitcnt lgkmcnt(0)
	v_pk_add_f32 v[78:79], v[78:79], v[114:115]
	v_pk_add_f32 v[76:77], v[76:77], v[104:105]
	v_pk_add_f32 v[74:75], v[74:75], v[102:103]
	v_pk_add_f32 v[72:73], v[72:73], v[100:101]
	v_pk_add_f32 v[70:71], v[70:71], v[122:123]
	v_pk_add_f32 v[68:69], v[68:69], v[120:121]
	v_pk_add_f32 v[66:67], v[66:67], v[118:119]
	v_pk_add_f32 v[64:65], v[64:65], v[116:117]
.LBB0_1938:
	ds_read_b128 v[100:103], v107 offset:24576
	ds_read_b128 v[114:117], v108 offset:24576
	ds_read_b128 v[118:121], v109 offset:24576
	ds_read_b128 v[122:125], v110 offset:24576
	ds_read_b64_tr_b16 v[132:133], v98 offset:0x2000
	ds_read_b64_tr_b16 v[134:135], v98 offset:0x2800
	ds_read_b64_tr_b16 v[136:137], v98 offset:0x3000
	ds_read_b64_tr_b16 v[138:139], v98 offset:0x3800
	ds_read_b64_tr_b16 v[140:141], v98 offset:0x2200
	ds_read_b64_tr_b16 v[142:143], v98 offset:0x2a00
	ds_read_b64_tr_b16 v[144:145], v98 offset:0x3200
	ds_read_b64_tr_b16 v[146:147], v98 offset:0x3a00
	ds_read_b64_tr_b16 v[148:149], v98 offset:0x2400
	ds_read_b64_tr_b16 v[150:151], v98 offset:0x2c00
	ds_read_b64_tr_b16 v[152:153], v98 offset:0x3400
	ds_read_b64_tr_b16 v[154:155], v98 offset:0x3c00
	ds_read_b64_tr_b16 v[156:157], v98 offset:0x2600
	ds_read_b64_tr_b16 v[158:159], v98 offset:0x2e00
	ds_read_b64_tr_b16 v[162:163], v98 offset:0x3600
	ds_read_b64_tr_b16 v[164:165], v98 offset:0x3e00
	s_nop 6
	v_exp_f32_e32 v64, v64
	v_exp_f32_e32 v65, v65
	v_exp_f32_e32 v66, v66
	v_exp_f32_e32 v67, v67
	v_exp_f32_e32 v68, v68
	v_add_f32_e32 v97, 0, v64
	v_exp_f32_e32 v69, v69
	v_add_f32_e32 v97, v65, v97
	v_exp_f32_e32 v70, v70
	v_add_f32_e32 v97, v66, v97
	v_exp_f32_e32 v71, v71
	v_add_f32_e32 v97, v67, v97
	v_exp_f32_e32 v72, v72
	v_add_f32_e32 v97, v68, v97
	v_exp_f32_e32 v73, v73
	v_add_f32_e32 v97, v69, v97
	v_exp_f32_e32 v74, v74
	v_add_f32_e32 v97, v70, v97
	v_exp_f32_e32 v75, v75
	v_add_f32_e32 v97, v71, v97
	v_exp_f32_e32 v76, v76
	v_add_f32_e32 v97, v72, v97
	v_exp_f32_e32 v77, v77
	v_add_f32_e32 v97, v73, v97
	v_exp_f32_e32 v78, v78
	v_add_f32_e32 v97, v74, v97
	v_exp_f32_e32 v79, v79
	v_add_f32_e32 v97, v75, v97
	v_add_f32_e32 v97, v76, v97
	v_add_f32_e32 v97, v77, v97
	v_add_f32_e32 v97, v78, v97
	v_add_f32_e32 v97, v79, v97
	v_add_f32_e32 v96, v96, v97
	v_cvt_pk_bf16_f32 v64, v64, v65
	v_cvt_pk_bf16_f32 v65, v66, v67
	v_cvt_pk_bf16_f32 v66, v68, v69
	v_cvt_pk_bf16_f32 v67, v70, v71
	v_cvt_pk_bf16_f32 v68, v72, v73
	v_cvt_pk_bf16_f32 v69, v74, v75
	v_cvt_pk_bf16_f32 v70, v76, v77
	v_cvt_pk_bf16_f32 v71, v78, v79
	s_nop 0
	v_permlane32_swap_b32_e32 v64, v66
	v_permlane32_swap_b32_e32 v65, v67
	v_permlane32_swap_b32_e32 v68, v70
	v_permlane32_swap_b32_e32 v69, v71
	s_waitcnt lgkmcnt(0)
	s_cmp_lt_u32 s33, 0x100
	s_cbranch_scc1 .Lstg_d0_m62_15
	s_waitcnt vmcnt(0)
	s_barrier

; DI void expsum(f32x16& p, float& l_reg, bf16x8& pa0, bf16x8& pa1) {
; #pragma unroll
;     for (int r = 0; r < 16; ++r) p[r] = __builtin_amdgcn_exp2f(p[r]);
;     float ps = 0.f;
; #pragma unroll
;     for (int r = 0; r < 16; ++r) ps += p[r];
;     l_reg += ps; asm volatile("" : "+v"(l_reg));
;     ...
;     ATT_PK4(p, 0, pa0); ATT_PK4(p, 8, pa1);
;     ...
; }
.LBB0_1942:
	ds_read_b128 v[98:101], v107 offset:28672
	ds_read_b128 v[102:105], v108 offset:28672
	ds_read_b128 v[112:115], v109 offset:28672
	ds_read_b128 v[108:111], v110 offset:28672
	ds_read_b64_tr_b16 v[116:117], v106 offset:0
	ds_read_b64_tr_b16 v[118:119], v106 offset:0x800
	ds_read_b64_tr_b16 v[120:121], v106 offset:0x1000
	ds_read_b64_tr_b16 v[122:123], v106 offset:0x1800
	ds_read_b64_tr_b16 v[124:125], v106 offset:0x200
	ds_read_b64_tr_b16 v[126:127], v106 offset:0xa00
	ds_read_b64_tr_b16 v[132:133], v106 offset:0x1200
	ds_read_b64_tr_b16 v[134:135], v106 offset:0x1a00
	ds_read_b64_tr_b16 v[136:137], v106 offset:0x400
	ds_read_b64_tr_b16 v[138:139], v106 offset:0xc00
	ds_read_b64_tr_b16 v[140:141], v106 offset:0x1400
	ds_read_b64_tr_b16 v[142:143], v106 offset:0x1c00
	ds_read_b64_tr_b16 v[144:145], v106 offset:0x600
	ds_read_b64_tr_b16 v[146:147], v106 offset:0xe00
	ds_read_b64_tr_b16 v[148:149], v106 offset:0x1600
	ds_read_b64_tr_b16 v[150:151], v106 offset:0x1e00
	v_exp_f32_e32 v64, v64
	v_exp_f32_e32 v65, v65
	v_exp_f32_e32 v66, v66
	v_exp_f32_e32 v67, v67
	v_exp_f32_e32 v68, v68
	v_add_f32_e32 v107, 0, v64
	v_exp_f32_e32 v69, v69
	v_add_f32_e32 v107, v65, v107
	v_exp_f32_e32 v70, v70
	v_add_f32_e32 v107, v66, v107
	v_exp_f32_e32 v71, v71
	v_add_f32_e32 v107, v67, v107
	v_exp_f32_e32 v72, v72
	v_add_f32_e32 v107, v68, v107
	v_exp_f32_e32 v73, v73
	v_add_f32_e32 v107, v69, v107
	v_exp_f32_e32 v74, v74
	v_add_f32_e32 v107, v70, v107
	v_exp_f32_e32 v75, v75
	v_add_f32_e32 v107, v71, v107
	v_exp_f32_e32 v76, v76
	v_add_f32_e32 v107, v72, v107
	v_exp_f32_e32 v77, v77
	v_add_f32_e32 v107, v73, v107
	v_exp_f32_e32 v78, v78
	v_add_f32_e32 v107, v74, v107
	v_exp_f32_e32 v79, v79
	v_add_f32_e32 v107, v75, v107
	v_add_f32_e32 v107, v76, v107
	v_add_f32_e32 v107, v77, v107
	v_add_f32_e32 v107, v78, v107
	v_add_f32_e32 v107, v79, v107
	v_add_f32_e32 v96, v107, v96
	v_cvt_pk_bf16_f32 v64, v64, v65
	v_cvt_pk_bf16_f32 v65, v66, v67
	v_cvt_pk_bf16_f32 v66, v68, v69
	v_cvt_pk_bf16_f32 v67, v70, v71
	v_cvt_pk_bf16_f32 v68, v72, v73
	v_cvt_pk_bf16_f32 v69, v74, v75
	v_cvt_pk_bf16_f32 v70, v76, v77
	v_cvt_pk_bf16_f32 v71, v78, v79
	s_nop 0
	v_permlane32_swap_b32_e32 v64, v66
	v_permlane32_swap_b32_e32 v65, v67
	v_permlane32_swap_b32_e32 v68, v70
	v_permlane32_swap_b32_e32 v69, v71
	s_waitcnt lgkmcnt(0)
	v_mfma_f32_32x32x16_bf16 v[0:15], v[64:67], v[116:119], v[0:15]
	s_and_b64 vcc, exec, s[2:3]
	v_mfma_f32_32x32x16_bf16 v[48:63], v[64:67], v[124:127], v[48:63]
	v_mfma_f32_32x32x16_bf16 v[32:47], v[64:67], v[136:139], v[32:47]
	v_mfma_f32_32x32x16_bf16 v[16:31], v[64:67], v[144:147], v[16:31]
	v_mfma_f32_32x32x16_bf16 v[0:15], v[68:71], v[120:123], v[0:15]
	v_mfma_f32_32x32x16_bf16 v[48:63], v[68:71], v[132:135], v[48:63]
	v_mfma_f32_32x32x16_bf16 v[32:47], v[68:71], v[140:143], v[32:47]
	v_mfma_f32_32x32x16_bf16 v[16:31], v[68:71], v[148:151], v[16:31]
	s_waitcnt lgkmcnt(0)
	v_mfma_f32_32x32x16_bf16 v[64:79], v[98:101], v[92:95], 0
	v_mfma_f32_32x32x16_bf16 v[64:79], v[102:105], v[88:91], v[64:79]
	v_mfma_f32_32x32x16_bf16 v[64:79], v[112:115], v[84:87], v[64:79]
	v_mfma_f32_32x32x16_bf16 v[64:79], v[108:111], v[80:83], v[64:79]
	s_cbranch_vccnz .LBB0_1944
	v_add3_u32 v80, s88, v97, v130
	v_add_u32_e32 v88, 0x400, v80
	v_add_u32_e32 v90, 0x408, v80
	v_add_u32_e32 v92, 0x420, v80
	v_add_u32_e32 v94, 0x428, v80
	v_add_u32_e32 v81, 0x440, v80
	v_add_u32_e32 v82, 0x448, v80
	v_add_u32_e32 v84, 0x460, v80
	v_add_u32_e32 v86, 0x468, v80
	ds_read2_b32 v[80:81], v81 offset1:1
	ds_read2_b32 v[82:83], v82 offset1:1
	ds_read2_b32 v[84:85], v84 offset1:1
	ds_read2_b32 v[86:87], v86 offset1:1
	ds_read2_b32 v[88:89], v88 offset1:1
	ds_read2_b32 v[90:91], v90 offset1:1
	ds_read2_b32 v[92:93], v92 offset1:1
	ds_read2_b32 v[94:95], v94 offset1:1
	s_waitcnt lgkmcnt(0)
	v_pk_add_f32 v[78:79], v[78:79], v[86:87]
	v_pk_add_f32 v[76:77], v[76:77], v[84:85]
	v_pk_add_f32 v[74:75], v[74:75], v[82:83]
	v_pk_add_f32 v[72:73], v[72:73], v[80:81]
	v_pk_add_f32 v[70:71], v[70:71], v[94:95]
	v_pk_add_f32 v[68:69], v[68:69], v[92:93]
	v_pk_add_f32 v[66:67], v[66:67], v[90:91]
	v_pk_add_f32 v[64:65], v[64:65], v[88:89]
.LBB0_1944:
	s_lshl_b32 s0, s54, 2
	s_add_i32 s0, s0, 0
	s_add_i32 s0, s0, 0x24000
	ds_read_b64_tr_b16 v[80:81], v106 offset:0x2000
	ds_read_b64_tr_b16 v[82:83], v106 offset:0x2800
	ds_read_b64_tr_b16 v[84:85], v106 offset:0x3000
	ds_read_b64_tr_b16 v[86:87], v106 offset:0x3800
	ds_read_b64_tr_b16 v[88:89], v106 offset:0x2200
	ds_read_b64_tr_b16 v[90:91], v106 offset:0x2a00
	ds_read_b64_tr_b16 v[92:93], v106 offset:0x3200
	ds_read_b64_tr_b16 v[94:95], v106 offset:0x3a00
	ds_read_b64_tr_b16 v[98:99], v106 offset:0x2400
	ds_read_b64_tr_b16 v[100:101], v106 offset:0x2c00
	ds_read_b64_tr_b16 v[102:103], v106 offset:0x3400
	ds_read_b64_tr_b16 v[104:105], v106 offset:0x3c00
	ds_read_b64_tr_b16 v[108:109], v106 offset:0x2600
	ds_read_b64_tr_b16 v[110:111], v106 offset:0x2e00
	ds_read_b64_tr_b16 v[112:113], v106 offset:0x3600
	ds_read_b64_tr_b16 v[114:115], v106 offset:0x3e00
	s_nop 7
	v_exp_f32_e32 v97, v64
	v_exp_f32_e32 v65, v65
	v_exp_f32_e32 v106, v66
	v_exp_f32_e32 v67, v67
	v_exp_f32_e32 v68, v68
	v_add_f32_e32 v64, 0, v97
	v_exp_f32_e32 v69, v69
	v_add_f32_e32 v64, v65, v64
	v_exp_f32_e32 v70, v70
	v_add_f32_e32 v64, v106, v64
	v_exp_f32_e32 v71, v71
	v_add_f32_e32 v64, v67, v64
	v_exp_f32_e32 v72, v72
	v_add_f32_e32 v64, v68, v64
	v_exp_f32_e32 v73, v73
	v_add_f32_e32 v64, v69, v64
	v_exp_f32_e32 v74, v74
	v_add_f32_e32 v64, v70, v64
	v_exp_f32_e32 v75, v75
	v_add_f32_e32 v64, v71, v64
	v_exp_f32_e32 v76, v76
	v_add_f32_e32 v64, v72, v64
	v_exp_f32_e32 v77, v77
	v_add_f32_e32 v64, v73, v64
	v_exp_f32_e32 v78, v78
	v_add_f32_e32 v64, v74, v64
	v_exp_f32_e32 v79, v79
	v_add_f32_e32 v64, v75, v64
	v_add_f32_e32 v64, v76, v64
	v_add_f32_e32 v64, v77, v64
	v_add_f32_e32 v64, v78, v64
	v_add_f32_e32 v64, v79, v64
	v_add_f32_e32 v64, v96, v64
	v_cvt_pk_bf16_f32 v66, v97, v65
	v_cvt_pk_bf16_f32 v67, v106, v67
	v_cvt_pk_bf16_f32 v68, v68, v69
	v_cvt_pk_bf16_f32 v69, v70, v71
	v_cvt_pk_bf16_f32 v70, v72, v73
	v_cvt_pk_bf16_f32 v71, v74, v75
	v_cvt_pk_bf16_f32 v72, v76, v77
	v_cvt_pk_bf16_f32 v73, v78, v79
	s_nop 0
	v_permlane32_swap_b32_e32 v66, v68
	v_permlane32_swap_b32_e32 v67, v69
	v_permlane32_swap_b32_e32 v70, v72
	v_permlane32_swap_b32_e32 v71, v73
	s_waitcnt lgkmcnt(0)
; template <int TAG = 0> DI int fresh_tid(int wv) { int l; asm volatile("v_mbcnt_lo_u32_b32 %0, -1, 0\n\tv_mbcnt_hi_u32_b32 %0, -1, %0 ; site %1" : "=v"(l) : "n"(TAG)); return wv * 64 + l; }
; DI unsigned short f2bf(float x) { unsigned u = __float_as_uint(x); u += 0x7fffu + ((u >> 16) & 1u); return (unsigned short)(u >> 16); }
; DI int crow(int r, int hi) { return (r & 3) + 8 * (r >> 2) + 4 * hi; }
; DI float swap_sum(float v) { auto rr = __builtin_amdgcn_permlane32_swap(__float_as_uint(v), __float_as_uint(v), false, false); return __uint_as_float(rr[0]) + __uint_as_float(rr[1]); }
; DI void pv_mma(f32x16* o, const s16x4* vf, bf16x8 pa0, bf16x8 pa1) {
;     ...
; #pragma unroll
;     for (int d0 = 0; d0 < 4; ++d0) {
;         o[d0] = __builtin_amdgcn_mfma_f32_32x32x16_bf16(pa0, ATT_PK(vf[4 * d0], vf[4 * d0 + 1]), o[d0], 0, 0, 0);
;         o[d0] = __builtin_amdgcn_mfma_f32_32x32x16_bf16(pa1, ATT_PK(vf[4 * d0 + 2], vf[4 * d0 + 3]), o[d0], 0, 0, 0); }
;     ...
; }
; template <int DQK, int MODE, int LDQ, int LDK, int LDV> ...
;     ...
;     __builtin_amdgcn_s_setprio(0);
;     ...
;     l_reg = swap_sum(l_reg);
;     { const int lane2 = fresh_tid<110 + MODE>(wv) & 63, r32 = lane2 & 31, hi = lane2 >> 5;
;     if (hi == 0) li_l[r32] = l_reg;
;     asm volatile("s_waitcnt lgkmcnt(0)" ::: "memory");
;     float s0v[MODE == 2 ? 16 : 1][4];
;     if constexpr (MODE == 2) {
; #pragma unroll
;         for (int r = 0; r < 16; ++r)
; #pragma unroll
;             for (int d0 = 0; d0 < 4; ++d0) s0v[r][d0] = S0[(size_t)(wid * 32 + crow(r, hi)) * 512 + d0 * 32 + r32];
;     }
; #pragma unroll
;     for (int r = 0; r < 16; ++r) { const int orow = wid * 32 + crow(r, hi); const float rl = __builtin_amdgcn_rcpf(li_l[crow(r, hi)]);
;         if constexpr (MODE == 0) {
; #pragma unroll
;             for (int d0 = 0; d0 < 4; ++d0) AOb[(size_t)orow * 1024 + d0 * 32 + r32] = f2bf(o[d0][r] * rl);
;         } else if constexpr (MODE == 1) {
; #pragma unroll
;             for (int d0 = 0; d0 < 4; ++d0) S0[(size_t)orow * 512 + d0 * 32 + r32] = o[d0][r] * rl;
	v_mfma_f32_32x32x16_bf16 v[0:15], v[66:69], v[80:83], v[0:15]
	v_mfma_f32_32x32x16_bf16 v[48:63], v[66:69], v[88:91], v[48:63]
	v_mfma_f32_32x32x16_bf16 v[32:47], v[66:69], v[98:101], v[32:47]
	v_mfma_f32_32x32x16_bf16 v[16:31], v[66:69], v[108:111], v[16:31]
	v_mfma_f32_32x32x16_bf16 v[0:15], v[70:73], v[84:87], v[0:15]
	v_mfma_f32_32x32x16_bf16 v[48:63], v[70:73], v[92:95], v[48:63]
	v_mfma_f32_32x32x16_bf16 v[32:47], v[70:73], v[102:105], v[32:47]
	v_mfma_f32_32x32x16_bf16 v[16:31], v[70:73], v[112:115], v[16:31]
	s_setprio 0
	v_mbcnt_lo_u32_b32 v66, -1, 0
	v_mbcnt_hi_u32_b32 v66, -1, v66
	v_mov_b32_e32 v67, v64
	v_and_b32_e32 v65, 31, v66
	v_bfe_u32 v66, v66, 5, 1
	v_permlane32_swap_b32_e32 v64, v67
	v_cmp_eq_u32_e32 vcc, 0, v66
	s_and_saveexec_b64 s[2:3], vcc
	v_lshl_add_u32 v68, v65, 2, s0
	v_add_f32_e32 v64, v64, v67
	ds_write_b32 v68, v64
	s_or_b64 exec, exec, s[2:3]
	s_waitcnt lgkmcnt(0)
	v_lshl_add_u32 v68, v66, 4, s0
	ds_read_b128 v[70:73], v68
	ds_read_b128 v[74:77], v68 offset:32
	s_lshl_b64 s[58:59], s[40:41], 11
	v_readlane_b32 s1, v255, 2
	s_add_u32 s1, s1, s58
	v_readlane_b32 s2, v255, 0
	s_addc_u32 s2, s2, s59
	s_lshl_b32 s3, s87, 2
	s_waitcnt lgkmcnt(0)
	v_rcp_f32_e32 v69, v70
	s_add_u32 s54, s1, s3
	v_lshl_or_b32 v66, v66, 2, s94
	s_addc_u32 s55, s2, 0
	v_lshlrev_b32_e32 v130, 2, v65
	v_ashrrev_i32_e32 v67, 31, v66
	v_lshl_add_u64 v[64:65], s[54:55], 0, v[130:131]
	v_lshlrev_b64 v[78:79], 11, v[66:67]
	v_lshl_add_u64 v[78:79], v[64:65], 0, v[78:79]
	v_mul_f32_e32 v0, v0, v69
	global_store_dword v[78:79], v0, off
	v_mul_f32_e32 v0, v48, v69
	global_store_dword v[78:79], v0, off offset:128
	v_mul_f32_e32 v0, v32, v69
	global_store_dword v[78:79], v0, off offset:256
	v_mul_f32_e32 v0, v16, v69
	global_store_dword v[78:79], v0, off offset:384
	v_rcp_f32_e32 v0, v71
	v_or_b32_e32 v70, 1, v66
	v_ashrrev_i32_e32 v71, 31, v70
	v_lshlrev_b64 v[70:71], 11, v[70:71]
	v_lshl_add_u64 v[70:71], v[64:65], 0, v[70:71]
	v_mul_f32_e32 v1, v1, v0
	global_store_dword v[70:71], v1, off
	v_mul_f32_e32 v1, v49, v0
	global_store_dword v[70:71], v1, off offset:128
	v_mul_f32_e32 v1, v33, v0
	v_mul_f32_e32 v0, v17, v0
	v_rcp_f32_e32 v16, v72
	global_store_dword v[70:71], v0, off offset:384
	v_or_b32_e32 v0, 2, v66
	global_store_dword v[70:71], v1, off offset:256
	v_ashrrev_i32_e32 v1, 31, v0
	v_lshlrev_b64 v[0:1], 11, v[0:1]
	v_lshl_add_u64 v[0:1], v[64:65], 0, v[0:1]
	v_mul_f32_e32 v2, v2, v16
	global_store_dword v[0:1], v2, off
	v_mul_f32_e32 v2, v50, v16
	global_store_dword v[0:1], v2, off offset:128
	v_mul_f32_e32 v2, v34, v16
	global_store_dword v[0:1], v2, off offset:256
	v_mul_f32_e32 v2, v18, v16
	global_store_dword v[0:1], v2, off offset:384
	v_rcp_f32_e32 v2, v73
	v_or_b32_e32 v0, 3, v66
	v_ashrrev_i32_e32 v1, 31, v0
	v_lshlrev_b64 v[0:1], 11, v[0:1]
	v_lshl_add_u64 v[0:1], v[64:65], 0, v[0:1]
	v_mul_f32_e32 v3, v3, v2
	global_store_dword v[0:1], v3, off
	v_mul_f32_e32 v3, v51, v2
	global_store_dword v[0:1], v3, off offset:128
	v_mul_f32_e32 v3, v35, v2
	v_mul_f32_e32 v2, v19, v2
	global_store_dword v[0:1], v2, off offset:384
	v_rcp_f32_e32 v2, v74
	global_store_dword v[0:1], v3, off offset:256
	v_or_b32_e32 v0, 8, v66
	v_ashrrev_i32_e32 v1, 31, v0
	v_lshlrev_b64 v[0:1], 11, v[0:1]
	v_lshl_add_u64 v[0:1], v[64:65], 0, v[0:1]
	v_mul_f32_e32 v3, v4, v2
	global_store_dword v[0:1], v3, off
	v_mul_f32_e32 v3, v52, v2
	global_store_dword v[0:1], v3, off offset:128
	v_mul_f32_e32 v3, v36, v2
	v_mul_f32_e32 v2, v20, v2
	global_store_dword v[0:1], v2, off offset:384
	v_rcp_f32_e32 v2, v75
	global_store_dword v[0:1], v3, off offset:256
	v_or_b32_e32 v0, 9, v66
	v_ashrrev_i32_e32 v1, 31, v0
	v_lshlrev_b64 v[0:1], 11, v[0:1]
	v_lshl_add_u64 v[0:1], v[64:65], 0, v[0:1]
	v_mul_f32_e32 v3, v5, v2
	global_store_dword v[0:1], v3, off
	v_mul_f32_e32 v3, v53, v2
	global_store_dword v[0:1], v3, off offset:128
	v_mul_f32_e32 v3, v37, v2
	v_mul_f32_e32 v2, v21, v2
	global_store_dword v[0:1], v2, off offset:384
	v_rcp_f32_e32 v2, v76
	global_store_dword v[0:1], v3, off offset:256
	v_or_b32_e32 v0, 10, v66
	v_ashrrev_i32_e32 v1, 31, v0
	v_lshlrev_b64 v[0:1], 11, v[0:1]
	v_lshl_add_u64 v[0:1], v[64:65], 0, v[0:1]
	v_mul_f32_e32 v3, v6, v2
	global_store_dword v[0:1], v3, off
	v_mul_f32_e32 v3, v54, v2
	global_store_dword v[0:1], v3, off offset:128
	v_mul_f32_e32 v3, v38, v2
	v_mul_f32_e32 v2, v22, v2
	v_rcp_f32_e32 v6, v77
	global_store_dword v[0:1], v3, off offset:256
	global_store_dword v[0:1], v2, off offset:384
	v_or_b32_e32 v0, 11, v66
	v_ashrrev_i32_e32 v1, 31, v0
	v_lshlrev_b64 v[0:1], 11, v[0:1]
	v_lshl_add_u64 v[4:5], v[64:65], 0, v[0:1]
	v_mul_f32_e32 v0, v7, v6
	global_store_dword v[4:5], v0, off
	v_mul_f32_e32 v0, v55, v6
	global_store_dword v[4:5], v0, off offset:128
	v_mul_f32_e32 v0, v39, v6
	global_store_dword v[4:5], v0, off offset:256
	ds_read_b128 v[0:3], v68 offset:64
	v_mul_f32_e32 v6, v23, v6
	global_store_dword v[4:5], v6, off offset:384
	ds_read_b128 v[4:7], v68 offset:96
	v_or_b32_e32 v16, 16, v66
	s_waitcnt lgkmcnt(0)
; DI unsigned short f2bf(float x) { unsigned u = __float_as_uint(x); u += 0x7fffu + ((u >> 16) & 1u); return (unsigned short)(u >> 16); }
; DI int crow(int r, int hi) { return (r & 3) + 8 * (r >> 2) + 4 * hi; }
; template <int DQK, int MODE, int LDQ, int LDK, int LDV> ...
;     ...
;     for (int r = 0; r < 16; ++r) { const int orow = wid * 32 + crow(r, hi); const float rl = __builtin_amdgcn_rcpf(li_l[crow(r, hi)]);
;         if constexpr (MODE == 0) {
; #pragma unroll
;             for (int d0 = 0; d0 < 4; ++d0) AOb[(size_t)orow * 1024 + d0 * 32 + r32] = f2bf(o[d0][r] * rl);
;         } else if constexpr (MODE == 1) {
; #pragma unroll
;             for (int d0 = 0; d0 < 4; ++d0) S0[(size_t)orow * 512 + d0 * 32 + r32] = o[d0][r] * rl;
; DI void phase4(const Params& p, LAS unsigned char* lds, int wv) {
;     ...
;             __syncthreads();
	v_rcp_f32_e32 v0, v0
	v_ashrrev_i32_e32 v17, 31, v16
	v_lshlrev_b64 v[16:17], 11, v[16:17]
	v_lshl_add_u64 v[16:17], v[64:65], 0, v[16:17]
	v_mul_f32_e32 v8, v8, v0
	global_store_dword v[16:17], v8, off
	v_mul_f32_e32 v8, v56, v0
	global_store_dword v[16:17], v8, off offset:128
	v_mul_f32_e32 v8, v40, v0
	global_store_dword v[16:17], v8, off offset:256
	v_mul_f32_e32 v0, v24, v0
	v_rcp_f32_e32 v8, v1
	global_store_dword v[16:17], v0, off offset:384
	v_or_b32_e32 v0, 17, v66
	v_ashrrev_i32_e32 v1, 31, v0
	v_lshlrev_b64 v[0:1], 11, v[0:1]
	v_lshl_add_u64 v[0:1], v[64:65], 0, v[0:1]
	v_mul_f32_e32 v9, v9, v8
	global_store_dword v[0:1], v9, off
	v_mul_f32_e32 v9, v57, v8
	global_store_dword v[0:1], v9, off offset:128
	v_mul_f32_e32 v9, v41, v8
	v_mul_f32_e32 v8, v25, v8
	v_rcp_f32_e32 v2, v2
	global_store_dword v[0:1], v9, off offset:256
	global_store_dword v[0:1], v8, off offset:384
	v_or_b32_e32 v0, 18, v66
	v_ashrrev_i32_e32 v1, 31, v0
	v_lshlrev_b64 v[0:1], 11, v[0:1]
	v_lshl_add_u64 v[0:1], v[64:65], 0, v[0:1]
	v_mul_f32_e32 v8, v10, v2
	global_store_dword v[0:1], v8, off
	v_mul_f32_e32 v8, v58, v2
	global_store_dword v[0:1], v8, off offset:128
	v_mul_f32_e32 v8, v42, v2
	v_mul_f32_e32 v2, v26, v2
	global_store_dword v[0:1], v2, off offset:384
	v_rcp_f32_e32 v2, v3
	global_store_dword v[0:1], v8, off offset:256
	v_or_b32_e32 v0, 19, v66
	v_ashrrev_i32_e32 v1, 31, v0
	v_lshlrev_b64 v[0:1], 11, v[0:1]
	v_lshl_add_u64 v[0:1], v[64:65], 0, v[0:1]
	v_mul_f32_e32 v3, v11, v2
	global_store_dword v[0:1], v3, off
	v_mul_f32_e32 v3, v59, v2
	global_store_dword v[0:1], v3, off offset:128
	v_mul_f32_e32 v3, v43, v2
	v_mul_f32_e32 v2, v27, v2
	global_store_dword v[0:1], v2, off offset:384
	v_rcp_f32_e32 v2, v4
	global_store_dword v[0:1], v3, off offset:256
	v_or_b32_e32 v0, 24, v66
	v_ashrrev_i32_e32 v1, 31, v0
	v_lshlrev_b64 v[0:1], 11, v[0:1]
	v_lshl_add_u64 v[0:1], v[64:65], 0, v[0:1]
	v_mul_f32_e32 v3, v12, v2
	global_store_dword v[0:1], v3, off
	v_mul_f32_e32 v3, v60, v2
	global_store_dword v[0:1], v3, off offset:128
	v_mul_f32_e32 v3, v44, v2
	v_mul_f32_e32 v2, v28, v2
	global_store_dword v[0:1], v2, off offset:384
	v_rcp_f32_e32 v2, v5
	global_store_dword v[0:1], v3, off offset:256
	v_or_b32_e32 v0, 25, v66
	v_ashrrev_i32_e32 v1, 31, v0
	v_lshlrev_b64 v[0:1], 11, v[0:1]
	v_lshl_add_u64 v[0:1], v[64:65], 0, v[0:1]
	v_mul_f32_e32 v3, v13, v2
	global_store_dword v[0:1], v3, off
	v_mul_f32_e32 v3, v61, v2
	global_store_dword v[0:1], v3, off offset:128
	v_mul_f32_e32 v3, v45, v2
	v_mul_f32_e32 v2, v29, v2
	global_store_dword v[0:1], v2, off offset:384
	v_rcp_f32_e32 v2, v6
	global_store_dword v[0:1], v3, off offset:256
	v_or_b32_e32 v0, 26, v66
	v_ashrrev_i32_e32 v1, 31, v0
	v_lshlrev_b64 v[0:1], 11, v[0:1]
	v_lshl_add_u64 v[0:1], v[64:65], 0, v[0:1]
	v_mul_f32_e32 v3, v14, v2
	global_store_dword v[0:1], v3, off
	v_mul_f32_e32 v3, v62, v2
	global_store_dword v[0:1], v3, off offset:128
	v_mul_f32_e32 v3, v46, v2
	v_mul_f32_e32 v2, v30, v2
	global_store_dword v[0:1], v2, off offset:384
	v_rcp_f32_e32 v2, v7
	global_store_dword v[0:1], v3, off offset:256
	v_or_b32_e32 v0, 27, v66
	v_ashrrev_i32_e32 v1, 31, v0
	v_lshlrev_b64 v[0:1], 11, v[0:1]
	v_lshl_add_u64 v[0:1], v[64:65], 0, v[0:1]
	v_mul_f32_e32 v3, v15, v2
	global_store_dword v[0:1], v3, off
	v_mul_f32_e32 v3, v63, v2
	global_store_dword v[0:1], v3, off offset:128
	v_mul_f32_e32 v3, v47, v2
	v_mul_f32_e32 v2, v31, v2
	global_store_dword v[0:1], v3, off offset:256
	global_store_dword v[0:1], v2, off offset:384
	s_waitcnt vmcnt(0)
	s_barrier
; DI float bf2f(unsigned short h) { return __uint_as_float((unsigned)h << 16); }
; template <int DQK, int MODE, int LDQ, int LDK, int LDV> ...
;     ...
;     int kgo[NKP], vgo[2];
; #pragma unroll
;     for (int i = 0; i < NKP; ++i) { const int L = (wid + 8 * i) * 64 + lane, row = L / CPR, slot = L % CPR, cc = (slot & ~7) | ((slot & 7) ^ ((row >> 1) & 7)); kgo[i] = row * LDK + cc * 8; }
; #pragma unroll
;     for (int i = 0; i < 2; ++i) { const int L = (2 * wid + i) * 64 + lane, st = L >> 5, w5 = L & 31, kk = (st >> 2) * 8 + (w5 >> 2), c = (st & 3) * 32 + (w5 & 3) * 8;
;         const int k = (kk & ~0xC) | ((kk & 4) << 1) | ((kk & 8) >> 1); vgo[i] = k * LDV + c; }
;     ...
;     ATT_DMA_K(0); ATT_DMA_K(1); ATT_DMA_V(0, 0); ATT_DMA_K(2); ATT_DMA_V(1, 1);
;     bf16x8 qr[ND0];
;     { const bf16_t* Qw = Qb + (size_t)(wid * 32 + r32) * LDQ + hi * 8;
; #pragma unroll
;       for (int d0 = 0; d0 < ND0; ++d0) qr[d0] = *(const bf16x8*)(Qw + d0 * 16);
;       if constexpr (MODE == 0) {
;           float ss = 0.f;
; #pragma unroll
;           for (int d0 = 0; d0 < ND0; ++d0)
; #pragma unroll
;               for (int j = 0; j < 8; ++j) { const float f = bf2f((unsigned short)qr[d0][j]); ss += f * f; }
;           ss = swap_sum(ss);
;           const float rstd = rsqrtf(ss * (1.f / DQK) + EPS) * C;
; #pragma unroll
;           for (int d0 = 0; d0 < ND0; ++d0) { const float* g = gq + d0 * 16 + hi * 8;
;               { float f[8]; _Pragma("unroll") for (int j = 0; j < 8; ++j) f[j] = bf2f((unsigned short)qr[d0][j]) * rstd * g[j];
;                 u32x4 w = {cvtpk(f[0], f[1]), cvtpk(f[2], f[3]), cvtpk(f[4], f[5]), cvtpk(f[6], f[7])}; qr[d0] = __builtin_bit_cast(bf16x8, w); asm volatile("" ::: "memory"); } }
;       } }
;     const int qlo = q0 + wid * 32, qpos = qlo + r32;
;     const int tL = MODE == 0 ? 0 : (qlo >= 191 ? (qlo - 127) >> 6 : 0), tR = MODE == 0 ? NT : min(NT, (qlo + 222) >> 6);
;     float fL = 1.f, fR = 1.f; if constexpr (MODE != 0) { fL = __builtin_amdgcn_exp2f(bt[0]); fR = __builtin_amdgcn_exp2f(-bt[448]); }
;     ...
;     const int vbase = (int)(unsigned)(size_t)lds + V_OFF + v_rd_base(lane);
;     ...
;     constexpr int NDA = ND0 > 6 ? 6 : ND0;
;     ...
;     f32x16 pA, pB; bf16x8 pa0, pa1;
;     int v0 = 0, v1 = 1, v2 = 2;
;     ATT_TOP(NKP + 2);
;     { bf16x8 kf[NDA]; k_reads<DQK, 0, NDA>(kf, lds, 0, r32, hi); ATT_LGKM0(); qk_mma<0, NDA>(pA, kf, qr);
	v_mbcnt_lo_u32_b32 v7, -1, 0
	v_mbcnt_hi_u32_b32 v7, -1, v7
	s_mov_b64 s[4:5], 0x880
	v_add_u32_e32 v0, s33, v7
	v_bfe_u32 v4, v0, 2, 2
	v_readfirstlane_b32 s0, v0
	s_ashr_i32 s2, s0, 31
	s_ashr_i32 s1, s0, 6
	v_mov_b32_e32 v1, s0
	v_bfi_b32 v1, s63, v1, v7
	s_lshr_b32 s2, s2, 29
	v_add_u32_e32 v3, s2, v1
	s_lshl_b32 s2, s1, 7
	v_ashrrev_i32_e32 v9, 3, v3
	v_and_b32_e32 v3, 0x1ffffff8, v3
	s_ashr_i32 s3, s2, 4
	v_lshrrev_b32_e32 v0, 1, v0
	v_sub_u32_e32 v1, v1, v3
	v_lshrrev_b32_e32 v3, 1, v9
	v_lshlrev_b32_e32 v18, 3, v7
	s_and_b32 s2, s3, -16
	v_and_b32_e32 v6, 8, v0
	s_lshr_b32 s3, s3, 1
	v_bitop3_b32 v1, v3, v1, 7 bitop3:0x6c
	v_and_b32_e32 v3, 32, v7
	v_and_b32_e32 v5, 24, v18
	s_and_b32 s3, s3, 4
	v_or3_b32 v0, v6, v4, s2
	v_or_b32_e32 v10, v3, v5
	v_or_b32_e32 v0, s3, v0
	v_lshl_or_b32 v96, v0, 11, v10
	v_lshlrev_b32_e32 v0, 11, v9
	v_lshl_add_u32 v0, v1, 3, v0
	v_ashrrev_i32_e32 v1, 31, v0
	v_lshlrev_b64 v[10:11], 1, v[0:1]
	v_lshl_add_u64 v[12:13], s[46:47], 0, v[10:11]
	v_lshl_add_u64 v[12:13], v[12:13], 0, s[4:5]
	s_lshl_b32 s4, s1, 10
	s_add_i32 s94, s4, 0
	s_mov_b32 m0, s94
	v_lshl_add_u64 v[10:11], s[48:49], 0, v[10:11]
	s_mov_b64 s[4:5], 0x40080
	global_load_lds_dwordx4 v[12:13], off
	v_lshl_add_u64 v[12:13], v[10:11], 0, s[4:5]
	s_add_i32 m0, s94, 0x2000
	s_lshl_b32 s4, s1, 11
	v_ashrrev_i32_e32 v97, 31, v96
	global_load_lds_dwordx4 v[12:13], off
	s_add_i32 s6, s4, 0
	v_lshlrev_b64 v[12:13], 1, v[96:97]
	s_add_i32 s48, s6, 0x18000
	v_lshl_add_u64 v[14:15], s[46:47], 0, v[12:13]
	v_lshl_add_u64 v[16:17], v[14:15], 0, s[96:97]
	s_mov_b32 m0, s48
	s_mov_b64 s[4:5], 0xc80
	global_load_lds_dwordx4 v[16:17], off
	v_lshl_add_u64 v[14:15], v[14:15], 0, s[4:5]
	s_add_i32 m0, s6, 0x18400
	s_mov_b64 s[4:5], 0x80080
	v_or_b32_e32 v98, 64, v96
	global_load_lds_dwordx4 v[14:15], off
	v_lshl_add_u64 v[10:11], v[10:11], 0, s[4:5]
	s_add_i32 m0, s94, 0x4000
	v_ashrrev_i32_e32 v99, 31, v98
	global_load_lds_dwordx4 v[10:11], off
	s_add_i32 m0, s6, 0x1c000
	v_lshl_add_u64 v[10:11], s[52:53], 0, v[12:13]
	v_and_b32_e32 v2, 31, v7
	global_load_lds_dwordx4 v[10:11], off
	v_lshl_add_u64 v[10:11], v[98:99], 1, s[52:53]
	s_add_i32 m0, s6, 0x1c400
	s_lshl_b32 s46, s1, 5
	global_load_lds_dwordx4 v[10:11], off
	v_or_b32_e32 v10, s46, v2
	v_ashrrev_i32_e32 v11, 31, v10
	v_bfe_u32 v8, v7, 5, 1
	v_lshlrev_b64 v[10:11], 12, v[10:11]
	v_lshl_add_u64 v[10:11], s[44:45], 0, v[10:11]
	v_lshlrev_b32_e32 v130, 4, v8
	v_lshl_add_u64 v[10:11], v[10:11], 0, v[130:131]
	global_load_dwordx4 v[92:95], v[10:11], off offset:1152
	global_load_dwordx4 v[88:91], v[10:11], off offset:1184
	global_load_dwordx4 v[84:87], v[10:11], off offset:1216
	global_load_dwordx4 v[80:83], v[10:11], off offset:1248
	v_and_b32_e32 v11, 0x70, v18
	v_mov_b32_e32 v9, s88
	v_mov_b32_e32 v10, s81
	v_lshl_add_u32 v114, v2, 7, 0
	v_bitop3_b32 v115, v130, v18, s64 bitop3:0x78
	v_bitop3_b32 v117, v130, v11, 64 bitop3:0x36
	s_add_i32 s4, s46, s89
	ds_read_b32 v9, v9
	ds_read_b32 v10, v10
	s_waitcnt vmcnt(3)
	s_barrier
	v_add_u32_e32 v107, v114, v115
	v_bitop3_b32 v116, v130, v11, 32 bitop3:0x36
	v_add_u32_e32 v109, v114, v117
	v_bitop3_b32 v118, v130, v11, s65 bitop3:0x36
	s_add_i32 s5, s4, 0xffffff81
	v_add_u32_e32 v108, v114, v116
	ds_read_b128 v[12:15], v107
	ds_read_b128 v[16:19], v108
	v_add_u32_e32 v110, v114, v118
	ds_read_b128 v[20:23], v109
	ds_read_b128 v[24:27], v110
	s_ashr_i32 s5, s5, 6
	s_cmpk_gt_i32 s4, 0xbe
	v_or_b32_e32 v111, s4, v2
	s_cselect_b32 s47, s5, 0
	s_addk_i32 s4, 0xde
	s_ashr_i32 s45, s4, 6
	s_waitcnt lgkmcnt(0)
	s_waitcnt vmcnt(0) lgkmcnt(0)
	v_mfma_f32_32x32x16_bf16 v[64:79], v[12:15], v[92:95], 0
	s_cmp_gt_i32 s47, 0
	s_cselect_b64 s[4:5], -1, 0
	s_cmp_lt_i32 s45, 1
	s_cselect_b64 s[6:7], -1, 0
	s_or_b64 s[4:5], s[6:7], s[4:5]
	s_and_b64 vcc, exec, s[4:5]
	v_mfma_f32_32x32x16_bf16 v[64:79], v[16:19], v[88:91], v[64:79]
	v_mfma_f32_32x32x16_bf16 v[64:79], v[20:23], v[84:87], v[64:79]
	v_mfma_f32_32x32x16_bf16 v[64:79], v[24:27], v[80:83], v[64:79]
	s_cbranch_vccnz .LBB0_1948
	v_lshlrev_b32_e32 v8, 2, v8
	v_sub_u32_e32 v8, v8, v111
	v_lshl_add_u32 v8, v8, 2, s88
	ds_read2_b32 v[12:13], v8 offset0:240 offset1:241
	ds_read2_b32 v[14:15], v8 offset0:242 offset1:243
	ds_read2_b32 v[16:17], v8 offset0:248 offset1:249
	ds_read2_b32 v[18:19], v8 offset0:250 offset1:251
	ds_read2_b32 v[20:21], v8 offset0:224 offset1:225
	ds_read2_b32 v[22:23], v8 offset0:226 offset1:227
	ds_read2_b32 v[24:25], v8 offset0:232 offset1:233
	ds_read2_b32 v[26:27], v8 offset0:234 offset1:235
	s_waitcnt lgkmcnt(4)
	v_pk_add_f32 v[78:79], v[78:79], v[18:19]
	v_pk_add_f32 v[76:77], v[76:77], v[16:17]
	v_pk_add_f32 v[74:75], v[74:75], v[14:15]
	v_pk_add_f32 v[72:73], v[72:73], v[12:13]
	s_waitcnt lgkmcnt(0)
	v_pk_add_f32 v[70:71], v[70:71], v[26:27]
	v_pk_add_f32 v[68:69], v[68:69], v[24:25]
	v_pk_add_f32 v[66:67], v[66:67], v[22:23]
	v_pk_add_f32 v[64:65], v[64:65], v[20:21]

; #define LAS __attribute__((address_space(3)))
; DI void pv_mma(f32x16* o, const s16x4* vf, bf16x8 pa0, bf16x8 pa1) {
;     ...
; #pragma unroll
;     for (int d0 = 0; d0 < 4; ++d0) {
;         o[d0] = __builtin_amdgcn_mfma_f32_32x32x16_bf16(pa0, ATT_PK(vf[4 * d0], vf[4 * d0 + 1]), o[d0], 0, 0, 0);
;         o[d0] = __builtin_amdgcn_mfma_f32_32x32x16_bf16(pa1, ATT_PK(vf[4 * d0 + 2], vf[4 * d0 + 3]), o[d0], 0, 0, 0); }
;     ...
; }
; template <int DQK, int D0A, int D0B> DI void k_reads(bf16x8* kf, const LAS unsigned char* Ks, int half, int r32, int hi) {
; #pragma unroll
;     for (int d0 = D0A; d0 < D0B; ++d0) kf[d0 - D0A] = *(const LAS bf16x8*)(Ks + half * (32 * DQK * 2) + kswz<DQK>(r32, (d0 * 16 + hi * 8) * 2));
; }
; template <int D0A, int D0B> DI void qk_mma(f32x16& p, const bf16x8* kf, const bf16x8* qr) {
; #pragma unroll
;     for (int d0 = D0A; d0 < D0B; ++d0) {
;         if (d0 == 0) { f32x16 z; _Pragma("unroll") for (int r = 0; r < 16; ++r) z[r] = 0.f; p = __builtin_amdgcn_mfma_f32_32x32x16_bf16(kf[0], qr[0], z, 0, 0, 0); }
;         else p = __builtin_amdgcn_mfma_f32_32x32x16_bf16(kf[d0 - D0A], qr[d0], p, 0, 0, 0); }
; }
.LBB0_1953:
	s_add_i32 s3, s0, -1
	s_add_i32 s2, s22, 0xffffa000
	s_and_b32 s2, s2, 0x6000
	v_add_u32_e32 v121, s2, v114
	v_add_u32_e32 v122, v121, v115
	v_add_u32_e32 v126, v121, v116
	ds_read_b128 v[122:125], v122 offset:4096
	ds_read_b128 v[132:135], v126 offset:4096
	v_add_u32_e32 v126, v121, v117
	v_add_u32_e32 v121, v121, v118
	s_lshl_b32 s2, s23, 14
	ds_read_b128 v[136:139], v126 offset:4096
	ds_read_b128 v[140:143], v121 offset:4096
	v_add_u32_e32 v121, s2, v106
	ds_read_b64_tr_b16 v[144:145], v121 offset:0
	ds_read_b64_tr_b16 v[146:147], v121 offset:0x800
	ds_read_b64_tr_b16 v[148:149], v121 offset:0x1000
	ds_read_b64_tr_b16 v[150:151], v121 offset:0x1800
	ds_read_b64_tr_b16 v[152:153], v121 offset:0x200
	ds_read_b64_tr_b16 v[154:155], v121 offset:0xa00
	ds_read_b64_tr_b16 v[156:157], v121 offset:0x1200
	ds_read_b64_tr_b16 v[158:159], v121 offset:0x1a00
	ds_read_b64_tr_b16 v[162:163], v121 offset:0x400
	ds_read_b64_tr_b16 v[164:165], v121 offset:0xc00
	ds_read_b64_tr_b16 v[166:167], v121 offset:0x1400
	ds_read_b64_tr_b16 v[168:169], v121 offset:0x1c00
	ds_read_b64_tr_b16 v[170:171], v121 offset:0x600
	ds_read_b64_tr_b16 v[172:173], v121 offset:0xe00
	ds_read_b64_tr_b16 v[174:175], v121 offset:0x1600
	ds_read_b64_tr_b16 v[176:177], v121 offset:0x1e00
	v_exp_f32_e32 v64, v64
	v_exp_f32_e32 v65, v65
	v_exp_f32_e32 v66, v66
	v_exp_f32_e32 v67, v67
	v_exp_f32_e32 v68, v68
	v_add_f32_e32 v126, 0, v64
	v_exp_f32_e32 v69, v69
	v_add_f32_e32 v126, v65, v126
	v_exp_f32_e32 v70, v70
	v_add_f32_e32 v126, v66, v126
	v_exp_f32_e32 v71, v71
	v_add_f32_e32 v126, v67, v126
	v_exp_f32_e32 v72, v72
	v_add_f32_e32 v126, v68, v126
	v_exp_f32_e32 v73, v73
	v_add_f32_e32 v126, v69, v126
	v_exp_f32_e32 v74, v74
	v_add_f32_e32 v126, v70, v126
	v_exp_f32_e32 v75, v75
	v_add_f32_e32 v126, v71, v126
	v_exp_f32_e32 v76, v76
	v_add_f32_e32 v126, v72, v126
	v_exp_f32_e32 v77, v77
	v_add_f32_e32 v126, v73, v126
	v_exp_f32_e32 v78, v78
	v_add_f32_e32 v126, v74, v126
	v_exp_f32_e32 v79, v79
	v_add_f32_e32 v126, v75, v126
	v_add_f32_e32 v126, v76, v126
	v_add_f32_e32 v126, v77, v126
	v_add_f32_e32 v126, v78, v126
	v_add_f32_e32 v126, v79, v126
	v_add_f32_e32 v120, v126, v120
	v_cvt_pk_bf16_f32 v64, v64, v65
	v_cvt_pk_bf16_f32 v65, v66, v67
	v_cvt_pk_bf16_f32 v66, v68, v69
	v_cvt_pk_bf16_f32 v67, v70, v71
	v_cvt_pk_bf16_f32 v68, v72, v73
	v_cvt_pk_bf16_f32 v69, v74, v75
	v_cvt_pk_bf16_f32 v70, v76, v77
	v_cvt_pk_bf16_f32 v71, v78, v79
	s_nop 0
	v_permlane32_swap_b32_e32 v64, v66
	v_permlane32_swap_b32_e32 v65, v67
	v_permlane32_swap_b32_e32 v68, v70
	v_permlane32_swap_b32_e32 v69, v71
	s_waitcnt lgkmcnt(0)
	v_mfma_f32_32x32x16_bf16 v[0:15], v[64:67], v[144:147], v[0:15]
	s_cmp_lt_i32 s3, s47
	s_cselect_b64 s[74:75], -1, 0
	s_cmp_ge_i32 s3, s52
	s_cselect_b64 s[90:91], -1, 0
	s_or_b64 s[74:75], s[74:75], s[90:91]
	s_and_b64 vcc, exec, s[74:75]
	v_mfma_f32_32x32x16_bf16 v[48:63], v[64:67], v[152:155], v[48:63]
	v_mfma_f32_32x32x16_bf16 v[16:31], v[64:67], v[162:165], v[16:31]
	v_mfma_f32_32x32x16_bf16 v[32:47], v[64:67], v[170:173], v[32:47]
	v_mfma_f32_32x32x16_bf16 v[0:15], v[68:71], v[148:151], v[0:15]
	v_mfma_f32_32x32x16_bf16 v[48:63], v[68:71], v[156:159], v[48:63]
	v_mfma_f32_32x32x16_bf16 v[16:31], v[68:71], v[166:169], v[16:31]
	v_mfma_f32_32x32x16_bf16 v[32:47], v[68:71], v[174:177], v[32:47]
	v_mfma_f32_32x32x16_bf16 v[64:79], v[122:125], v[92:95], 0
	v_mfma_f32_32x32x16_bf16 v[64:79], v[132:135], v[88:91], v[64:79]
	v_mfma_f32_32x32x16_bf16 v[64:79], v[136:139], v[84:87], v[64:79]
	v_mfma_f32_32x32x16_bf16 v[64:79], v[140:143], v[80:83], v[64:79]
	v_add_u32_e32 v122, s7, v119
	s_cbranch_vccnz .LBB0_1955
	v_add_u32_e32 v138, 0x28908, v122
	v_add_u32_e32 v140, 0x28920, v122
	v_add_u32_e32 v142, 0x28928, v122
	v_add_u32_e32 v124, 0x28940, v122
	v_add_u32_e32 v126, 0x28948, v122
	v_add_u32_e32 v132, 0x28960, v122
	v_add_u32_e32 v134, 0x28968, v122
	v_add_u32_e32 v123, 0x28900, v122
	ds_read2_b32 v[124:125], v124 offset1:1
	ds_read2_b32 v[126:127], v126 offset1:1
	ds_read2_b32 v[132:133], v132 offset1:1
	ds_read2_b32 v[134:135], v134 offset1:1
	ds_read2_b32 v[136:137], v123 offset1:1
	ds_read2_b32 v[138:139], v138 offset1:1
	ds_read2_b32 v[140:141], v140 offset1:1
	ds_read2_b32 v[142:143], v142 offset1:1
	s_waitcnt lgkmcnt(0)
	v_pk_add_f32 v[78:79], v[78:79], v[134:135]
	v_pk_add_f32 v[76:77], v[76:77], v[132:133]
	v_pk_add_f32 v[74:75], v[74:75], v[126:127]
	v_pk_add_f32 v[72:73], v[72:73], v[124:125]
	v_pk_add_f32 v[70:71], v[70:71], v[142:143]
	v_pk_add_f32 v[68:69], v[68:69], v[140:141]
	v_pk_add_f32 v[66:67], v[66:67], v[138:139]
	v_pk_add_f32 v[64:65], v[64:65], v[136:137]

; #define SBAR() __builtin_amdgcn_sched_barrier(0)
; #define ATT_DMA_K(t) do { const bf16_t* kg_ = Kh + (size_t)(t) * 64 * LDK; LAS unsigned char* sb_ = lds + ((t) & 3) * KBUF; \
;     _Pragma("unroll") for (int i_ = 0; i_ < NKP; ++i_) __builtin_amdgcn_global_load_lds((const unsigned*)(kg_ + kgo[i_]), (LAS unsigned*)(sb_ + (wid + 8 * i_) * 1024), 16, 0, 0); } while (0)
; #define ATT_DMA_V(t, vs) do { const bf16_t* vg_ = Vh + (size_t)(t) * 64 * LDV; LAS unsigned char* sb_ = lds + V_OFF + (vs) * SHM_V; \
;     _Pragma("unroll") for (int i_ = 0; i_ < 2; ++i_) __builtin_amdgcn_global_load_lds((const unsigned*)(vg_ + vgo[i_]), (LAS unsigned*)(sb_ + (2 * wid + i_) * 1024), 16, 0, 0); } while (0)
; #define ATT_SEG(t) do { if constexpr (MODE != 0) { if (((t) == tL && tL > 0) || (t) == tR) { const float f_ = (t) == tR ? fR : fL; l_reg *= f_; \
;     _Pragma("unroll") for (int d = 0; d < 4; ++d) _Pragma("unroll") for (int r = 0; r < 16; ++r) o[d][r] *= f_; } } } while (0)
; #define ATT_BIAS(P, t, half) do { if constexpr (MODE != 0) { if ((t) >= tL && (t) < tR) { const LAS float* bp_ = bt + ((t) * 64 + (half) * 32 - qpos + 224 + 4 * hi);     \
;     _Pragma("unroll") for (int r = 0; r < 16; ++r) P[r] += bp_[(r & 3) + 8 * (r >> 2)]; } } } while (0)
; #define ATT_TOP(N) do { asm volatile("s_waitcnt vmcnt(%0)" :: "n"(N) : "memory"); __builtin_amdgcn_s_barrier(); asm volatile("" ::: "memory"); } while (0)
; template <int DQK, int MODE, int LDQ, int LDK, int LDV> ...
;     ...
;     f32x16 pA, pB; bf16x8 pa0, pa1;
;     int v0 = 0, v1 = 1, v2 = 2;
;     ATT_TOP(NKP + 2);
;     { bf16x8 kf[NDA]; k_reads<DQK, 0, NDA>(kf, lds, 0, r32, hi); ATT_LGKM0(); qk_mma<0, NDA>(pA, kf, qr);
;       if constexpr (ND0 > NDA) { bf16x8 kg[ND0 - NDA]; k_reads<DQK, NDA, ND0>(kg, lds, 0, r32, hi); ATT_LGKM0(); qk_mma<NDA, ND0>(pA, kg, qr); }
;       ATT_BIAS(pA, 0, 0); }
;     if (wid >= 4) __builtin_amdgcn_s_setprio(1);
;     for (int j = 0; j < NT; ++j) {
;         if (j + 2 < NT) ATT_TOP(NKP + 2); else ATT_TOP(0);
;         if (j + 3 < NT) ATT_DMA_K(j + 3);
;         if (j + 2 < NT) ATT_DMA_V(j + 2, v2);
;         ATT_SEG(j); SBAR();
;         ATT_STEP(pA, pB, 0, v0, true, 1, j);
;         ATT_STEP(pB, pA, 1, v0, (j + 1 < NT), 0, j + 1);
;         { const int t_ = v0; v0 = v1; v1 = v2; v2 = t_; }
;     }
.LBB0_1961:
	ds_read_b128 v[98:101], v107 offset:12288
	ds_read_b128 v[102:105], v108 offset:12288
	ds_read_b128 v[114:117], v109 offset:12288
	ds_read_b128 v[122:125], v110 offset:12288
	v_lshl_add_u32 v96, s49, 14, v106
	ds_read_b64_tr_b16 v[132:133], v96 offset:0
	ds_read_b64_tr_b16 v[134:135], v96 offset:0x800
	ds_read_b64_tr_b16 v[136:137], v96 offset:0x1000
	ds_read_b64_tr_b16 v[138:139], v96 offset:0x1800
	ds_read_b64_tr_b16 v[140:141], v96 offset:0x200
	ds_read_b64_tr_b16 v[142:143], v96 offset:0xa00
	ds_read_b64_tr_b16 v[144:145], v96 offset:0x1200
	ds_read_b64_tr_b16 v[146:147], v96 offset:0x1a00
	ds_read_b64_tr_b16 v[148:149], v96 offset:0x400
	ds_read_b64_tr_b16 v[150:151], v96 offset:0xc00
	ds_read_b64_tr_b16 v[152:153], v96 offset:0x1400
	ds_read_b64_tr_b16 v[154:155], v96 offset:0x1c00
	ds_read_b64_tr_b16 v[156:157], v96 offset:0x600
	ds_read_b64_tr_b16 v[158:159], v96 offset:0xe00
	ds_read_b64_tr_b16 v[162:163], v96 offset:0x1600
	ds_read_b64_tr_b16 v[164:165], v96 offset:0x1e00
	v_exp_f32_e32 v64, v64
	v_exp_f32_e32 v65, v65
	v_exp_f32_e32 v66, v66
	v_exp_f32_e32 v67, v67
	v_exp_f32_e32 v68, v68
	v_add_f32_e32 v97, 0, v64
	v_exp_f32_e32 v69, v69
	v_add_f32_e32 v97, v65, v97
	v_exp_f32_e32 v70, v70
	v_add_f32_e32 v97, v66, v97
	v_exp_f32_e32 v71, v71
	v_add_f32_e32 v97, v67, v97
	v_exp_f32_e32 v72, v72
	v_add_f32_e32 v97, v68, v97
	v_exp_f32_e32 v73, v73
	v_add_f32_e32 v97, v69, v97
	v_exp_f32_e32 v74, v74
	v_add_f32_e32 v97, v70, v97
	v_exp_f32_e32 v75, v75
	v_add_f32_e32 v97, v71, v97
	v_exp_f32_e32 v76, v76
	v_add_f32_e32 v97, v72, v97
	v_exp_f32_e32 v77, v77
	v_add_f32_e32 v97, v73, v97
	v_exp_f32_e32 v78, v78
	v_add_f32_e32 v97, v74, v97
	v_exp_f32_e32 v79, v79
	v_add_f32_e32 v97, v75, v97
	v_add_f32_e32 v97, v76, v97
	v_add_f32_e32 v97, v77, v97
	v_add_f32_e32 v97, v78, v97
	v_add_f32_e32 v97, v79, v97
	v_add_f32_e32 v97, v97, v120
	v_cvt_pk_bf16_f32 v64, v64, v65
	v_cvt_pk_bf16_f32 v65, v66, v67
	v_cvt_pk_bf16_f32 v66, v68, v69
	v_cvt_pk_bf16_f32 v67, v70, v71
	v_cvt_pk_bf16_f32 v68, v72, v73
	v_cvt_pk_bf16_f32 v69, v74, v75
	v_cvt_pk_bf16_f32 v70, v76, v77
	v_cvt_pk_bf16_f32 v71, v78, v79
	s_nop 0
	v_permlane32_swap_b32_e32 v64, v66
	v_permlane32_swap_b32_e32 v65, v67
	v_permlane32_swap_b32_e32 v68, v70
	v_permlane32_swap_b32_e32 v69, v71
	s_waitcnt lgkmcnt(0)
	v_mfma_f32_32x32x16_bf16 v[0:15], v[64:67], v[132:135], v[0:15]
	s_cmp_gt_i32 s47, 61
	s_cselect_b64 s[0:1], -1, 0
	s_cmp_lt_i32 s45, 62
	s_cselect_b64 s[2:3], -1, 0
	s_or_b64 s[0:1], s[0:1], s[2:3]
	s_and_b64 vcc, exec, s[0:1]
	v_mfma_f32_32x32x16_bf16 v[48:63], v[64:67], v[140:143], v[48:63]
	v_mfma_f32_32x32x16_bf16 v[16:31], v[64:67], v[148:151], v[16:31]
	v_mfma_f32_32x32x16_bf16 v[32:47], v[64:67], v[156:159], v[32:47]
	v_mfma_f32_32x32x16_bf16 v[0:15], v[68:71], v[136:139], v[0:15]
	v_mfma_f32_32x32x16_bf16 v[48:63], v[68:71], v[144:147], v[48:63]
	v_mfma_f32_32x32x16_bf16 v[16:31], v[68:71], v[152:155], v[16:31]
	v_mfma_f32_32x32x16_bf16 v[32:47], v[68:71], v[162:165], v[32:47]
	s_waitcnt lgkmcnt(0)
	v_mfma_f32_32x32x16_bf16 v[64:79], v[98:101], v[92:95], 0
	v_mfma_f32_32x32x16_bf16 v[64:79], v[102:105], v[88:91], v[64:79]
	v_mfma_f32_32x32x16_bf16 v[64:79], v[114:117], v[84:87], v[64:79]
	v_mfma_f32_32x32x16_bf16 v[64:79], v[122:125], v[80:83], v[64:79]
	s_cbranch_vccnz .LBB0_1963
	v_sub_u32_e32 v98, 0xf40, v111
	v_lshlrev_b32_e32 v98, 2, v98
	v_add3_u32 v98, s88, v98, v130
	v_add_u32_e32 v114, 0x400, v98
	v_add_u32_e32 v116, 0x408, v98
	v_add_u32_e32 v118, 0x420, v98
	v_add_u32_e32 v120, 0x428, v98
	v_add_u32_e32 v99, 0x440, v98
	v_add_u32_e32 v100, 0x448, v98
	v_add_u32_e32 v102, 0x460, v98
	v_add_u32_e32 v104, 0x468, v98
	ds_read2_b32 v[98:99], v99 offset1:1
	ds_read2_b32 v[100:101], v100 offset1:1
	ds_read2_b32 v[102:103], v102 offset1:1
	ds_read2_b32 v[104:105], v104 offset1:1
	ds_read2_b32 v[114:115], v114 offset1:1
	ds_read2_b32 v[116:117], v116 offset1:1
	ds_read2_b32 v[118:119], v118 offset1:1
	ds_read2_b32 v[120:121], v120 offset1:1
	s_waitcnt lgkmcnt(0)
	v_pk_add_f32 v[78:79], v[78:79], v[104:105]
	v_pk_add_f32 v[76:77], v[76:77], v[102:103]
	v_pk_add_f32 v[74:75], v[74:75], v[100:101]
	v_pk_add_f32 v[72:73], v[72:73], v[98:99]
	v_pk_add_f32 v[70:71], v[70:71], v[120:121]
	v_pk_add_f32 v[68:69], v[68:69], v[118:119]
	v_pk_add_f32 v[66:67], v[66:67], v[116:117]
	v_pk_add_f32 v[64:65], v[64:65], v[114:115]
.LBB0_1963:
	ds_read_b128 v[98:101], v107 offset:16384
	ds_read_b128 v[102:105], v108 offset:16384
	ds_read_b128 v[114:117], v109 offset:16384
	ds_read_b128 v[118:121], v110 offset:16384
	ds_read_b64_tr_b16 v[122:123], v96 offset:0x2000
	ds_read_b64_tr_b16 v[124:125], v96 offset:0x2800
	ds_read_b64_tr_b16 v[132:133], v96 offset:0x3000
	ds_read_b64_tr_b16 v[134:135], v96 offset:0x3800
	ds_read_b64_tr_b16 v[136:137], v96 offset:0x2200
	ds_read_b64_tr_b16 v[138:139], v96 offset:0x2a00
	ds_read_b64_tr_b16 v[140:141], v96 offset:0x3200
	ds_read_b64_tr_b16 v[142:143], v96 offset:0x3a00
	ds_read_b64_tr_b16 v[144:145], v96 offset:0x2400
	ds_read_b64_tr_b16 v[146:147], v96 offset:0x2c00
	ds_read_b64_tr_b16 v[148:149], v96 offset:0x3400
	ds_read_b64_tr_b16 v[150:151], v96 offset:0x3c00
	ds_read_b64_tr_b16 v[152:153], v96 offset:0x2600
	ds_read_b64_tr_b16 v[154:155], v96 offset:0x2e00
	ds_read_b64_tr_b16 v[156:157], v96 offset:0x3600
	ds_read_b64_tr_b16 v[158:159], v96 offset:0x3e00
	s_nop 6
	v_exp_f32_e32 v64, v64
	v_exp_f32_e32 v65, v65
	v_exp_f32_e32 v66, v66
	v_exp_f32_e32 v67, v67
	v_exp_f32_e32 v68, v68
	v_add_f32_e32 v96, 0, v64
	v_exp_f32_e32 v69, v69
	v_add_f32_e32 v96, v65, v96
	v_exp_f32_e32 v70, v70
	v_add_f32_e32 v96, v66, v96
	v_exp_f32_e32 v71, v71
	v_add_f32_e32 v96, v67, v96
	v_exp_f32_e32 v72, v72
	v_add_f32_e32 v96, v68, v96
	v_exp_f32_e32 v73, v73
	v_add_f32_e32 v96, v69, v96
	v_exp_f32_e32 v74, v74
	v_add_f32_e32 v96, v70, v96
	v_exp_f32_e32 v75, v75
	v_add_f32_e32 v96, v71, v96
	v_exp_f32_e32 v76, v76
	v_add_f32_e32 v96, v72, v96
	v_exp_f32_e32 v77, v77
	v_add_f32_e32 v96, v73, v96
	v_exp_f32_e32 v78, v78
	v_add_f32_e32 v96, v74, v96
	v_exp_f32_e32 v79, v79
	v_add_f32_e32 v96, v75, v96
	v_add_f32_e32 v96, v76, v96
	v_add_f32_e32 v96, v77, v96
	v_add_f32_e32 v96, v78, v96
	v_add_f32_e32 v96, v79, v96
	v_add_f32_e32 v96, v97, v96
	v_cvt_pk_bf16_f32 v64, v64, v65
	v_cvt_pk_bf16_f32 v65, v66, v67
	v_cvt_pk_bf16_f32 v66, v68, v69
	v_cvt_pk_bf16_f32 v67, v70, v71
	v_cvt_pk_bf16_f32 v68, v72, v73
	v_cvt_pk_bf16_f32 v69, v74, v75
	v_cvt_pk_bf16_f32 v70, v76, v77
	v_cvt_pk_bf16_f32 v71, v78, v79
	s_nop 0
	v_permlane32_swap_b32_e32 v64, v66
	v_permlane32_swap_b32_e32 v65, v67
	v_permlane32_swap_b32_e32 v68, v70
	v_permlane32_swap_b32_e32 v69, v71
	s_waitcnt lgkmcnt(0)
	s_cmp_lt_u32 s33, 0x100
	s_cbranch_scc1 .Lstg_d1_m61_21
	s_waitcnt vmcnt(0)
	s_barrier

.LBB0_1967:
	ds_read_b128 v[100:103], v107 offset:20480
	ds_read_b128 v[114:117], v108 offset:20480
	ds_read_b128 v[118:121], v109 offset:20480
	ds_read_b128 v[122:125], v110 offset:20480
	v_add_u32_e32 v98, 0x8000, v106
	ds_read_b64_tr_b16 v[132:133], v98 offset:0
	ds_read_b64_tr_b16 v[134:135], v98 offset:0x800
	ds_read_b64_tr_b16 v[136:137], v98 offset:0x1000
	ds_read_b64_tr_b16 v[138:139], v98 offset:0x1800
	ds_read_b64_tr_b16 v[140:141], v98 offset:0x200
	ds_read_b64_tr_b16 v[142:143], v98 offset:0xa00
	ds_read_b64_tr_b16 v[144:145], v98 offset:0x1200
	ds_read_b64_tr_b16 v[146:147], v98 offset:0x1a00
	ds_read_b64_tr_b16 v[148:149], v98 offset:0x400
	ds_read_b64_tr_b16 v[150:151], v98 offset:0xc00
	ds_read_b64_tr_b16 v[152:153], v98 offset:0x1400
	ds_read_b64_tr_b16 v[154:155], v98 offset:0x1c00
	ds_read_b64_tr_b16 v[156:157], v98 offset:0x600
	ds_read_b64_tr_b16 v[158:159], v98 offset:0xe00
	ds_read_b64_tr_b16 v[162:163], v98 offset:0x1600
	ds_read_b64_tr_b16 v[164:165], v98 offset:0x1e00
	v_exp_f32_e32 v64, v64
	v_exp_f32_e32 v65, v65
	v_exp_f32_e32 v66, v66
	v_exp_f32_e32 v67, v67
	v_exp_f32_e32 v68, v68
	v_add_f32_e32 v99, 0, v64
	v_exp_f32_e32 v69, v69
	v_add_f32_e32 v99, v65, v99
	v_exp_f32_e32 v70, v70
	v_add_f32_e32 v99, v66, v99
	v_exp_f32_e32 v71, v71
	v_add_f32_e32 v99, v67, v99
	v_exp_f32_e32 v72, v72
	v_add_f32_e32 v99, v68, v99
	v_exp_f32_e32 v73, v73
	v_add_f32_e32 v99, v69, v99
	v_exp_f32_e32 v74, v74
	v_add_f32_e32 v99, v70, v99
	v_exp_f32_e32 v75, v75
	v_add_f32_e32 v99, v71, v99
	v_exp_f32_e32 v76, v76
	v_add_f32_e32 v99, v72, v99
	v_exp_f32_e32 v77, v77
	v_add_f32_e32 v99, v73, v99
	v_exp_f32_e32 v78, v78
	v_add_f32_e32 v99, v74, v99
	v_exp_f32_e32 v79, v79
	v_add_f32_e32 v99, v75, v99
	v_add_f32_e32 v99, v76, v99
	v_add_f32_e32 v99, v77, v99
	v_add_f32_e32 v99, v78, v99
	v_add_f32_e32 v99, v79, v99
	v_add_f32_e32 v96, v99, v96
	v_cvt_pk_bf16_f32 v64, v64, v65
	v_cvt_pk_bf16_f32 v65, v66, v67
	v_cvt_pk_bf16_f32 v66, v68, v69
	v_cvt_pk_bf16_f32 v67, v70, v71
	v_cvt_pk_bf16_f32 v68, v72, v73
	v_cvt_pk_bf16_f32 v69, v74, v75
	v_cvt_pk_bf16_f32 v70, v76, v77
	v_cvt_pk_bf16_f32 v71, v78, v79
	s_nop 0
	v_permlane32_swap_b32_e32 v64, v66
	v_permlane32_swap_b32_e32 v65, v67
	v_permlane32_swap_b32_e32 v68, v70
	v_permlane32_swap_b32_e32 v69, v71
	s_waitcnt lgkmcnt(0)
	v_mfma_f32_32x32x16_bf16 v[0:15], v[64:67], v[132:135], v[0:15]
	s_and_b64 vcc, exec, s[2:3]
	v_mfma_f32_32x32x16_bf16 v[48:63], v[64:67], v[140:143], v[48:63]
	v_mfma_f32_32x32x16_bf16 v[16:31], v[64:67], v[148:151], v[16:31]
	v_mfma_f32_32x32x16_bf16 v[32:47], v[64:67], v[156:159], v[32:47]
	v_mfma_f32_32x32x16_bf16 v[0:15], v[68:71], v[136:139], v[0:15]
	v_mfma_f32_32x32x16_bf16 v[48:63], v[68:71], v[144:147], v[48:63]
	v_mfma_f32_32x32x16_bf16 v[16:31], v[68:71], v[152:155], v[16:31]
	v_mfma_f32_32x32x16_bf16 v[32:47], v[68:71], v[162:165], v[32:47]
	s_waitcnt lgkmcnt(0)
	v_mfma_f32_32x32x16_bf16 v[64:79], v[100:103], v[92:95], 0
	v_mfma_f32_32x32x16_bf16 v[64:79], v[114:117], v[88:91], v[64:79]
	v_mfma_f32_32x32x16_bf16 v[64:79], v[118:121], v[84:87], v[64:79]
	v_mfma_f32_32x32x16_bf16 v[64:79], v[122:125], v[80:83], v[64:79]
	s_cbranch_vccnz .LBB0_1969
	v_add3_u32 v97, s88, v97, v130
	v_add_u32_e32 v118, 0x408, v97
	v_add_u32_e32 v120, 0x420, v97
	v_add_u32_e32 v122, 0x428, v97
	v_add_u32_e32 v100, 0x440, v97
	v_add_u32_e32 v102, 0x448, v97
	v_add_u32_e32 v104, 0x460, v97
	v_add_u32_e32 v99, 0x400, v97
	v_add_u32_e32 v97, 0x468, v97
	ds_read2_b32 v[100:101], v100 offset1:1
	ds_read2_b32 v[102:103], v102 offset1:1
	ds_read2_b32 v[104:105], v104 offset1:1
	ds_read2_b32 v[114:115], v97 offset1:1
	ds_read2_b32 v[116:117], v99 offset1:1
	ds_read2_b32 v[118:119], v118 offset1:1
	ds_read2_b32 v[120:121], v120 offset1:1
	ds_read2_b32 v[122:123], v122 offset1:1
	s_waitcnt lgkmcnt(0)
	v_pk_add_f32 v[78:79], v[78:79], v[114:115]
	v_pk_add_f32 v[76:77], v[76:77], v[104:105]
	v_pk_add_f32 v[74:75], v[74:75], v[102:103]
	v_pk_add_f32 v[72:73], v[72:73], v[100:101]
	v_pk_add_f32 v[70:71], v[70:71], v[122:123]
	v_pk_add_f32 v[68:69], v[68:69], v[120:121]
	v_pk_add_f32 v[66:67], v[66:67], v[118:119]
	v_pk_add_f32 v[64:65], v[64:65], v[116:117]

; DI void expsum(f32x16& p, float& l_reg, bf16x8& pa0, bf16x8& pa1) {
; #pragma unroll
;     for (int r = 0; r < 16; ++r) p[r] = __builtin_amdgcn_exp2f(p[r]);
;     float ps = 0.f;
; #pragma unroll
;     for (int r = 0; r < 16; ++r) ps += p[r];
;     l_reg += ps; asm volatile("" : "+v"(l_reg));
;     ...
;     ATT_PK4(p, 0, pa0); ATT_PK4(p, 8, pa1);
;     ...
; }
.LBB0_1973:
	ds_read_b128 v[98:101], v107 offset:28672
	ds_read_b128 v[102:105], v108 offset:28672
	ds_read_b128 v[112:115], v109 offset:28672
	ds_read_b128 v[108:111], v110 offset:28672
	ds_read_b64_tr_b16 v[116:117], v106 offset:0
	ds_read_b64_tr_b16 v[118:119], v106 offset:0x800
	ds_read_b64_tr_b16 v[120:121], v106 offset:0x1000
	ds_read_b64_tr_b16 v[122:123], v106 offset:0x1800
	ds_read_b64_tr_b16 v[124:125], v106 offset:0x200
	ds_read_b64_tr_b16 v[126:127], v106 offset:0xa00
	ds_read_b64_tr_b16 v[132:133], v106 offset:0x1200
	ds_read_b64_tr_b16 v[134:135], v106 offset:0x1a00
	ds_read_b64_tr_b16 v[136:137], v106 offset:0x400
	ds_read_b64_tr_b16 v[138:139], v106 offset:0xc00
	ds_read_b64_tr_b16 v[140:141], v106 offset:0x1400
	ds_read_b64_tr_b16 v[142:143], v106 offset:0x1c00
	ds_read_b64_tr_b16 v[144:145], v106 offset:0x600
	ds_read_b64_tr_b16 v[146:147], v106 offset:0xe00
	ds_read_b64_tr_b16 v[148:149], v106 offset:0x1600
	ds_read_b64_tr_b16 v[150:151], v106 offset:0x1e00
	v_exp_f32_e32 v64, v64
	v_exp_f32_e32 v65, v65
	v_exp_f32_e32 v66, v66
	v_exp_f32_e32 v67, v67
	v_exp_f32_e32 v68, v68
	v_add_f32_e32 v107, 0, v64
	v_exp_f32_e32 v69, v69
	v_add_f32_e32 v107, v65, v107
	v_exp_f32_e32 v70, v70
	v_add_f32_e32 v107, v66, v107
	v_exp_f32_e32 v71, v71
	v_add_f32_e32 v107, v67, v107
	v_exp_f32_e32 v72, v72
	v_add_f32_e32 v107, v68, v107
	v_exp_f32_e32 v73, v73
	v_add_f32_e32 v107, v69, v107
	v_exp_f32_e32 v74, v74
	v_add_f32_e32 v107, v70, v107
	v_exp_f32_e32 v75, v75
	v_add_f32_e32 v107, v71, v107
	v_exp_f32_e32 v76, v76
	v_add_f32_e32 v107, v72, v107
	v_exp_f32_e32 v77, v77
	v_add_f32_e32 v107, v73, v107
	v_exp_f32_e32 v78, v78
	v_add_f32_e32 v107, v74, v107
	v_exp_f32_e32 v79, v79
	v_add_f32_e32 v107, v75, v107
	v_add_f32_e32 v107, v76, v107
	v_add_f32_e32 v107, v77, v107
	v_add_f32_e32 v107, v78, v107
	v_add_f32_e32 v107, v79, v107
	v_add_f32_e32 v96, v107, v96
	v_cvt_pk_bf16_f32 v64, v64, v65
	v_cvt_pk_bf16_f32 v65, v66, v67
	v_cvt_pk_bf16_f32 v66, v68, v69
	v_cvt_pk_bf16_f32 v67, v70, v71
	v_cvt_pk_bf16_f32 v68, v72, v73
	v_cvt_pk_bf16_f32 v69, v74, v75
	v_cvt_pk_bf16_f32 v70, v76, v77
	v_cvt_pk_bf16_f32 v71, v78, v79
	s_nop 0
	v_permlane32_swap_b32_e32 v64, v66
	v_permlane32_swap_b32_e32 v65, v67
	v_permlane32_swap_b32_e32 v68, v70
	v_permlane32_swap_b32_e32 v69, v71
	s_waitcnt lgkmcnt(0)
	v_mfma_f32_32x32x16_bf16 v[0:15], v[64:67], v[116:119], v[0:15]
	s_and_b64 vcc, exec, s[2:3]
	v_mfma_f32_32x32x16_bf16 v[48:63], v[64:67], v[124:127], v[48:63]
	v_mfma_f32_32x32x16_bf16 v[16:31], v[64:67], v[136:139], v[16:31]
	v_mfma_f32_32x32x16_bf16 v[32:47], v[64:67], v[144:147], v[32:47]
	v_mfma_f32_32x32x16_bf16 v[0:15], v[68:71], v[120:123], v[0:15]
	v_mfma_f32_32x32x16_bf16 v[48:63], v[68:71], v[132:135], v[48:63]
	v_mfma_f32_32x32x16_bf16 v[16:31], v[68:71], v[140:143], v[16:31]
	v_mfma_f32_32x32x16_bf16 v[32:47], v[68:71], v[148:151], v[32:47]
	s_waitcnt lgkmcnt(0)
	v_mfma_f32_32x32x16_bf16 v[64:79], v[98:101], v[92:95], 0
	v_mfma_f32_32x32x16_bf16 v[64:79], v[102:105], v[88:91], v[64:79]
	v_mfma_f32_32x32x16_bf16 v[64:79], v[112:115], v[84:87], v[64:79]
	v_mfma_f32_32x32x16_bf16 v[64:79], v[108:111], v[80:83], v[64:79]
	s_cbranch_vccnz .LBB0_1975
	v_add3_u32 v80, s88, v97, v130
	v_add_u32_e32 v88, 0x400, v80
	v_add_u32_e32 v90, 0x408, v80
	v_add_u32_e32 v92, 0x420, v80
	v_add_u32_e32 v94, 0x428, v80
	v_add_u32_e32 v81, 0x440, v80
	v_add_u32_e32 v82, 0x448, v80
	v_add_u32_e32 v84, 0x460, v80
	v_add_u32_e32 v86, 0x468, v80
	ds_read2_b32 v[80:81], v81 offset1:1
	ds_read2_b32 v[82:83], v82 offset1:1
	ds_read2_b32 v[84:85], v84 offset1:1
	ds_read2_b32 v[86:87], v86 offset1:1
	ds_read2_b32 v[88:89], v88 offset1:1
	ds_read2_b32 v[90:91], v90 offset1:1
	ds_read2_b32 v[92:93], v92 offset1:1
	ds_read2_b32 v[94:95], v94 offset1:1
	s_waitcnt lgkmcnt(0)
	v_pk_add_f32 v[78:79], v[78:79], v[86:87]
	v_pk_add_f32 v[76:77], v[76:77], v[84:85]
	v_pk_add_f32 v[74:75], v[74:75], v[82:83]
	v_pk_add_f32 v[72:73], v[72:73], v[80:81]
	v_pk_add_f32 v[70:71], v[70:71], v[94:95]
	v_pk_add_f32 v[68:69], v[68:69], v[92:93]
	v_pk_add_f32 v[66:67], v[66:67], v[90:91]
	v_pk_add_f32 v[64:65], v[64:65], v[88:89]
.LBB0_1975:
	s_lshl_b32 s0, s44, 2
	s_add_i32 s0, s0, 0
	s_add_i32 s0, s0, 0x24000
	ds_read_b64_tr_b16 v[80:81], v106 offset:0x2000
	ds_read_b64_tr_b16 v[82:83], v106 offset:0x2800
	ds_read_b64_tr_b16 v[84:85], v106 offset:0x3000
	ds_read_b64_tr_b16 v[86:87], v106 offset:0x3800
	ds_read_b64_tr_b16 v[88:89], v106 offset:0x2200
	ds_read_b64_tr_b16 v[90:91], v106 offset:0x2a00
	ds_read_b64_tr_b16 v[92:93], v106 offset:0x3200
	ds_read_b64_tr_b16 v[94:95], v106 offset:0x3a00
	ds_read_b64_tr_b16 v[98:99], v106 offset:0x2400
	ds_read_b64_tr_b16 v[100:101], v106 offset:0x2c00
	ds_read_b64_tr_b16 v[102:103], v106 offset:0x3400
	ds_read_b64_tr_b16 v[104:105], v106 offset:0x3c00
	ds_read_b64_tr_b16 v[108:109], v106 offset:0x2600
	ds_read_b64_tr_b16 v[110:111], v106 offset:0x2e00
	ds_read_b64_tr_b16 v[112:113], v106 offset:0x3600
	ds_read_b64_tr_b16 v[114:115], v106 offset:0x3e00
	s_nop 7
	v_exp_f32_e32 v97, v64
	v_exp_f32_e32 v65, v65
	v_exp_f32_e32 v106, v66
	v_exp_f32_e32 v67, v67
	v_exp_f32_e32 v68, v68
	v_add_f32_e32 v64, 0, v97
	v_exp_f32_e32 v69, v69
	v_add_f32_e32 v64, v65, v64
	v_exp_f32_e32 v70, v70
	v_add_f32_e32 v64, v106, v64
	v_exp_f32_e32 v71, v71
	v_add_f32_e32 v64, v67, v64
	v_exp_f32_e32 v72, v72
	v_add_f32_e32 v64, v68, v64
	v_exp_f32_e32 v73, v73
	v_add_f32_e32 v64, v69, v64
	v_exp_f32_e32 v74, v74
	v_add_f32_e32 v64, v70, v64
	v_exp_f32_e32 v75, v75
	v_add_f32_e32 v64, v71, v64
	v_exp_f32_e32 v76, v76
	v_add_f32_e32 v64, v72, v64
	v_exp_f32_e32 v77, v77
	v_add_f32_e32 v64, v73, v64
	v_exp_f32_e32 v78, v78
	v_add_f32_e32 v64, v74, v64
	v_exp_f32_e32 v79, v79
	v_add_f32_e32 v64, v75, v64
	v_add_f32_e32 v64, v76, v64
	v_add_f32_e32 v64, v77, v64
	v_add_f32_e32 v64, v78, v64
	v_add_f32_e32 v64, v79, v64
	v_add_f32_e32 v64, v96, v64
	v_cvt_pk_bf16_f32 v66, v97, v65
	v_cvt_pk_bf16_f32 v67, v106, v67
	v_cvt_pk_bf16_f32 v68, v68, v69
	v_cvt_pk_bf16_f32 v69, v70, v71
	v_cvt_pk_bf16_f32 v70, v72, v73
	v_cvt_pk_bf16_f32 v71, v74, v75
	v_cvt_pk_bf16_f32 v72, v76, v77
	v_cvt_pk_bf16_f32 v73, v78, v79
	s_nop 0
	v_permlane32_swap_b32_e32 v66, v68
	v_permlane32_swap_b32_e32 v67, v69
	v_permlane32_swap_b32_e32 v70, v72
	v_permlane32_swap_b32_e32 v71, v73
	s_waitcnt lgkmcnt(0)
; template <int TAG = 0> DI int fresh_tid(int wv) { int l; asm volatile("v_mbcnt_lo_u32_b32 %0, -1, 0\n\tv_mbcnt_hi_u32_b32 %0, -1, %0 ; site %1" : "=v"(l) : "n"(TAG)); return wv * 64 + l; }
; DI int crow(int r, int hi) { return (r & 3) + 8 * (r >> 2) + 4 * hi; }
; DI float swap_sum(float v) { auto rr = __builtin_amdgcn_permlane32_swap(__float_as_uint(v), __float_as_uint(v), false, false); return __uint_as_float(rr[0]) + __uint_as_float(rr[1]); }
; DI void pv_mma(f32x16* o, const s16x4* vf, bf16x8 pa0, bf16x8 pa1) {
;     ...
; #pragma unroll
;     for (int d0 = 0; d0 < 4; ++d0) {
;         o[d0] = __builtin_amdgcn_mfma_f32_32x32x16_bf16(pa0, ATT_PK(vf[4 * d0], vf[4 * d0 + 1]), o[d0], 0, 0, 0);
;         o[d0] = __builtin_amdgcn_mfma_f32_32x32x16_bf16(pa1, ATT_PK(vf[4 * d0 + 2], vf[4 * d0 + 3]), o[d0], 0, 0, 0); }
;     ...
; }
; template <int DQK, int MODE, int LDQ, int LDK, int LDV> ...
;     ...
;     __builtin_amdgcn_s_setprio(0);
;     ...
;     l_reg = swap_sum(l_reg);
;     { const int lane2 = fresh_tid<110 + MODE>(wv) & 63, r32 = lane2 & 31, hi = lane2 >> 5;
;     if (hi == 0) li_l[r32] = l_reg;
;     asm volatile("s_waitcnt lgkmcnt(0)" ::: "memory");
;     float s0v[MODE == 2 ? 16 : 1][4];
;     if constexpr (MODE == 2) {
; #pragma unroll
;         for (int r = 0; r < 16; ++r)
; #pragma unroll
;             for (int d0 = 0; d0 < 4; ++d0) s0v[r][d0] = S0[(size_t)(wid * 32 + crow(r, hi)) * 512 + d0 * 32 + r32];
;     }
	v_mfma_f32_32x32x16_bf16 v[0:15], v[66:69], v[80:83], v[0:15]
	v_mfma_f32_32x32x16_bf16 v[48:63], v[66:69], v[88:91], v[48:63]
	v_mfma_f32_32x32x16_bf16 v[16:31], v[66:69], v[98:101], v[16:31]
	v_mfma_f32_32x32x16_bf16 v[32:47], v[66:69], v[108:111], v[32:47]
	v_mfma_f32_32x32x16_bf16 v[0:15], v[70:73], v[84:87], v[0:15]
	v_mfma_f32_32x32x16_bf16 v[48:63], v[70:73], v[92:95], v[48:63]
	v_mfma_f32_32x32x16_bf16 v[16:31], v[70:73], v[102:105], v[16:31]
	v_mfma_f32_32x32x16_bf16 v[32:47], v[70:73], v[112:115], v[32:47]
	s_setprio 0
	v_mov_b32_e32 v66, v64
	v_mbcnt_lo_u32_b32 v65, -1, 0
	v_mbcnt_hi_u32_b32 v65, -1, v65
	s_nop 1
	v_permlane32_swap_b32_e32 v64, v66
	v_and_b32_e32 v114, 63, v65
	v_and_b32_e32 v170, 31, v65
	v_cmp_gt_u32_e32 vcc, 32, v114
	s_and_saveexec_b64 s[2:3], vcc
	v_lshl_add_u32 v67, v170, 2, s0
	v_add_f32_e32 v64, v64, v66
	ds_write_b32 v67, v64
	s_or_b64 exec, exec, s[2:3]
	v_lshrrev_b32_e32 v64, 3, v65
	v_and_b32_e32 v69, 4, v64
	v_or_b32_e32 v102, s46, v69
	v_lshlrev_b32_e32 v130, 2, v170
	v_ashrrev_i32_e32 v103, 31, v102
	v_or_b32_e32 v66, 1, v102
	v_lshl_add_u64 v[92:93], s[54:55], 0, v[130:131]
	v_lshlrev_b64 v[156:157], 11, v[102:103]
	v_ashrrev_i32_e32 v67, 31, v66
	s_waitcnt lgkmcnt(0)
	v_lshl_add_u64 v[64:65], v[92:93], 0, v[156:157]
	v_lshlrev_b64 v[148:149], 11, v[66:67]
	v_lshl_add_u64 v[66:67], v[92:93], 0, v[148:149]
	global_load_dword v110, v[64:65], off
	global_load_dword v111, v[64:65], off offset:128
	global_load_dword v109, v[64:65], off offset:256
	global_load_dword v108, v[64:65], off offset:384
	global_load_dword v106, v[66:67], off
	global_load_dword v107, v[66:67], off offset:128
	global_load_dword v105, v[66:67], off offset:256
	global_load_dword v104, v[66:67], off offset:384
	v_or_b32_e32 v64, 2, v102
	v_or_b32_e32 v66, 3, v102
	v_ashrrev_i32_e32 v65, 31, v64
	v_ashrrev_i32_e32 v67, 31, v66
	v_lshlrev_b64 v[146:147], 11, v[64:65]
	v_lshlrev_b64 v[136:137], 11, v[66:67]
	v_lshl_add_u64 v[64:65], v[92:93], 0, v[146:147]
	v_lshl_add_u64 v[66:67], v[92:93], 0, v[136:137]
	global_load_dword v158, v[64:65], off
	global_load_dword v159, v[64:65], off offset:128
	global_load_dword v155, v[64:65], off offset:256
	global_load_dword v154, v[64:65], off offset:384
	global_load_dword v152, v[66:67], off
	global_load_dword v153, v[66:67], off offset:128
	global_load_dword v151, v[66:67], off offset:256
	global_load_dword v150, v[66:67], off offset:384
	v_or_b32_e32 v64, 8, v102
	v_or_b32_e32 v66, 9, v102
	v_ashrrev_i32_e32 v65, 31, v64
	v_ashrrev_i32_e32 v67, 31, v66
	v_lshlrev_b64 v[134:135], 11, v[64:65]
	v_lshlrev_b64 v[120:121], 11, v[66:67]
	v_lshl_add_u64 v[64:65], v[92:93], 0, v[134:135]
	v_lshl_add_u64 v[66:67], v[92:93], 0, v[120:121]
	global_load_dword v144, v[64:65], off
	global_load_dword v145, v[64:65], off offset:128
	global_load_dword v143, v[64:65], off offset:256
	global_load_dword v142, v[64:65], off offset:384
	global_load_dword v140, v[66:67], off
	global_load_dword v141, v[66:67], off offset:128
	global_load_dword v139, v[66:67], off offset:256
	global_load_dword v138, v[66:67], off offset:384
	v_or_b32_e32 v64, 10, v102
	v_or_b32_e32 v66, 11, v102
	v_ashrrev_i32_e32 v65, 31, v64
	v_ashrrev_i32_e32 v67, 31, v66
	v_lshlrev_b64 v[118:119], 11, v[64:65]
	v_lshlrev_b64 v[90:91], 11, v[66:67]
	v_lshl_add_u64 v[64:65], v[92:93], 0, v[118:119]
	v_lshl_add_u64 v[66:67], v[92:93], 0, v[90:91]
	global_load_dword v132, v[64:65], off
	global_load_dword v133, v[64:65], off offset:128
	global_load_dword v127, v[64:65], off offset:256
	global_load_dword v126, v[64:65], off offset:384
	global_load_dword v124, v[66:67], off
	global_load_dword v125, v[66:67], off offset:128
	global_load_dword v123, v[66:67], off offset:256
	global_load_dword v122, v[66:67], off offset:384
	v_or_b32_e32 v64, 16, v102
	v_or_b32_e32 v66, 17, v102
	v_ashrrev_i32_e32 v65, 31, v64
	v_ashrrev_i32_e32 v67, 31, v66
	v_lshlrev_b64 v[86:87], 11, v[64:65]
	v_lshlrev_b64 v[78:79], 11, v[66:67]
	v_lshl_add_u64 v[64:65], v[92:93], 0, v[86:87]
	v_lshl_add_u64 v[66:67], v[92:93], 0, v[78:79]
	global_load_dword v100, v[64:65], off
	global_load_dword v101, v[64:65], off offset:128
	global_load_dword v99, v[64:65], off offset:256
	global_load_dword v98, v[64:65], off offset:384
	global_load_dword v96, v[66:67], off
	global_load_dword v97, v[66:67], off offset:128
	global_load_dword v95, v[66:67], off offset:256
	global_load_dword v94, v[66:67], off offset:384
	v_or_b32_e32 v64, 18, v102
	v_or_b32_e32 v66, 19, v102
	v_ashrrev_i32_e32 v65, 31, v64
	v_ashrrev_i32_e32 v67, 31, v66
	v_lshlrev_b64 v[76:77], 11, v[64:65]
	v_lshlrev_b64 v[72:73], 11, v[66:67]
	v_lshl_add_u64 v[64:65], v[92:93], 0, v[76:77]
	v_lshl_add_u64 v[66:67], v[92:93], 0, v[72:73]
	v_lshl_add_u32 v169, v69, 2, s0
	global_load_dword v88, v[64:65], off
	global_load_dword v89, v[64:65], off offset:128
	global_load_dword v85, v[64:65], off offset:256
	global_load_dword v84, v[64:65], off offset:384
	global_load_dword v82, v[66:67], off
	global_load_dword v83, v[66:67], off offset:128
	global_load_dword v81, v[66:67], off offset:256
	global_load_dword v80, v[66:67], off offset:384
	ds_read_b128 v[64:67], v169
	v_or_b32_e32 v68, 24, v102
	v_ashrrev_i32_e32 v69, 31, v68
	v_lshlrev_b64 v[74:75], 11, v[68:69]
	ds_read_b128 v[68:71], v169 offset:32
	s_waitcnt lgkmcnt(0)
; DI unsigned short f2bf(float x) { unsigned u = __float_as_uint(x); u += 0x7fffu + ((u >> 16) & 1u); return (unsigned short)(u >> 16); }
; DI float shx(float v, int mask, int lane) { return __int_as_float(__builtin_amdgcn_ds_bpermute((lane ^ mask) << 2, __float_as_int(v))); }
; DI int crow(int r, int hi) { return (r & 3) + 8 * (r >> 2) + 4 * hi; }
; template <int DQK, int MODE, int LDQ, int LDK, int LDV> ...
;     ...
;     for (int r = 0; r < 16; ++r) { const int orow = wid * 32 + crow(r, hi); const float rl = __builtin_amdgcn_rcpf(li_l[crow(r, hi)]);
;         if constexpr (MODE == 0) {
; #pragma unroll
;             for (int d0 = 0; d0 < 4; ++d0) AOb[(size_t)orow * 1024 + d0 * 32 + r32] = f2bf(o[d0][r] * rl);
;         } else if constexpr (MODE == 1) {
; #pragma unroll
;             for (int d0 = 0; d0 < 4; ++d0) S0[(size_t)orow * 512 + d0 * 32 + r32] = o[d0][r] * rl;
;         } else {
;             float v[4]; float ss = 0.f;
; #pragma unroll
;             for (int d0 = 0; d0 < 4; ++d0) { v[d0] = s0v[r][d0] - lam * (o[d0][r] * rl); ss += v[d0] * v[d0]; }
; #pragma unroll
;             for (int mk = 1; mk <= 16; mk <<= 1) ss += shx(ss, mk, lane2);
;             const float rs = rsqrtf(ss * (1.f / 128.f) + EPS) * 0.8f;
; #pragma unroll
;             for (int d0 = 0; d0 < 4; ++d0) AOb[(size_t)orow * 1024 + d0 * 32 + r32] = f2bf(v[d0] * rs * gout[d0 * 32 + r32]);
	v_rcp_f32_e32 v64, v64
	v_mov_b32_e32 v162, v0
	v_mov_b32_e32 v163, v48
	v_rcp_f32_e32 v0, v65
	v_pk_mul_f32 v[162:163], v[162:163], v[64:65] op_sel_hi:[1,0]
	v_mov_b32_e32 v48, v1
	v_lshlrev_b32_e32 v166, 2, v114
	v_pk_mul_f32 v[48:49], v[48:49], v[0:1] op_sel_hi:[1,0]
	v_xor_b32_e32 v164, 4, v166
	v_xor_b32_e32 v165, 8, v166
	v_xor_b32_e32 v168, 16, v166
	v_xor_b32_e32 v167, 32, v166
	v_or_b32_e32 v116, 25, v102
	v_ashrrev_i32_e32 v117, 31, v116
	v_xor_b32_e32 v166, 64, v166
	v_lshl_add_u64 v[112:113], v[92:93], 0, v[74:75]
	s_add_u32 s1, s60, s58
	s_mov_b32 s0, 0x358637bd
	s_addc_u32 s3, s61, s59
	s_lshl_b32 s2, s87, 1
	s_add_u32 s2, s1, s2
	s_addc_u32 s3, s3, 0
	s_waitcnt vmcnt(0)
	v_pk_fma_f32 v[172:173], v[128:129], v[162:163], v[110:111] neg_lo:[1,0,0] neg_hi:[1,0,0]
	v_mov_b32_e32 v162, v32
	v_mov_b32_e32 v163, v16
	v_pk_mul_f32 v[162:163], v[162:163], v[64:65] op_sel_hi:[1,0]
	v_mov_b32_e32 v16, v33
	v_pk_fma_f32 v[174:175], v[128:129], v[162:163], v[108:109] neg_lo:[1,0,0] neg_hi:[1,0,0]
	global_load_dword v163, v130, s[50:51]
	global_load_dword v162, v130, s[50:51] offset:128
	global_load_dword v161, v130, s[50:51] offset:256
	s_nop 0
	global_load_dword v130, v130, s[50:51] offset:384
	v_pk_fma_f32 v[176:177], v[128:129], v[48:49], v[106:107] neg_lo:[1,0,0] neg_hi:[1,0,0]
	v_pk_mul_f32 v[0:1], v[16:17], v[0:1] op_sel_hi:[1,0]
	v_pk_mul_f32 v[110:111], v[172:173], v[172:173]
	v_pk_mul_f32 v[48:49], v[176:177], v[176:177]
	v_pk_fma_f32 v[0:1], v[128:129], v[0:1], v[104:105] neg_lo:[1,0,0] neg_hi:[1,0,0]
	v_pk_mul_f32 v[108:109], v[174:175], v[174:175]
	v_pk_mul_f32 v[16:17], v[0:1], v[0:1]
	v_mov_b32_e32 v32, v48
	v_mov_b32_e32 v33, v110
	v_mov_b32_e32 v110, v49
	v_pk_add_f32 v[32:33], v[32:33], v[110:111]
	v_mov_b32_e32 v48, v17
	v_mov_b32_e32 v49, v109
	v_pk_add_f32 v[32:33], v[48:49], v[32:33]
	v_mov_b32_e32 v17, v108
	v_pk_add_f32 v[16:17], v[16:17], v[32:33]
	ds_bpermute_b32 v33, v164, v17
	ds_bpermute_b32 v32, v164, v16
	v_lshlrev_b64 v[64:65], 11, v[116:117]
	v_lshl_add_u64 v[48:49], v[92:93], 0, v[64:65]
	global_load_dword v116, v[112:113], off
	global_load_dword v117, v[112:113], off offset:128
	global_load_dword v115, v[112:113], off offset:256
	global_load_dword v114, v[112:113], off offset:384
	s_nop 0
	global_load_dword v112, v[48:49], off
	global_load_dword v113, v[48:49], off offset:128
	global_load_dword v111, v[48:49], off offset:256
	global_load_dword v110, v[48:49], off offset:384
	v_or_b32_e32 v48, 26, v102
	s_waitcnt lgkmcnt(0)
	v_pk_add_f32 v[16:17], v[16:17], v[32:33]
	ds_bpermute_b32 v33, v165, v17
	ds_bpermute_b32 v32, v165, v16
	v_or_b32_e32 v102, 27, v102
	v_ashrrev_i32_e32 v49, 31, v48
	v_ashrrev_i32_e32 v103, 31, v102
	v_lshlrev_b64 v[48:49], 11, v[48:49]
	s_waitcnt lgkmcnt(0)
	v_pk_add_f32 v[16:17], v[16:17], v[32:33]
	ds_bpermute_b32 v33, v168, v17
	ds_bpermute_b32 v32, v168, v16
	v_lshl_add_u64 v[104:105], v[92:93], 0, v[48:49]
	v_lshlrev_b32_e32 v170, 1, v170
	v_mov_b32_e32 v171, v131
	v_rcp_f32_e32 v66, v66
	s_waitcnt lgkmcnt(0)
	v_pk_add_f32 v[32:33], v[16:17], v[32:33]
	ds_bpermute_b32 v107, v167, v33
	ds_bpermute_b32 v106, v167, v32
	v_lshlrev_b64 v[16:17], 11, v[102:103]
	v_lshl_add_u64 v[92:93], v[92:93], 0, v[16:17]
	s_waitcnt lgkmcnt(0)
	v_pk_add_f32 v[32:33], v[32:33], v[106:107]
	ds_bpermute_b32 v179, v166, v33
	ds_bpermute_b32 v178, v166, v32
	global_load_dword v108, v[104:105], off
	global_load_dword v109, v[104:105], off offset:128
	global_load_dword v107, v[104:105], off offset:256
	global_load_dword v106, v[104:105], off offset:384
	s_nop 0
	global_load_dword v104, v[92:93], off
	global_load_dword v105, v[92:93], off offset:128
	global_load_dword v103, v[92:93], off offset:256
	global_load_dword v102, v[92:93], off offset:384
	v_mov_b64_e32 v[92:93], s[0:1]
	s_waitcnt lgkmcnt(0)
	v_pk_add_f32 v[32:33], v[32:33], v[178:179]
	s_nop 0
	v_pk_fma_f32 v[178:179], v[32:33], s[24:25], v[92:93] op_sel_hi:[1,0,0]
	s_nop 0
	v_mul_f32_e32 v32, 0x4b800000, v179
	v_cmp_gt_f32_e32 vcc, s67, v179
	s_nop 1
	v_cndmask_b32_e32 v32, v179, v32, vcc
	v_rsq_f32_e32 v179, v32
	v_lshl_add_u64 v[32:33], s[2:3], 0, v[170:171]
	v_lshl_add_u64 v[156:157], v[32:33], 0, v[156:157]
	v_lshl_add_u64 v[148:149], v[32:33], 0, v[148:149]
	v_mul_f32_e32 v170, 0x45800000, v179
	v_cndmask_b32_e32 v170, v179, v170, vcc
	v_mul_f32_e32 v170, 0x3f4ccccd, v170
	v_mul_f32_e32 v171, v172, v170
	v_cmp_gt_f32_e32 vcc, s67, v178
	s_mov_b64 s[2:3], 0
	s_waitcnt vmcnt(19)
	v_mul_f32_e32 v171, v163, v171
	v_bfe_u32 v172, v171, 16, 1
	v_add3_u32 v171, v171, v172, s68
	global_store_short_d16_hi v[156:157], v171, off offset:1024
	v_mul_f32_e32 v171, v173, v170
	s_waitcnt vmcnt(19)
	v_mul_f32_e32 v171, v162, v171
	v_bfe_u32 v172, v171, 16, 1
	v_add3_u32 v171, v171, v172, s68
	global_store_short_d16_hi v[156:157], v171, off offset:1088
	v_mul_f32_e32 v171, v175, v170
	s_waitcnt vmcnt(19)
	v_mul_f32_e32 v171, v161, v171
	v_bfe_u32 v172, v171, 16, 1
	v_add3_u32 v171, v171, v172, s68
	global_store_short_d16_hi v[156:157], v171, off offset:1152
	v_mul_f32_e32 v171, 0x4b800000, v178
	v_cndmask_b32_e32 v171, v178, v171, vcc
	v_mul_f32_e32 v170, v174, v170
	v_rsq_f32_e32 v171, v171
	s_waitcnt vmcnt(19)
; DI unsigned short f2bf(float x) { unsigned u = __float_as_uint(x); u += 0x7fffu + ((u >> 16) & 1u); return (unsigned short)(u >> 16); }
; DI float shx(float v, int mask, int lane) { return __int_as_float(__builtin_amdgcn_ds_bpermute((lane ^ mask) << 2, __float_as_int(v))); }
; DI int crow(int r, int hi) { return (r & 3) + 8 * (r >> 2) + 4 * hi; }
; template <int DQK, int MODE, int LDQ, int LDK, int LDV> ...
;     ...
;     for (int r = 0; r < 16; ++r) { const int orow = wid * 32 + crow(r, hi); const float rl = __builtin_amdgcn_rcpf(li_l[crow(r, hi)]);
;         if constexpr (MODE == 0) {
; #pragma unroll
;             for (int d0 = 0; d0 < 4; ++d0) AOb[(size_t)orow * 1024 + d0 * 32 + r32] = f2bf(o[d0][r] * rl);
;         } else if constexpr (MODE == 1) {
; #pragma unroll
;             for (int d0 = 0; d0 < 4; ++d0) S0[(size_t)orow * 512 + d0 * 32 + r32] = o[d0][r] * rl;
;         } else {
;             float v[4]; float ss = 0.f;
; #pragma unroll
;             for (int d0 = 0; d0 < 4; ++d0) { v[d0] = s0v[r][d0] - lam * (o[d0][r] * rl); ss += v[d0] * v[d0]; }
; #pragma unroll
;             for (int mk = 1; mk <= 16; mk <<= 1) ss += shx(ss, mk, lane2);
;             const float rs = rsqrtf(ss * (1.f / 128.f) + EPS) * 0.8f;
; #pragma unroll
;             for (int d0 = 0; d0 < 4; ++d0) AOb[(size_t)orow * 1024 + d0 * 32 + r32] = f2bf(v[d0] * rs * gout[d0 * 32 + r32]);
	v_mul_f32_e32 v170, v130, v170
	v_bfe_u32 v172, v170, 16, 1
	v_add3_u32 v170, v170, v172, s68
	global_store_short_d16_hi v[156:157], v170, off offset:1216
	v_mul_f32_e32 v156, 0x45800000, v171
	v_cndmask_b32_e32 v172, v171, v156, vcc
	v_mov_b32_e32 v156, v2
	v_rcp_f32_e32 v2, v67
	v_mov_b32_e32 v157, v50
	v_mov_b32_e32 v50, v3
	v_pk_mul_f32 v[156:157], v[156:157], v[66:67] op_sel_hi:[1,0]
	v_mov_b32_e32 v170, v34
	v_mov_b32_e32 v171, v18
	v_pk_mul_f32 v[50:51], v[50:51], v[2:3] op_sel_hi:[1,0]
	v_mov_b32_e32 v18, v35
	v_pk_fma_f32 v[156:157], v[128:129], v[156:157], v[158:159] neg_lo:[1,0,0] neg_hi:[1,0,0]
	v_pk_mul_f32 v[170:171], v[170:171], v[66:67] op_sel_hi:[1,0]
	v_pk_fma_f32 v[50:51], v[128:129], v[50:51], v[152:153] neg_lo:[1,0,0] neg_hi:[1,0,0]
	v_pk_mul_f32 v[2:3], v[18:19], v[2:3] op_sel_hi:[1,0]
	v_pk_mul_f32 v[158:159], v[156:157], v[156:157]
	v_pk_fma_f32 v[66:67], v[128:129], v[170:171], v[154:155] neg_lo:[1,0,0] neg_hi:[1,0,0]
	v_pk_mul_f32 v[152:153], v[50:51], v[50:51]
	v_pk_fma_f32 v[2:3], v[128:129], v[2:3], v[150:151] neg_lo:[1,0,0] neg_hi:[1,0,0]
	v_pk_mul_f32 v[154:155], v[66:67], v[66:67]
	v_pk_mul_f32 v[18:19], v[2:3], v[2:3]
	v_mov_b32_e32 v34, v152
	v_mov_b32_e32 v35, v158
	v_mov_b32_e32 v158, v153
	v_pk_add_f32 v[34:35], v[34:35], v[158:159]
	v_mov_b32_e32 v150, v19
	v_mov_b32_e32 v151, v155
	v_pk_add_f32 v[34:35], v[150:151], v[34:35]
	v_mov_b32_e32 v19, v154
	v_pk_add_f32 v[18:19], v[18:19], v[34:35]
	ds_bpermute_b32 v35, v164, v19
	ds_bpermute_b32 v34, v164, v18
	v_mul_f32_e32 v150, 0x3f4ccccd, v172
	v_mul_f32_e32 v151, v176, v150
	v_mul_f32_e32 v151, v163, v151
	v_bfe_u32 v152, v151, 16, 1
	s_waitcnt lgkmcnt(0)
	v_pk_add_f32 v[18:19], v[18:19], v[34:35]
	ds_bpermute_b32 v35, v165, v19
	ds_bpermute_b32 v34, v165, v18
	v_add3_u32 v151, v151, v152, s68
	global_store_short_d16_hi v[148:149], v151, off offset:1024
	v_mul_f32_e32 v151, v177, v150
	v_mul_f32_e32 v151, v162, v151
	s_waitcnt lgkmcnt(0)
	v_pk_add_f32 v[18:19], v[18:19], v[34:35]
	ds_bpermute_b32 v35, v168, v19
	ds_bpermute_b32 v34, v168, v18
	v_bfe_u32 v152, v151, 16, 1
	v_mul_f32_e32 v1, v1, v150
	v_add3_u32 v151, v151, v152, s68
	v_mul_f32_e32 v1, v161, v1
	s_waitcnt lgkmcnt(0)
	v_pk_add_f32 v[18:19], v[18:19], v[34:35]
	ds_bpermute_b32 v35, v167, v19
	ds_bpermute_b32 v34, v167, v18
	global_store_short_d16_hi v[148:149], v151, off offset:1088
	v_bfe_u32 v151, v1, 16, 1
	v_add3_u32 v1, v1, v151, s68
	v_mul_f32_e32 v0, v0, v150
	s_waitcnt lgkmcnt(0)
	v_pk_add_f32 v[18:19], v[18:19], v[34:35]
	ds_bpermute_b32 v35, v166, v19
	ds_bpermute_b32 v34, v166, v18
	global_store_short_d16_hi v[148:149], v1, off offset:1152
	v_mul_f32_e32 v150, v130, v0
	v_bfe_u32 v151, v150, 16, 1
	s_waitcnt lgkmcnt(0)
	v_pk_add_f32 v[0:1], v[18:19], v[34:35]
	s_nop 0
	v_pk_fma_f32 v[0:1], v[0:1], s[24:25], v[92:93] op_sel_hi:[1,0,0]
	s_nop 0
	v_mul_f32_e32 v18, 0x4b800000, v1
	v_cmp_gt_f32_e32 vcc, s67, v1
	s_nop 1
	v_cndmask_b32_e32 v1, v1, v18, vcc
	v_rsq_f32_e32 v1, v1
	v_add3_u32 v18, v150, v151, s68
	global_store_short_d16_hi v[148:149], v18, off offset:1216
	v_lshl_add_u64 v[18:19], v[32:33], 0, v[146:147]
	v_mul_f32_e32 v34, 0x45800000, v1
	v_cndmask_b32_e32 v1, v1, v34, vcc
	v_mul_f32_e32 v1, 0x3f4ccccd, v1
	v_mul_f32_e32 v34, v156, v1
	v_mul_f32_e32 v34, v163, v34
	v_bfe_u32 v35, v34, 16, 1
	v_add3_u32 v34, v34, v35, s68
	global_store_short_d16_hi v[18:19], v34, off offset:1024
	v_mul_f32_e32 v34, v157, v1
	v_mul_f32_e32 v34, v162, v34
	v_bfe_u32 v35, v34, 16, 1
	v_add3_u32 v34, v34, v35, s68
	global_store_short_d16_hi v[18:19], v34, off offset:1088
	v_mul_f32_e32 v34, v67, v1
	v_mul_f32_e32 v34, v161, v34
	v_bfe_u32 v35, v34, 16, 1
	v_add3_u32 v34, v34, v35, s68
	global_store_short_d16_hi v[18:19], v34, off offset:1152
	v_mul_f32_e32 v1, v66, v1
	v_mul_f32_e32 v34, 0x4b800000, v0
	v_cmp_gt_f32_e32 vcc, s67, v0
	v_mul_f32_e32 v1, v130, v1
	v_mov_b32_e32 v66, v36
	v_cndmask_b32_e32 v0, v0, v34, vcc
	v_rsq_f32_e32 v34, v0
	v_bfe_u32 v0, v1, 16, 1
	v_add3_u32 v0, v1, v0, s68
	global_store_short_d16_hi v[18:19], v0, off offset:1216
	v_rcp_f32_e32 v0, v68
	v_mov_b32_e32 v18, v4
	v_rcp_f32_e32 v4, v69
	v_mul_f32_e32 v1, 0x45800000, v34
	v_mov_b32_e32 v19, v52
	v_mov_b32_e32 v52, v5
	v_pk_mul_f32 v[18:19], v[18:19], v[0:1] op_sel_hi:[1,0]
	v_mov_b32_e32 v67, v20
	v_pk_mul_f32 v[52:53], v[52:53], v[4:5] op_sel_hi:[1,0]
	v_mov_b32_e32 v20, v37
	v_cndmask_b32_e32 v146, v34, v1, vcc
	v_pk_fma_f32 v[18:19], v[128:129], v[18:19], v[144:145] neg_lo:[1,0,0] neg_hi:[1,0,0]
	v_pk_mul_f32 v[0:1], v[66:67], v[0:1] op_sel_hi:[1,0]
	v_pk_fma_f32 v[52:53], v[128:129], v[52:53], v[140:141] neg_lo:[1,0,0] neg_hi:[1,0,0]
	v_pk_mul_f32 v[4:5], v[20:21], v[4:5] op_sel_hi:[1,0]
	v_pk_mul_f32 v[34:35], v[18:19], v[18:19]
	v_pk_fma_f32 v[0:1], v[128:129], v[0:1], v[142:143] neg_lo:[1,0,0] neg_hi:[1,0,0]
	v_pk_mul_f32 v[68:69], v[52:53], v[52:53]
	v_pk_fma_f32 v[4:5], v[128:129], v[4:5], v[138:139] neg_lo:[1,0,0] neg_hi:[1,0,0]
	v_pk_mul_f32 v[66:67], v[0:1], v[0:1]
	v_pk_mul_f32 v[20:21], v[4:5], v[4:5]
	v_mov_b32_e32 v36, v68
	v_mov_b32_e32 v37, v34
	v_mov_b32_e32 v34, v69
	v_pk_add_f32 v[34:35], v[36:37], v[34:35]
	v_mov_b32_e32 v36, v21
	v_mov_b32_e32 v37, v67
	v_pk_add_f32 v[34:35], v[36:37], v[34:35]
	v_mov_b32_e32 v21, v66
	v_pk_add_f32 v[20:21], v[20:21], v[34:35]
	ds_bpermute_b32 v35, v164, v21
	ds_bpermute_b32 v34, v164, v20
	v_mul_f32_e32 v66, 0x3f4ccccd, v146
	v_mul_f32_e32 v50, v50, v66
	v_mul_f32_e32 v50, v163, v50
	v_bfe_u32 v67, v50, 16, 1
	s_waitcnt lgkmcnt(0)
; DI unsigned short f2bf(float x) { unsigned u = __float_as_uint(x); u += 0x7fffu + ((u >> 16) & 1u); return (unsigned short)(u >> 16); }
; DI float shx(float v, int mask, int lane) { return __int_as_float(__builtin_amdgcn_ds_bpermute((lane ^ mask) << 2, __float_as_int(v))); }
; DI int crow(int r, int hi) { return (r & 3) + 8 * (r >> 2) + 4 * hi; }
; template <int DQK, int MODE, int LDQ, int LDK, int LDV> ...
;     ...
;     for (int r = 0; r < 16; ++r) { const int orow = wid * 32 + crow(r, hi); const float rl = __builtin_amdgcn_rcpf(li_l[crow(r, hi)]);
;         if constexpr (MODE == 0) {
; #pragma unroll
;             for (int d0 = 0; d0 < 4; ++d0) AOb[(size_t)orow * 1024 + d0 * 32 + r32] = f2bf(o[d0][r] * rl);
;         } else if constexpr (MODE == 1) {
; #pragma unroll
;             for (int d0 = 0; d0 < 4; ++d0) S0[(size_t)orow * 512 + d0 * 32 + r32] = o[d0][r] * rl;
;         } else {
;             float v[4]; float ss = 0.f;
; #pragma unroll
;             for (int d0 = 0; d0 < 4; ++d0) { v[d0] = s0v[r][d0] - lam * (o[d0][r] * rl); ss += v[d0] * v[d0]; }
; #pragma unroll
;             for (int mk = 1; mk <= 16; mk <<= 1) ss += shx(ss, mk, lane2);
;             const float rs = rsqrtf(ss * (1.f / 128.f) + EPS) * 0.8f;
; #pragma unroll
;             for (int d0 = 0; d0 < 4; ++d0) AOb[(size_t)orow * 1024 + d0 * 32 + r32] = f2bf(v[d0] * rs * gout[d0 * 32 + r32]);
	v_pk_add_f32 v[20:21], v[20:21], v[34:35]
	ds_bpermute_b32 v35, v165, v21
	ds_bpermute_b32 v34, v165, v20
	v_lshl_add_u64 v[36:37], v[32:33], 0, v[136:137]
	v_add3_u32 v50, v50, v67, s68
	global_store_short_d16_hi v[36:37], v50, off offset:1024
	v_mul_f32_e32 v50, v51, v66
	s_waitcnt lgkmcnt(0)
	v_pk_add_f32 v[20:21], v[20:21], v[34:35]
	ds_bpermute_b32 v35, v168, v21
	ds_bpermute_b32 v34, v168, v20
	v_mul_f32_e32 v50, v162, v50
	v_bfe_u32 v51, v50, 16, 1
	v_mul_f32_e32 v3, v3, v66
	v_add3_u32 v50, v50, v51, s68
	s_waitcnt lgkmcnt(0)
	v_pk_add_f32 v[20:21], v[20:21], v[34:35]
	ds_bpermute_b32 v35, v167, v21
	ds_bpermute_b32 v34, v167, v20
	v_mul_f32_e32 v3, v161, v3
	global_store_short_d16_hi v[36:37], v50, off offset:1088
	v_bfe_u32 v50, v3, 16, 1
	v_add3_u32 v3, v3, v50, s68
	s_waitcnt lgkmcnt(0)
	v_pk_add_f32 v[20:21], v[20:21], v[34:35]
	ds_bpermute_b32 v35, v166, v21
	ds_bpermute_b32 v34, v166, v20
	v_mul_f32_e32 v2, v2, v66
	global_store_short_d16_hi v[36:37], v3, off offset:1152
	v_mul_f32_e32 v50, v130, v2
	v_bfe_u32 v51, v50, 16, 1
	s_waitcnt lgkmcnt(0)
	v_pk_add_f32 v[2:3], v[20:21], v[34:35]
	s_nop 0
	v_pk_fma_f32 v[2:3], v[2:3], s[24:25], v[92:93] op_sel_hi:[1,0,0]
	s_nop 0
	v_mul_f32_e32 v20, 0x4b800000, v3
	v_cmp_gt_f32_e32 vcc, s67, v3
	s_nop 1
	v_cndmask_b32_e32 v3, v3, v20, vcc
	v_rsq_f32_e32 v3, v3
	v_add3_u32 v20, v50, v51, s68
	global_store_short_d16_hi v[36:37], v20, off offset:1216
	v_lshl_add_u64 v[20:21], v[32:33], 0, v[134:135]
	v_mul_f32_e32 v34, 0x45800000, v3
	v_cndmask_b32_e32 v3, v3, v34, vcc
	v_mul_f32_e32 v3, 0x3f4ccccd, v3
	v_mul_f32_e32 v18, v18, v3
	v_mul_f32_e32 v18, v163, v18
	v_bfe_u32 v34, v18, 16, 1
	v_add3_u32 v18, v18, v34, s68
	global_store_short_d16_hi v[20:21], v18, off offset:1024
	v_mul_f32_e32 v18, v19, v3
	v_mul_f32_e32 v18, v162, v18
	v_bfe_u32 v19, v18, 16, 1
	v_mul_f32_e32 v1, v1, v3
	v_add3_u32 v18, v18, v19, s68
	v_mul_f32_e32 v1, v161, v1
	global_store_short_d16_hi v[20:21], v18, off offset:1088
	v_bfe_u32 v18, v1, 16, 1
	v_add3_u32 v1, v1, v18, s68
	global_store_short_d16_hi v[20:21], v1, off offset:1152
	v_mul_f32_e32 v1, 0x4b800000, v2
	v_cmp_gt_f32_e32 vcc, s67, v2
	v_mul_f32_e32 v0, v0, v3
	v_mul_f32_e32 v0, v130, v0
	v_cndmask_b32_e32 v1, v2, v1, vcc
	v_rsq_f32_e32 v1, v1
	v_bfe_u32 v2, v0, 16, 1
	v_add3_u32 v0, v0, v2, s68
	global_store_short_d16_hi v[20:21], v0, off offset:1216
	v_mul_f32_e32 v2, 0x45800000, v1
	v_rcp_f32_e32 v0, v70
	v_cndmask_b32_e32 v66, v1, v2, vcc
	v_mov_b32_e32 v2, v6
	v_rcp_f32_e32 v6, v71
	v_mov_b32_e32 v3, v54
	v_mov_b32_e32 v18, v38
	v_mov_b32_e32 v19, v22
	v_mov_b32_e32 v54, v7
	v_pk_mul_f32 v[2:3], v[2:3], v[0:1] op_sel_hi:[1,0]
	v_pk_mul_f32 v[0:1], v[18:19], v[0:1] op_sel_hi:[1,0]
	v_pk_mul_f32 v[18:19], v[54:55], v[6:7] op_sel_hi:[1,0]
	v_mov_b32_e32 v22, v39
	v_pk_fma_f32 v[2:3], v[128:129], v[2:3], v[132:133] neg_lo:[1,0,0] neg_hi:[1,0,0]
	v_pk_fma_f32 v[20:21], v[128:129], v[18:19], v[124:125] neg_lo:[1,0,0] neg_hi:[1,0,0]
	v_pk_mul_f32 v[6:7], v[22:23], v[6:7] op_sel_hi:[1,0]
	v_pk_mul_f32 v[34:35], v[2:3], v[2:3]
	v_pk_fma_f32 v[0:1], v[128:129], v[0:1], v[126:127] neg_lo:[1,0,0] neg_hi:[1,0,0]
	v_pk_mul_f32 v[50:51], v[20:21], v[20:21]
	v_pk_fma_f32 v[18:19], v[128:129], v[6:7], v[122:123] neg_lo:[1,0,0] neg_hi:[1,0,0]
	v_pk_mul_f32 v[36:37], v[0:1], v[0:1]
	v_pk_mul_f32 v[6:7], v[18:19], v[18:19]
	v_mov_b32_e32 v22, v50
	v_mov_b32_e32 v23, v34
	v_mov_b32_e32 v34, v51
	v_pk_add_f32 v[22:23], v[22:23], v[34:35]
	v_mov_b32_e32 v34, v7
	v_mov_b32_e32 v35, v37
	v_pk_add_f32 v[22:23], v[34:35], v[22:23]
	v_mov_b32_e32 v7, v36
	v_pk_add_f32 v[6:7], v[6:7], v[22:23]
	ds_bpermute_b32 v23, v164, v7
	ds_bpermute_b32 v22, v164, v6
	v_mul_f32_e32 v36, 0x3f4ccccd, v66
	v_mul_f32_e32 v37, v52, v36
	v_mul_f32_e32 v37, v163, v37
	v_bfe_u32 v38, v37, 16, 1
	s_waitcnt lgkmcnt(0)
	v_pk_add_f32 v[6:7], v[6:7], v[22:23]
	ds_bpermute_b32 v23, v165, v7
	ds_bpermute_b32 v22, v165, v6
	v_lshl_add_u64 v[34:35], v[32:33], 0, v[120:121]
	v_add3_u32 v37, v37, v38, s68
	global_store_short_d16_hi v[34:35], v37, off offset:1024
	v_mul_f32_e32 v37, v53, v36
	s_waitcnt lgkmcnt(0)
	v_pk_add_f32 v[6:7], v[6:7], v[22:23]
	ds_bpermute_b32 v23, v168, v7
	ds_bpermute_b32 v22, v168, v6
	v_mul_f32_e32 v37, v162, v37
	v_bfe_u32 v38, v37, 16, 1
	v_mul_f32_e32 v5, v5, v36
	v_add3_u32 v37, v37, v38, s68
	s_waitcnt lgkmcnt(0)
	v_pk_add_f32 v[6:7], v[6:7], v[22:23]
	ds_bpermute_b32 v23, v167, v7
	ds_bpermute_b32 v22, v167, v6
	v_mul_f32_e32 v5, v161, v5
	global_store_short_d16_hi v[34:35], v37, off offset:1088
	v_bfe_u32 v37, v5, 16, 1
	v_add3_u32 v5, v5, v37, s68
	s_waitcnt lgkmcnt(0)
	v_pk_add_f32 v[6:7], v[6:7], v[22:23]
	ds_bpermute_b32 v23, v166, v7
	ds_bpermute_b32 v22, v166, v6
	v_mul_f32_e32 v4, v4, v36
	global_store_short_d16_hi v[34:35], v5, off offset:1152
	v_mul_f32_e32 v36, v130, v4
	v_bfe_u32 v37, v36, 16, 1
	s_waitcnt lgkmcnt(0)
	v_pk_add_f32 v[4:5], v[6:7], v[22:23]
	v_lshl_add_u64 v[22:23], v[32:33], 0, v[118:119]
	v_pk_fma_f32 v[4:5], v[4:5], s[24:25], v[92:93] op_sel_hi:[1,0,0]
	s_nop 0
	v_mul_f32_e32 v6, 0x4b800000, v5
	v_cmp_gt_f32_e32 vcc, s67, v5
	s_nop 1
	v_cndmask_b32_e32 v5, v5, v6, vcc
	v_rsq_f32_e32 v5, v5
	v_add3_u32 v6, v36, v37, s68
	global_store_short_d16_hi v[34:35], v6, off offset:1216
	v_mov_b32_e32 v36, v40
	v_mul_f32_e32 v6, 0x45800000, v5
	v_cndmask_b32_e32 v5, v5, v6, vcc
	v_mul_f32_e32 v5, 0x3f4ccccd, v5
	v_mul_f32_e32 v2, v2, v5
	v_mul_f32_e32 v2, v163, v2
	v_bfe_u32 v6, v2, 16, 1
	v_add3_u32 v2, v2, v6, s68
	global_store_short_d16_hi v[22:23], v2, off offset:1024
	v_mul_f32_e32 v2, v3, v5
	v_mul_f32_e32 v2, v162, v2
	v_bfe_u32 v3, v2, 16, 1
	v_mul_f32_e32 v1, v1, v5
	v_add3_u32 v2, v2, v3, s68
	v_mul_f32_e32 v1, v161, v1
	global_store_short_d16_hi v[22:23], v2, off offset:1088
	v_bfe_u32 v2, v1, 16, 1
	v_add3_u32 v1, v1, v2, s68
	v_mul_f32_e32 v2, 0x4b800000, v4
	v_cmp_gt_f32_e32 vcc, s67, v4
	v_mul_f32_e32 v0, v0, v5
	v_mul_f32_e32 v0, v130, v0
	v_cndmask_b32_e32 v2, v4, v2, vcc
	ds_read_b128 v[4:7], v169 offset:64
	global_store_short_d16_hi v[22:23], v1, off offset:1152
	v_bfe_u32 v1, v0, 16, 1
	v_rsq_f32_e32 v34, v2
	v_add3_u32 v0, v0, v1, s68
	global_store_short_d16_hi v[22:23], v0, off offset:1216
	ds_read_b128 v[0:3], v169 offset:96
	s_waitcnt lgkmcnt(1)
; DI unsigned short f2bf(float x) { unsigned u = __float_as_uint(x); u += 0x7fffu + ((u >> 16) & 1u); return (unsigned short)(u >> 16); }
; DI float shx(float v, int mask, int lane) { return __int_as_float(__builtin_amdgcn_ds_bpermute((lane ^ mask) << 2, __float_as_int(v))); }
; DI int crow(int r, int hi) { return (r & 3) + 8 * (r >> 2) + 4 * hi; }
; template <int DQK, int MODE, int LDQ, int LDK, int LDV> ...
;     ...
;     for (int r = 0; r < 16; ++r) { const int orow = wid * 32 + crow(r, hi); const float rl = __builtin_amdgcn_rcpf(li_l[crow(r, hi)]);
;         if constexpr (MODE == 0) {
; #pragma unroll
;             for (int d0 = 0; d0 < 4; ++d0) AOb[(size_t)orow * 1024 + d0 * 32 + r32] = f2bf(o[d0][r] * rl);
;         } else if constexpr (MODE == 1) {
; #pragma unroll
;             for (int d0 = 0; d0 < 4; ++d0) S0[(size_t)orow * 512 + d0 * 32 + r32] = o[d0][r] * rl;
;         } else {
;             float v[4]; float ss = 0.f;
; #pragma unroll
;             for (int d0 = 0; d0 < 4; ++d0) { v[d0] = s0v[r][d0] - lam * (o[d0][r] * rl); ss += v[d0] * v[d0]; }
; #pragma unroll
;             for (int mk = 1; mk <= 16; mk <<= 1) ss += shx(ss, mk, lane2);
;             const float rs = rsqrtf(ss * (1.f / 128.f) + EPS) * 0.8f;
; #pragma unroll
;             for (int d0 = 0; d0 < 4; ++d0) AOb[(size_t)orow * 1024 + d0 * 32 + r32] = f2bf(v[d0] * rs * gout[d0 * 32 + r32]);
	v_rcp_f32_e32 v4, v4
	v_mul_f32_e32 v22, 0x45800000, v34
	v_cndmask_b32_e32 v52, v34, v22, vcc
	v_mov_b32_e32 v22, v8
	v_mov_b32_e32 v23, v56
	v_mov_b32_e32 v37, v24
	v_pk_mul_f32 v[22:23], v[22:23], v[4:5] op_sel_hi:[1,0]
	v_pk_mul_f32 v[36:37], v[36:37], v[4:5] op_sel_hi:[1,0]
	v_rcp_f32_e32 v4, v5
	v_mov_b32_e32 v56, v9
	v_mov_b32_e32 v24, v41
	v_pk_fma_f32 v[22:23], v[128:129], v[22:23], v[100:101] neg_lo:[1,0,0] neg_hi:[1,0,0]
	v_pk_mul_f32 v[8:9], v[56:57], v[4:5] op_sel_hi:[1,0]
	v_pk_mul_f32 v[4:5], v[24:25], v[4:5] op_sel_hi:[1,0]
	v_pk_fma_f32 v[8:9], v[128:129], v[8:9], v[96:97] neg_lo:[1,0,0] neg_hi:[1,0,0]
	v_pk_mul_f32 v[34:35], v[22:23], v[22:23]
	v_pk_fma_f32 v[36:37], v[128:129], v[36:37], v[98:99] neg_lo:[1,0,0] neg_hi:[1,0,0]
	v_pk_mul_f32 v[50:51], v[8:9], v[8:9]
	v_pk_fma_f32 v[4:5], v[128:129], v[4:5], v[94:95] neg_lo:[1,0,0] neg_hi:[1,0,0]
	v_pk_mul_f32 v[38:39], v[36:37], v[36:37]
	v_pk_mul_f32 v[24:25], v[4:5], v[4:5]
	v_mov_b32_e32 v40, v50
	v_mov_b32_e32 v41, v34
	v_mov_b32_e32 v34, v51
	v_pk_add_f32 v[34:35], v[40:41], v[34:35]
	v_mov_b32_e32 v40, v25
	v_mov_b32_e32 v41, v39
	v_pk_add_f32 v[34:35], v[40:41], v[34:35]
	v_mov_b32_e32 v25, v38
	v_pk_add_f32 v[24:25], v[24:25], v[34:35]
	ds_bpermute_b32 v35, v164, v25
	ds_bpermute_b32 v34, v164, v24
	v_mul_f32_e32 v40, 0x3f4ccccd, v52
	v_mul_f32_e32 v20, v20, v40
	v_mul_f32_e32 v20, v163, v20
	v_bfe_u32 v41, v20, 16, 1
	s_waitcnt lgkmcnt(0)
	v_pk_add_f32 v[24:25], v[24:25], v[34:35]
	ds_bpermute_b32 v35, v165, v25
	ds_bpermute_b32 v34, v165, v24
	v_lshl_add_u64 v[38:39], v[32:33], 0, v[90:91]
	v_add3_u32 v20, v20, v41, s68
	global_store_short_d16_hi v[38:39], v20, off offset:1024
	v_mul_f32_e32 v41, v21, v40
	s_waitcnt lgkmcnt(0)
	v_pk_add_f32 v[20:21], v[24:25], v[34:35]
	ds_bpermute_b32 v25, v168, v21
	ds_bpermute_b32 v24, v168, v20
	v_mul_f32_e32 v34, v162, v41
	v_bfe_u32 v35, v34, 16, 1
	v_mul_f32_e32 v19, v19, v40
	v_add3_u32 v34, v34, v35, s68
	s_waitcnt lgkmcnt(0)
	v_pk_add_f32 v[20:21], v[20:21], v[24:25]
	ds_bpermute_b32 v25, v167, v21
	ds_bpermute_b32 v24, v167, v20
	v_mul_f32_e32 v19, v161, v19
	global_store_short_d16_hi v[38:39], v34, off offset:1088
	v_bfe_u32 v34, v19, 16, 1
	v_add3_u32 v19, v19, v34, s68
	s_waitcnt lgkmcnt(0)
	v_pk_add_f32 v[20:21], v[20:21], v[24:25]
	ds_bpermute_b32 v25, v166, v21
	ds_bpermute_b32 v24, v166, v20
	v_mul_f32_e32 v18, v18, v40
	global_store_short_d16_hi v[38:39], v19, off offset:1152
	v_mul_f32_e32 v34, v130, v18
	v_bfe_u32 v35, v34, 16, 1
	s_waitcnt lgkmcnt(0)
	v_pk_add_f32 v[18:19], v[20:21], v[24:25]
	v_rcp_f32_e32 v6, v6
	v_pk_fma_f32 v[18:19], v[18:19], s[24:25], v[92:93] op_sel_hi:[1,0,0]
	v_rcp_f32_e32 v0, v0
	v_mul_f32_e32 v20, 0x4b800000, v19
	v_cmp_gt_f32_e32 vcc, s67, v19
	v_rcp_f32_e32 v2, v2
	s_nop 0
	v_cndmask_b32_e32 v19, v19, v20, vcc
	v_rsq_f32_e32 v19, v19
	v_add3_u32 v20, v34, v35, s68
	global_store_short_d16_hi v[38:39], v20, off offset:1216
	v_lshl_add_u64 v[20:21], v[32:33], 0, v[86:87]
	v_mul_f32_e32 v24, 0x45800000, v19
	v_cndmask_b32_e32 v19, v19, v24, vcc
	v_mul_f32_e32 v19, 0x3f4ccccd, v19
	v_mul_f32_e32 v22, v22, v19
	v_mul_f32_e32 v22, v163, v22
	v_bfe_u32 v24, v22, 16, 1
	v_add3_u32 v22, v22, v24, s68
	global_store_short_d16_hi v[20:21], v22, off offset:1024
	v_mul_f32_e32 v22, v23, v19
	v_mul_f32_e32 v22, v162, v22
	v_bfe_u32 v23, v22, 16, 1
	v_add3_u32 v22, v22, v23, s68
	global_store_short_d16_hi v[20:21], v22, off offset:1088
	v_mul_f32_e32 v22, v37, v19
	v_mul_f32_e32 v22, v161, v22
	v_bfe_u32 v23, v22, 16, 1
	v_add3_u32 v22, v22, v23, s68
	global_store_short_d16_hi v[20:21], v22, off offset:1152
	v_mul_f32_e32 v22, 0x4b800000, v18
	v_cmp_gt_f32_e32 vcc, s67, v18
	v_mul_f32_e32 v19, v36, v19
	v_mul_f32_e32 v19, v130, v19
	v_cndmask_b32_e32 v18, v18, v22, vcc
	v_rsq_f32_e32 v18, v18
	v_bfe_u32 v22, v19, 16, 1
	v_add3_u32 v19, v19, v22, s68
	global_store_short_d16_hi v[20:21], v19, off offset:1216
	v_mul_f32_e32 v19, 0x45800000, v18
	v_cndmask_b32_e32 v38, v18, v19, vcc
	v_mov_b32_e32 v18, v10
	v_mov_b32_e32 v19, v58
	v_mov_b32_e32 v22, v42
	v_mov_b32_e32 v23, v26
	v_pk_mul_f32 v[18:19], v[18:19], v[6:7] op_sel_hi:[1,0]
	v_pk_mul_f32 v[22:23], v[22:23], v[6:7] op_sel_hi:[1,0]
	v_rcp_f32_e32 v6, v7
	v_mov_b32_e32 v58, v11
	v_mov_b32_e32 v26, v43
	v_pk_fma_f32 v[18:19], v[128:129], v[18:19], v[88:89] neg_lo:[1,0,0] neg_hi:[1,0,0]
	v_pk_mul_f32 v[10:11], v[58:59], v[6:7] op_sel_hi:[1,0]
	v_pk_mul_f32 v[6:7], v[26:27], v[6:7] op_sel_hi:[1,0]
	v_pk_fma_f32 v[10:11], v[128:129], v[10:11], v[82:83] neg_lo:[1,0,0] neg_hi:[1,0,0]
	v_pk_mul_f32 v[20:21], v[18:19], v[18:19]
	v_pk_fma_f32 v[22:23], v[128:129], v[22:23], v[84:85] neg_lo:[1,0,0] neg_hi:[1,0,0]
	v_pk_mul_f32 v[34:35], v[10:11], v[10:11]
	v_pk_fma_f32 v[6:7], v[128:129], v[6:7], v[80:81] neg_lo:[1,0,0] neg_hi:[1,0,0]
	v_pk_mul_f32 v[24:25], v[22:23], v[22:23]
	v_pk_mul_f32 v[26:27], v[6:7], v[6:7]
	v_mov_b32_e32 v36, v34
	v_mov_b32_e32 v37, v20
	v_mov_b32_e32 v20, v35
	v_pk_add_f32 v[20:21], v[36:37], v[20:21]
	v_mov_b32_e32 v34, v27
	v_mov_b32_e32 v35, v25
	v_pk_add_f32 v[20:21], v[34:35], v[20:21]
	v_mov_b32_e32 v27, v24
	v_pk_add_f32 v[20:21], v[26:27], v[20:21]
	ds_bpermute_b32 v25, v164, v21
	ds_bpermute_b32 v24, v164, v20
	v_mul_f32_e32 v34, 0x3f4ccccd, v38
	v_mul_f32_e32 v8, v8, v34
	v_mul_f32_e32 v8, v163, v8
	v_bfe_u32 v35, v8, 16, 1
	s_waitcnt lgkmcnt(0)
	v_pk_add_f32 v[20:21], v[20:21], v[24:25]
	ds_bpermute_b32 v25, v165, v21
	ds_bpermute_b32 v24, v165, v20
	v_lshl_add_u64 v[26:27], v[32:33], 0, v[78:79]
	v_add3_u32 v8, v8, v35, s68
	global_store_short_d16_hi v[26:27], v8, off offset:1024
	v_mul_f32_e32 v35, v9, v34
	s_waitcnt lgkmcnt(0)
; DI unsigned short f2bf(float x) { unsigned u = __float_as_uint(x); u += 0x7fffu + ((u >> 16) & 1u); return (unsigned short)(u >> 16); }
; DI float shx(float v, int mask, int lane) { return __int_as_float(__builtin_amdgcn_ds_bpermute((lane ^ mask) << 2, __float_as_int(v))); }
; DI int crow(int r, int hi) { return (r & 3) + 8 * (r >> 2) + 4 * hi; }
; template <int DQK, int MODE, int LDQ, int LDK, int LDV> ...
;     ...
;     for (int r = 0; r < 16; ++r) { const int orow = wid * 32 + crow(r, hi); const float rl = __builtin_amdgcn_rcpf(li_l[crow(r, hi)]);
;         if constexpr (MODE == 0) {
; #pragma unroll
;             for (int d0 = 0; d0 < 4; ++d0) AOb[(size_t)orow * 1024 + d0 * 32 + r32] = f2bf(o[d0][r] * rl);
;         } else if constexpr (MODE == 1) {
; #pragma unroll
;             for (int d0 = 0; d0 < 4; ++d0) S0[(size_t)orow * 512 + d0 * 32 + r32] = o[d0][r] * rl;
;         } else {
;             float v[4]; float ss = 0.f;
; #pragma unroll
;             for (int d0 = 0; d0 < 4; ++d0) { v[d0] = s0v[r][d0] - lam * (o[d0][r] * rl); ss += v[d0] * v[d0]; }
; #pragma unroll
;             for (int mk = 1; mk <= 16; mk <<= 1) ss += shx(ss, mk, lane2);
;             const float rs = rsqrtf(ss * (1.f / 128.f) + EPS) * 0.8f;
; #pragma unroll
;             for (int d0 = 0; d0 < 4; ++d0) AOb[(size_t)orow * 1024 + d0 * 32 + r32] = f2bf(v[d0] * rs * gout[d0 * 32 + r32]);
	v_pk_add_f32 v[8:9], v[20:21], v[24:25]
	ds_bpermute_b32 v21, v168, v9
	ds_bpermute_b32 v20, v168, v8
	v_mul_f32_e32 v24, v162, v35
	v_bfe_u32 v25, v24, 16, 1
	v_mul_f32_e32 v5, v5, v34
	v_add3_u32 v24, v24, v25, s68
	s_waitcnt lgkmcnt(0)
	v_pk_add_f32 v[8:9], v[8:9], v[20:21]
	ds_bpermute_b32 v21, v167, v9
	ds_bpermute_b32 v20, v167, v8
	v_mul_f32_e32 v5, v161, v5
	global_store_short_d16_hi v[26:27], v24, off offset:1088
	v_bfe_u32 v24, v5, 16, 1
	v_add3_u32 v5, v5, v24, s68
	s_waitcnt lgkmcnt(0)
	v_pk_add_f32 v[8:9], v[8:9], v[20:21]
	ds_bpermute_b32 v21, v166, v9
	ds_bpermute_b32 v20, v166, v8
	v_mul_f32_e32 v4, v4, v34
	global_store_short_d16_hi v[26:27], v5, off offset:1152
	v_mul_f32_e32 v24, v130, v4
	v_bfe_u32 v25, v24, 16, 1
	s_waitcnt lgkmcnt(0)
	v_pk_add_f32 v[4:5], v[8:9], v[20:21]
	s_nop 0
	v_pk_fma_f32 v[4:5], v[4:5], s[24:25], v[92:93] op_sel_hi:[1,0,0]
	s_nop 0
	v_mul_f32_e32 v8, 0x4b800000, v5
	v_cmp_gt_f32_e32 vcc, s67, v5
	s_nop 1
	v_cndmask_b32_e32 v5, v5, v8, vcc
	v_rsq_f32_e32 v5, v5
	v_add3_u32 v8, v24, v25, s68
	global_store_short_d16_hi v[26:27], v8, off offset:1216
	v_lshl_add_u64 v[8:9], v[32:33], 0, v[76:77]
	v_mul_f32_e32 v20, 0x45800000, v5
	v_cndmask_b32_e32 v5, v5, v20, vcc
	v_mul_f32_e32 v5, 0x3f4ccccd, v5
	v_mul_f32_e32 v18, v18, v5
	v_mul_f32_e32 v18, v163, v18
	v_bfe_u32 v20, v18, 16, 1
	v_add3_u32 v18, v18, v20, s68
	global_store_short_d16_hi v[8:9], v18, off offset:1024
	v_mul_f32_e32 v18, v19, v5
	v_mul_f32_e32 v18, v162, v18
	v_bfe_u32 v19, v18, 16, 1
	v_add3_u32 v18, v18, v19, s68
	global_store_short_d16_hi v[8:9], v18, off offset:1088
	v_mul_f32_e32 v18, v23, v5
	v_mul_f32_e32 v18, v161, v18
	v_bfe_u32 v19, v18, 16, 1
	v_add3_u32 v18, v18, v19, s68
	global_store_short_d16_hi v[8:9], v18, off offset:1152
	v_mul_f32_e32 v18, 0x4b800000, v4
	v_cmp_gt_f32_e32 vcc, s67, v4
	v_mul_f32_e32 v5, v22, v5
	v_mul_f32_e32 v5, v130, v5
	v_cndmask_b32_e32 v4, v4, v18, vcc
	v_rsq_f32_e32 v4, v4
	v_bfe_u32 v18, v5, 16, 1
	v_add3_u32 v5, v5, v18, s68
	global_store_short_d16_hi v[8:9], v5, off offset:1216
	v_mul_f32_e32 v5, 0x45800000, v4
	v_cndmask_b32_e32 v34, v4, v5, vcc
	v_mov_b32_e32 v4, v12
	v_mov_b32_e32 v5, v60
	v_mov_b32_e32 v18, v44
	v_mov_b32_e32 v19, v28
	v_pk_mul_f32 v[4:5], v[4:5], v[0:1] op_sel_hi:[1,0]
	v_pk_mul_f32 v[18:19], v[18:19], v[0:1] op_sel_hi:[1,0]
	v_rcp_f32_e32 v0, v1
	v_mov_b32_e32 v60, v13
	v_mov_b32_e32 v28, v45
	s_waitcnt vmcnt(58)
	v_pk_fma_f32 v[4:5], v[128:129], v[4:5], v[116:117] neg_lo:[1,0,0] neg_hi:[1,0,0]
	v_pk_mul_f32 v[12:13], v[60:61], v[0:1] op_sel_hi:[1,0]
	v_pk_mul_f32 v[0:1], v[28:29], v[0:1] op_sel_hi:[1,0]
	s_waitcnt vmcnt(54)
	v_pk_fma_f32 v[12:13], v[128:129], v[12:13], v[112:113] neg_lo:[1,0,0] neg_hi:[1,0,0]
	v_pk_mul_f32 v[8:9], v[4:5], v[4:5]
	v_pk_fma_f32 v[18:19], v[128:129], v[18:19], v[114:115] neg_lo:[1,0,0] neg_hi:[1,0,0]
	v_pk_mul_f32 v[22:23], v[12:13], v[12:13]
	s_waitcnt vmcnt(52)
	v_pk_fma_f32 v[0:1], v[128:129], v[0:1], v[110:111] neg_lo:[1,0,0] neg_hi:[1,0,0]
	v_pk_mul_f32 v[20:21], v[18:19], v[18:19]
	v_pk_mul_f32 v[24:25], v[0:1], v[0:1]
	v_mov_b32_e32 v26, v22
	v_mov_b32_e32 v27, v8
	v_mov_b32_e32 v8, v23
	v_pk_add_f32 v[8:9], v[26:27], v[8:9]
	v_mov_b32_e32 v22, v25
	v_mov_b32_e32 v23, v21
	v_pk_add_f32 v[8:9], v[22:23], v[8:9]
	v_mov_b32_e32 v25, v20
	v_pk_add_f32 v[8:9], v[24:25], v[8:9]
	ds_bpermute_b32 v21, v164, v9
	ds_bpermute_b32 v20, v164, v8
	v_mul_f32_e32 v24, 0x3f4ccccd, v34
	v_mul_f32_e32 v10, v10, v24
	v_mul_f32_e32 v10, v163, v10
	v_bfe_u32 v25, v10, 16, 1
	s_waitcnt lgkmcnt(0)
	v_pk_add_f32 v[8:9], v[8:9], v[20:21]
	ds_bpermute_b32 v21, v165, v9
	ds_bpermute_b32 v20, v165, v8
	v_lshl_add_u64 v[22:23], v[32:33], 0, v[72:73]
	v_add3_u32 v10, v10, v25, s68
	global_store_short_d16_hi v[22:23], v10, off offset:1024
	v_mul_f32_e32 v25, v11, v24
	s_waitcnt lgkmcnt(0)
	v_pk_add_f32 v[8:9], v[8:9], v[20:21]
	ds_bpermute_b32 v11, v168, v9
	ds_bpermute_b32 v10, v168, v8
	v_mul_f32_e32 v20, v162, v25
	v_bfe_u32 v21, v20, 16, 1
	v_mul_f32_e32 v7, v7, v24
	v_add3_u32 v20, v20, v21, s68
	s_waitcnt lgkmcnt(0)
	v_pk_add_f32 v[8:9], v[8:9], v[10:11]
	ds_bpermute_b32 v11, v167, v9
	ds_bpermute_b32 v10, v167, v8
	v_mul_f32_e32 v7, v161, v7
	global_store_short_d16_hi v[22:23], v20, off offset:1088
	v_bfe_u32 v20, v7, 16, 1
	v_add3_u32 v7, v7, v20, s68
	s_waitcnt lgkmcnt(0)
	v_pk_add_f32 v[8:9], v[8:9], v[10:11]
	ds_bpermute_b32 v11, v166, v9
	ds_bpermute_b32 v10, v166, v8
	v_mul_f32_e32 v6, v6, v24
	global_store_short_d16_hi v[22:23], v7, off offset:1152
	v_mul_f32_e32 v20, v130, v6
	v_bfe_u32 v21, v20, 16, 1
	s_waitcnt lgkmcnt(0)
; DI unsigned short f2bf(float x) { unsigned u = __float_as_uint(x); u += 0x7fffu + ((u >> 16) & 1u); return (unsigned short)(u >> 16); }
; DI float shx(float v, int mask, int lane) { return __int_as_float(__builtin_amdgcn_ds_bpermute((lane ^ mask) << 2, __float_as_int(v))); }
; DI int crow(int r, int hi) { return (r & 3) + 8 * (r >> 2) + 4 * hi; }
; template <int DQK, int MODE, int LDQ, int LDK, int LDV> ...
;     ...
;     for (int r = 0; r < 16; ++r) { const int orow = wid * 32 + crow(r, hi); const float rl = __builtin_amdgcn_rcpf(li_l[crow(r, hi)]);
;         if constexpr (MODE == 0) {
; #pragma unroll
;             for (int d0 = 0; d0 < 4; ++d0) AOb[(size_t)orow * 1024 + d0 * 32 + r32] = f2bf(o[d0][r] * rl);
;         } else if constexpr (MODE == 1) {
; #pragma unroll
;             for (int d0 = 0; d0 < 4; ++d0) S0[(size_t)orow * 512 + d0 * 32 + r32] = o[d0][r] * rl;
;         } else {
;             float v[4]; float ss = 0.f;
; #pragma unroll
;             for (int d0 = 0; d0 < 4; ++d0) { v[d0] = s0v[r][d0] - lam * (o[d0][r] * rl); ss += v[d0] * v[d0]; }
; #pragma unroll
;             for (int mk = 1; mk <= 16; mk <<= 1) ss += shx(ss, mk, lane2);
;             const float rs = rsqrtf(ss * (1.f / 128.f) + EPS) * 0.8f;
; #pragma unroll
;             for (int d0 = 0; d0 < 4; ++d0) AOb[(size_t)orow * 1024 + d0 * 32 + r32] = f2bf(v[d0] * rs * gout[d0 * 32 + r32]);
;         } }
; DI void phase4(const Params& p, LAS unsigned char* lds, int wv) {
;     ...
;             __syncthreads();
	v_pk_add_f32 v[6:7], v[8:9], v[10:11]
	s_nop 0
	v_pk_fma_f32 v[6:7], v[6:7], s[24:25], v[92:93] op_sel_hi:[1,0,0]
	s_nop 0
	v_mul_f32_e32 v8, 0x4b800000, v7
	v_cmp_gt_f32_e32 vcc, s67, v7
	s_nop 1
	v_cndmask_b32_e32 v7, v7, v8, vcc
	v_rsq_f32_e32 v7, v7
	v_add3_u32 v8, v20, v21, s68
	global_store_short_d16_hi v[22:23], v8, off offset:1216
	v_lshl_add_u64 v[8:9], v[32:33], 0, v[74:75]
	v_mul_f32_e32 v10, 0x45800000, v7
	v_cndmask_b32_e32 v7, v7, v10, vcc
	v_mul_f32_e32 v7, 0x3f4ccccd, v7
	v_mul_f32_e32 v4, v4, v7
	v_mul_f32_e32 v4, v163, v4
	v_bfe_u32 v10, v4, 16, 1
	v_add3_u32 v4, v4, v10, s68
	global_store_short_d16_hi v[8:9], v4, off offset:1024
	v_mul_f32_e32 v4, v5, v7
	v_mul_f32_e32 v4, v162, v4
	v_bfe_u32 v5, v4, 16, 1
	v_add3_u32 v4, v4, v5, s68
	global_store_short_d16_hi v[8:9], v4, off offset:1088
	v_mul_f32_e32 v4, v19, v7
	v_mul_f32_e32 v4, v161, v4
	v_bfe_u32 v5, v4, 16, 1
	v_add3_u32 v4, v4, v5, s68
	v_mul_f32_e32 v5, 0x4b800000, v6
	v_cmp_gt_f32_e32 vcc, s67, v6
	global_store_short_d16_hi v[8:9], v4, off offset:1152
	v_mul_f32_e32 v4, v18, v7
	v_cndmask_b32_e32 v5, v6, v5, vcc
	v_rsq_f32_e32 v5, v5
	v_mul_f32_e32 v4, v130, v4
	v_bfe_u32 v6, v4, 16, 1
	v_add3_u32 v4, v4, v6, s68
	global_store_short_d16_hi v[8:9], v4, off offset:1216
	v_mul_f32_e32 v4, 0x45800000, v5
	v_cndmask_b32_e32 v24, v5, v4, vcc
	v_mov_b32_e32 v4, v14
	v_mov_b32_e32 v5, v62
	v_mov_b32_e32 v8, v46
	v_mov_b32_e32 v9, v30
	v_pk_mul_f32 v[4:5], v[4:5], v[2:3] op_sel_hi:[1,0]
	v_pk_mul_f32 v[8:9], v[8:9], v[2:3] op_sel_hi:[1,0]
	v_rcp_f32_e32 v2, v3
	v_mov_b32_e32 v62, v15
	v_mov_b32_e32 v30, v47
	s_waitcnt vmcnt(58)
	v_pk_fma_f32 v[4:5], v[128:129], v[4:5], v[108:109] neg_lo:[1,0,0] neg_hi:[1,0,0]
	v_pk_mul_f32 v[14:15], v[62:63], v[2:3] op_sel_hi:[1,0]
	v_pk_mul_f32 v[2:3], v[30:31], v[2:3] op_sel_hi:[1,0]
	s_waitcnt vmcnt(54)
	v_pk_fma_f32 v[14:15], v[128:129], v[14:15], v[104:105] neg_lo:[1,0,0] neg_hi:[1,0,0]
	v_pk_mul_f32 v[6:7], v[4:5], v[4:5]
	v_pk_fma_f32 v[8:9], v[128:129], v[8:9], v[106:107] neg_lo:[1,0,0] neg_hi:[1,0,0]
	v_pk_mul_f32 v[18:19], v[14:15], v[14:15]
	s_waitcnt vmcnt(52)
	v_pk_fma_f32 v[2:3], v[128:129], v[2:3], v[102:103] neg_lo:[1,0,0] neg_hi:[1,0,0]
	v_pk_mul_f32 v[10:11], v[8:9], v[8:9]
	v_pk_mul_f32 v[20:21], v[2:3], v[2:3]
	v_mov_b32_e32 v22, v18
	v_mov_b32_e32 v23, v6
	v_mov_b32_e32 v6, v19
	v_pk_add_f32 v[6:7], v[22:23], v[6:7]
	v_mov_b32_e32 v18, v21
	v_mov_b32_e32 v19, v11
	v_pk_add_f32 v[6:7], v[18:19], v[6:7]
	v_mov_b32_e32 v21, v10
	v_pk_add_f32 v[6:7], v[20:21], v[6:7]
	ds_bpermute_b32 v11, v164, v7
	ds_bpermute_b32 v10, v164, v6
	v_mul_f32_e32 v20, 0x3f4ccccd, v24
	v_mul_f32_e32 v12, v12, v20
	v_mul_f32_e32 v12, v163, v12
	v_bfe_u32 v21, v12, 16, 1
	s_waitcnt lgkmcnt(0)
	v_pk_add_f32 v[6:7], v[6:7], v[10:11]
	ds_bpermute_b32 v11, v165, v7
	ds_bpermute_b32 v10, v165, v6
	v_lshl_add_u64 v[18:19], v[32:33], 0, v[64:65]
	v_add3_u32 v12, v12, v21, s68
	global_store_short_d16_hi v[18:19], v12, off offset:1024
	v_mul_f32_e32 v12, v13, v20
	s_waitcnt lgkmcnt(0)
	v_pk_add_f32 v[6:7], v[6:7], v[10:11]
	ds_bpermute_b32 v11, v168, v7
	ds_bpermute_b32 v10, v168, v6
	v_mul_f32_e32 v12, v162, v12
	v_bfe_u32 v13, v12, 16, 1
	v_mul_f32_e32 v1, v1, v20
	v_add3_u32 v12, v12, v13, s68
	s_waitcnt lgkmcnt(0)
	v_pk_add_f32 v[6:7], v[6:7], v[10:11]
	ds_bpermute_b32 v11, v167, v7
	ds_bpermute_b32 v10, v167, v6
	v_mul_f32_e32 v1, v161, v1
	global_store_short_d16_hi v[18:19], v12, off offset:1088
	v_bfe_u32 v12, v1, 16, 1
	v_add3_u32 v1, v1, v12, s68
	s_waitcnt lgkmcnt(0)
	v_pk_add_f32 v[6:7], v[6:7], v[10:11]
	ds_bpermute_b32 v11, v166, v7
	ds_bpermute_b32 v10, v166, v6
	v_mul_f32_e32 v0, v0, v20
	global_store_short_d16_hi v[18:19], v1, off offset:1152
	v_mul_f32_e32 v12, v130, v0
	v_bfe_u32 v13, v12, 16, 1
	s_waitcnt lgkmcnt(0)
	v_pk_add_f32 v[0:1], v[6:7], v[10:11]
	s_nop 0
	v_pk_fma_f32 v[0:1], v[0:1], s[24:25], v[92:93] op_sel_hi:[1,0,0]
	s_nop 0
	v_mul_f32_e32 v6, 0x4b800000, v1
	v_cmp_gt_f32_e32 vcc, s67, v1
	s_nop 1
	v_cndmask_b32_e32 v1, v1, v6, vcc
	v_rsq_f32_e32 v1, v1
	v_add3_u32 v6, v12, v13, s68
	global_store_short_d16_hi v[18:19], v6, off offset:1216
	v_lshl_add_u64 v[6:7], v[32:33], 0, v[48:49]
	v_mul_f32_e32 v10, 0x45800000, v1
	v_cndmask_b32_e32 v1, v1, v10, vcc
	v_mul_f32_e32 v1, 0x3f4ccccd, v1
	v_mul_f32_e32 v4, v4, v1
	v_mul_f32_e32 v4, v163, v4
	v_bfe_u32 v10, v4, 16, 1
	v_add3_u32 v4, v4, v10, s68
	global_store_short_d16_hi v[6:7], v4, off offset:1024
	v_mul_f32_e32 v4, v5, v1
	v_mul_f32_e32 v4, v162, v4
	v_bfe_u32 v5, v4, 16, 1
	v_add3_u32 v4, v4, v5, s68
	global_store_short_d16_hi v[6:7], v4, off offset:1088
	v_mul_f32_e32 v4, v9, v1
	v_mul_f32_e32 v4, v161, v4
	v_bfe_u32 v5, v4, 16, 1
	v_add3_u32 v4, v4, v5, s68
	global_store_short_d16_hi v[6:7], v4, off offset:1152
	v_mul_f32_e32 v4, 0x4b800000, v0
	v_cmp_gt_f32_e32 vcc, s67, v0
	v_mul_f32_e32 v1, v8, v1
	v_mul_f32_e32 v1, v130, v1
	v_cndmask_b32_e32 v0, v0, v4, vcc
	v_rsq_f32_e32 v0, v0
	v_bfe_u32 v4, v1, 16, 1
	v_add3_u32 v1, v1, v4, s68
	global_store_short_d16_hi v[6:7], v1, off offset:1216
	v_mul_f32_e32 v1, 0x45800000, v0
	v_cndmask_b32_e32 v0, v0, v1, vcc
	v_mul_f32_e32 v4, 0x3f4ccccd, v0
	v_mul_f32_e32 v5, v14, v4
	v_mul_f32_e32 v5, v163, v5
	v_bfe_u32 v6, v5, 16, 1
	v_lshl_add_u64 v[0:1], v[32:33], 0, v[16:17]
	v_add3_u32 v5, v5, v6, s68
	global_store_short_d16_hi v[0:1], v5, off offset:1024
	v_mul_f32_e32 v5, v15, v4
	v_mul_f32_e32 v5, v162, v5
	v_bfe_u32 v6, v5, 16, 1
	v_mul_f32_e32 v3, v3, v4
	v_add3_u32 v5, v5, v6, s68
	v_mul_f32_e32 v3, v161, v3
	global_store_short_d16_hi v[0:1], v5, off offset:1088
	v_bfe_u32 v5, v3, 16, 1
	v_mul_f32_e32 v2, v2, v4
	v_add3_u32 v3, v3, v5, s68
	v_mul_f32_e32 v2, v130, v2
	global_store_short_d16_hi v[0:1], v3, off offset:1152
	v_bfe_u32 v3, v2, 16, 1
	v_add3_u32 v2, v2, v3, s68
	global_store_short_d16_hi v[0:1], v2, off offset:1216
	s_waitcnt vmcnt(63) expcnt(7) lgkmcnt(15)
	s_barrier

.Lstg_mla_top_2:
	s_mov_b32 m0, s1
	s_mov_b32 s0, s5
	s_mov_b32 s5, s44
	s_mov_b32 s44, s4
	s_lshl_b32 s4, s4, 14
	global_load_lds_dwordx4 v136, s[34:35]
	s_add_i32 m0, s1, 0x2000
	s_add_i32 s4, s52, s4
	global_load_lds_dwordx4 v138, s[34:35]
	s_add_i32 m0, s1, 0x4000
	s_add_i32 s6, s4, 0x400
	global_load_lds_dwordx4 v140, s[34:35]
	s_mov_b32 m0, s4
	s_add_i32 s1, s43, -3
	global_load_lds_dwordx4 v144, s[34:35]
	s_mov_b32 m0, s6
	s_nop 0
	global_load_lds_dwordx4 v142, s[34:35]
	s_and_b32 s1, s1, 3
	s_mulk_i32 s1, 0x6000
	v_add_u32_e32 v246, s1, v158
	v_add_u32_e32 v174, v246, v151
	v_add_u32_e32 v178, v246, v149
	v_add_u32_e32 v182, v246, v148
	v_add_u32_e32 v186, v246, v147
	v_add_u32_e32 v190, v246, v146
	v_add_u32_e32 v194, v246, v150
	s_lshl_b32 s1, s0, 14
	ds_read_b128 v[174:177], v174 offset:12288
	ds_read_b128 v[178:181], v178 offset:12288
	ds_read_b128 v[182:185], v182 offset:12288
	ds_read_b128 v[186:189], v186 offset:12288
	ds_read_b128 v[190:193], v190 offset:12288
	ds_read_b128 v[194:197], v194 offset:12288
	v_add_u32_e32 v254, s1, v130
	ds_read_b64_tr_b16 v[198:199], v254 offset:0
	ds_read_b64_tr_b16 v[200:201], v254 offset:0x800
	ds_read_b64_tr_b16 v[202:203], v254 offset:0x1000
	ds_read_b64_tr_b16 v[204:205], v254 offset:0x1800
	ds_read_b64_tr_b16 v[206:207], v254 offset:0x200
	ds_read_b64_tr_b16 v[208:209], v254 offset:0xa00
	ds_read_b64_tr_b16 v[210:211], v254 offset:0x1200
	ds_read_b64_tr_b16 v[212:213], v254 offset:0x1a00
	ds_read_b64_tr_b16 v[214:215], v254 offset:0x400
	ds_read_b64_tr_b16 v[216:217], v254 offset:0xc00
	ds_read_b64_tr_b16 v[218:219], v254 offset:0x1400
	ds_read_b64_tr_b16 v[220:221], v254 offset:0x1c00
	ds_read_b64_tr_b16 v[222:223], v254 offset:0x600
	ds_read_b64_tr_b16 v[224:225], v254 offset:0xe00
	ds_read_b64_tr_b16 v[226:227], v254 offset:0x1600
	ds_read_b64_tr_b16 v[228:229], v254 offset:0x1e00
	v_exp_f32_e32 v64, v64
	v_exp_f32_e32 v65, v65
	v_exp_f32_e32 v66, v66
	v_exp_f32_e32 v67, v67
	v_exp_f32_e32 v68, v68
	v_add_f32_e32 v230, 0, v64
	v_exp_f32_e32 v69, v69
	v_add_f32_e32 v230, v65, v230
	v_exp_f32_e32 v70, v70
	v_add_f32_e32 v230, v66, v230
	v_exp_f32_e32 v71, v71
	v_add_f32_e32 v230, v67, v230
	v_exp_f32_e32 v72, v72
	v_add_f32_e32 v230, v68, v230
	v_exp_f32_e32 v73, v73
	v_add_f32_e32 v230, v69, v230
	v_exp_f32_e32 v74, v74
	v_add_f32_e32 v230, v70, v230
	v_exp_f32_e32 v75, v75
	v_add_f32_e32 v230, v71, v230
	v_exp_f32_e32 v76, v76
	v_add_f32_e32 v230, v72, v230
	v_exp_f32_e32 v77, v77
	v_add_f32_e32 v230, v73, v230
	v_exp_f32_e32 v78, v78
	v_add_f32_e32 v230, v74, v230
	v_exp_f32_e32 v79, v79
	v_add_f32_e32 v230, v75, v230
	v_add_f32_e32 v230, v76, v230
	v_add_f32_e32 v230, v77, v230
	v_add_f32_e32 v230, v78, v230
	v_add_f32_e32 v230, v79, v230
	v_add_f32_e32 v173, v173, v230
	v_cvt_pk_bf16_f32 v64, v64, v65
	v_cvt_pk_bf16_f32 v65, v66, v67
	v_cvt_pk_bf16_f32 v66, v68, v69
	v_cvt_pk_bf16_f32 v67, v70, v71
	v_cvt_pk_bf16_f32 v68, v72, v73
	v_cvt_pk_bf16_f32 v69, v74, v75
	v_cvt_pk_bf16_f32 v70, v76, v77
	v_cvt_pk_bf16_f32 v71, v78, v79
	s_nop 0
	v_permlane32_swap_b32_e32 v64, v66
	v_permlane32_swap_b32_e32 v65, v67
	v_permlane32_swap_b32_e32 v68, v70
	v_permlane32_swap_b32_e32 v69, v71
	s_waitcnt lgkmcnt(0)
	v_add_u32_e32 v72, v246, v152
	v_add_u32_e32 v73, v246, v153
	ds_read_b128 v[230:233], v72 offset:12288
	ds_read_b128 v[234:237], v73 offset:12288
	v_add_u32_e32 v72, v246, v154
	v_add_u32_e32 v73, v246, v155
	ds_read_b128 v[238:241], v72 offset:12288
	ds_read_b128 v[242:245], v73 offset:12288
	v_add_u32_e32 v72, v246, v156
	v_add_u32_e32 v73, v246, v157
	ds_read_b128 v[246:249], v72 offset:12288
	ds_read_b128 v[250:253], v73 offset:12288
	v_mfma_f32_32x32x16_bf16 v[48:63], v[64:67], v[198:201], v[48:63]
	v_mfma_f32_32x32x16_bf16 v[32:47], v[64:67], v[206:209], v[32:47]
	v_mfma_f32_32x32x16_bf16 v[16:31], v[64:67], v[214:217], v[16:31]
	v_mfma_f32_32x32x16_bf16 v[0:15], v[64:67], v[222:225], v[0:15]
	v_mfma_f32_32x32x16_bf16 v[48:63], v[68:71], v[202:205], v[48:63]
	v_mfma_f32_32x32x16_bf16 v[32:47], v[68:71], v[210:213], v[32:47]
	v_mfma_f32_32x32x16_bf16 v[16:31], v[68:71], v[218:221], v[16:31]
	v_mfma_f32_32x32x16_bf16 v[0:15], v[68:71], v[226:229], v[0:15]
	s_waitcnt lgkmcnt(0)
; #define ATT_TOP(N) do { asm volatile("s_waitcnt vmcnt(%0)" :: "n"(N) : "memory"); __builtin_amdgcn_s_barrier(); asm volatile("" ::: "memory"); } while (0)
; template <int DQK, int MODE, int LDQ, int LDK, int LDV> ...
;     ...
;         if (j + 2 < NT) ATT_TOP(NKP + 2); else ATT_TOP(0);
	v_mfma_f32_32x32x16_bf16 v[64:79], v[174:177], v[80:83], 0
	v_mfma_f32_32x32x16_bf16 v[64:79], v[178:181], v[84:87], v[64:79]
	v_mfma_f32_32x32x16_bf16 v[64:79], v[182:185], v[88:91], v[64:79]
	v_mfma_f32_32x32x16_bf16 v[64:79], v[186:189], v[92:95], v[64:79]
	v_mfma_f32_32x32x16_bf16 v[64:79], v[190:193], v[96:99], v[64:79]
	v_mfma_f32_32x32x16_bf16 v[64:79], v[194:197], v[100:103], v[64:79]
	v_mfma_f32_32x32x16_bf16 v[64:79], v[230:233], v[104:107], v[64:79]
	v_mfma_f32_32x32x16_bf16 v[64:79], v[234:237], v[108:111], v[64:79]
	v_mfma_f32_32x32x16_bf16 v[64:79], v[238:241], v[112:115], v[64:79]
	v_mfma_f32_32x32x16_bf16 v[64:79], v[242:245], v[116:119], v[64:79]
	v_mfma_f32_32x32x16_bf16 v[64:79], v[246:249], v[120:123], v[64:79]
	v_mfma_f32_32x32x16_bf16 v[64:79], v[250:253], v[124:127], v[64:79]
	s_add_i32 s4, s43, -2
	s_and_b32 s4, s4, 3
	s_mulk_i32 s4, 0x6000
	v_add_u32_e32 v246, s4, v158
	v_add_u32_e32 v174, v246, v151
	v_add_u32_e32 v178, v246, v149
	v_add_u32_e32 v182, v246, v148
	v_add_u32_e32 v186, v246, v147
	v_add_u32_e32 v190, v246, v146
	v_add_u32_e32 v194, v246, v150
	ds_read_b128 v[174:177], v174
	ds_read_b128 v[178:181], v178
	ds_read_b128 v[182:185], v182
	ds_read_b128 v[186:189], v186
	ds_read_b128 v[190:193], v190
	ds_read_b128 v[194:197], v194
	ds_read_b64_tr_b16 v[198:199], v254 offset:0x2000
	ds_read_b64_tr_b16 v[200:201], v254 offset:0x2800
	ds_read_b64_tr_b16 v[202:203], v254 offset:0x3000
	ds_read_b64_tr_b16 v[204:205], v254 offset:0x3800
	ds_read_b64_tr_b16 v[206:207], v254 offset:0x2200
	ds_read_b64_tr_b16 v[208:209], v254 offset:0x2a00
	ds_read_b64_tr_b16 v[210:211], v254 offset:0x3200
	ds_read_b64_tr_b16 v[212:213], v254 offset:0x3a00
	ds_read_b64_tr_b16 v[214:215], v254 offset:0x2400
	ds_read_b64_tr_b16 v[216:217], v254 offset:0x2c00
	ds_read_b64_tr_b16 v[218:219], v254 offset:0x3400
	ds_read_b64_tr_b16 v[220:221], v254 offset:0x3c00
	ds_read_b64_tr_b16 v[222:223], v254 offset:0x2600
	ds_read_b64_tr_b16 v[224:225], v254 offset:0x2e00
	ds_read_b64_tr_b16 v[226:227], v254 offset:0x3600
	ds_read_b64_tr_b16 v[228:229], v254 offset:0x3e00
	v_exp_f32_e32 v64, v64
	v_exp_f32_e32 v65, v65
	v_exp_f32_e32 v66, v66
	v_exp_f32_e32 v67, v67
	v_exp_f32_e32 v68, v68
	v_add_f32_e32 v230, 0, v64
	v_exp_f32_e32 v69, v69
	v_add_f32_e32 v230, v65, v230
	v_exp_f32_e32 v70, v70
	v_add_f32_e32 v230, v66, v230
	v_exp_f32_e32 v71, v71
	v_add_f32_e32 v230, v67, v230
	v_exp_f32_e32 v72, v72
	v_add_f32_e32 v230, v68, v230
	v_exp_f32_e32 v73, v73
	v_add_f32_e32 v230, v69, v230
	v_exp_f32_e32 v74, v74
	v_add_f32_e32 v230, v70, v230
	v_exp_f32_e32 v75, v75
	v_add_f32_e32 v230, v71, v230
	v_exp_f32_e32 v76, v76
	v_add_f32_e32 v230, v72, v230
	v_exp_f32_e32 v77, v77
	v_add_f32_e32 v230, v73, v230
	v_exp_f32_e32 v78, v78
	v_add_f32_e32 v230, v74, v230
	v_exp_f32_e32 v79, v79
	v_add_f32_e32 v230, v75, v230
	v_add_f32_e32 v230, v76, v230
	v_add_f32_e32 v230, v77, v230
	v_add_f32_e32 v230, v78, v230
	v_add_f32_e32 v230, v79, v230
	v_add_f32_e32 v173, v173, v230
	v_cvt_pk_bf16_f32 v64, v64, v65
	v_cvt_pk_bf16_f32 v65, v66, v67
	v_cvt_pk_bf16_f32 v66, v68, v69
	v_cvt_pk_bf16_f32 v67, v70, v71
	v_cvt_pk_bf16_f32 v68, v72, v73
	v_cvt_pk_bf16_f32 v69, v74, v75
	v_cvt_pk_bf16_f32 v70, v76, v77
	v_cvt_pk_bf16_f32 v71, v78, v79
	s_nop 0
	v_permlane32_swap_b32_e32 v64, v66
	v_permlane32_swap_b32_e32 v65, v67
	v_permlane32_swap_b32_e32 v68, v70
	v_permlane32_swap_b32_e32 v69, v71
	s_waitcnt lgkmcnt(0)
	v_add_u32_e32 v72, v246, v152
	v_add_u32_e32 v73, v246, v153
	ds_read_b128 v[230:233], v72
	ds_read_b128 v[234:237], v73
	v_add_u32_e32 v72, v246, v154
	v_add_u32_e32 v73, v246, v155
	ds_read_b128 v[238:241], v72
	ds_read_b128 v[242:245], v73
	v_add_u32_e32 v72, v246, v156
	v_add_u32_e32 v73, v246, v157
	ds_read_b128 v[246:249], v72
	ds_read_b128 v[250:253], v73
	s_cmp_lt_u32 s33, 0x100
	s_cbranch_scc1 .Lstg_mla_mid_3
	s_waitcnt vmcnt(5)
	s_barrier

.Lstg_mla_t61_4:
	v_lshl_add_u64 v[132:133], v[132:133], 1, s[0:1]
	s_mov_b32 m0, s6
	v_lshl_add_u64 v[134:135], v[134:135], 1, s[0:1]
	global_load_lds_dwordx4 v[132:133], off
	s_mov_b32 m0, s7
	s_nop 0
	global_load_lds_dwordx4 v[134:135], off
	ds_read_b128 v[132:135], v161 offset:36864
	ds_read_b128 v[136:139], v162 offset:36864
	ds_read_b128 v[140:143], v163 offset:36864
	ds_read_b128 v[174:177], v164 offset:36864
	ds_read_b128 v[178:181], v165 offset:36864
	ds_read_b128 v[182:185], v166 offset:36864
	v_lshl_add_u32 v144, s5, 14, v130
	ds_read_b64_tr_b16 v[186:187], v144 offset:0
	ds_read_b64_tr_b16 v[188:189], v144 offset:0x800
	ds_read_b64_tr_b16 v[190:191], v144 offset:0x1000
	ds_read_b64_tr_b16 v[192:193], v144 offset:0x1800
	ds_read_b64_tr_b16 v[194:195], v144 offset:0x200
	ds_read_b64_tr_b16 v[196:197], v144 offset:0xa00
	ds_read_b64_tr_b16 v[198:199], v144 offset:0x1200
	ds_read_b64_tr_b16 v[200:201], v144 offset:0x1a00
	ds_read_b64_tr_b16 v[202:203], v144 offset:0x400
	ds_read_b64_tr_b16 v[204:205], v144 offset:0xc00
	ds_read_b64_tr_b16 v[206:207], v144 offset:0x1400
	ds_read_b64_tr_b16 v[208:209], v144 offset:0x1c00
	ds_read_b64_tr_b16 v[210:211], v144 offset:0x600
	ds_read_b64_tr_b16 v[212:213], v144 offset:0xe00
	ds_read_b64_tr_b16 v[214:215], v144 offset:0x1600
	ds_read_b64_tr_b16 v[216:217], v144 offset:0x1e00
	v_exp_f32_e32 v64, v64
	v_exp_f32_e32 v65, v65
	v_exp_f32_e32 v66, v66
	v_exp_f32_e32 v67, v67
	v_exp_f32_e32 v68, v68
	v_add_f32_e32 v145, 0, v64
	v_exp_f32_e32 v69, v69
	v_add_f32_e32 v145, v65, v145
	v_exp_f32_e32 v70, v70
	v_add_f32_e32 v145, v66, v145
	v_exp_f32_e32 v71, v71
	v_add_f32_e32 v145, v67, v145
	v_exp_f32_e32 v72, v72
	v_add_f32_e32 v145, v68, v145
	v_exp_f32_e32 v73, v73
	v_add_f32_e32 v145, v69, v145
	v_exp_f32_e32 v74, v74
	v_add_f32_e32 v145, v70, v145
	v_exp_f32_e32 v75, v75
	v_add_f32_e32 v145, v71, v145
	v_exp_f32_e32 v76, v76
	v_add_f32_e32 v145, v72, v145
	v_exp_f32_e32 v77, v77
	v_add_f32_e32 v145, v73, v145
	v_exp_f32_e32 v78, v78
	v_add_f32_e32 v145, v74, v145
	v_exp_f32_e32 v79, v79
	v_add_f32_e32 v145, v75, v145
	v_add_f32_e32 v145, v76, v145
	v_add_f32_e32 v145, v77, v145
	v_add_f32_e32 v145, v78, v145
	v_add_f32_e32 v145, v79, v145
	v_add_f32_e32 v145, v173, v145
	v_cvt_pk_bf16_f32 v64, v64, v65
	v_cvt_pk_bf16_f32 v65, v66, v67
	v_cvt_pk_bf16_f32 v66, v68, v69
	v_cvt_pk_bf16_f32 v67, v70, v71
	v_cvt_pk_bf16_f32 v68, v72, v73
	v_cvt_pk_bf16_f32 v69, v74, v75
	v_cvt_pk_bf16_f32 v70, v76, v77
	v_cvt_pk_bf16_f32 v71, v78, v79
	s_nop 0
	v_permlane32_swap_b32_e32 v64, v66
	v_permlane32_swap_b32_e32 v65, v67
	v_permlane32_swap_b32_e32 v68, v70
	v_permlane32_swap_b32_e32 v69, v71
	s_waitcnt lgkmcnt(0)
	ds_read_b128 v[218:221], v167 offset:36864
	ds_read_b128 v[222:225], v168 offset:36864
	ds_read_b128 v[226:229], v169 offset:36864
	ds_read_b128 v[230:233], v170 offset:36864
	ds_read_b128 v[234:237], v171 offset:36864
	ds_read_b128 v[238:241], v172 offset:36864
	v_mfma_f32_32x32x16_bf16 v[48:63], v[64:67], v[186:189], v[48:63]
	v_mfma_f32_32x32x16_bf16 v[32:47], v[64:67], v[194:197], v[32:47]
	v_mfma_f32_32x32x16_bf16 v[16:31], v[64:67], v[202:205], v[16:31]
	v_mfma_f32_32x32x16_bf16 v[0:15], v[64:67], v[210:213], v[0:15]
	v_mfma_f32_32x32x16_bf16 v[48:63], v[68:71], v[190:193], v[48:63]
	v_mfma_f32_32x32x16_bf16 v[32:47], v[68:71], v[198:201], v[32:47]
	v_mfma_f32_32x32x16_bf16 v[16:31], v[68:71], v[206:209], v[16:31]
	v_mfma_f32_32x32x16_bf16 v[0:15], v[68:71], v[214:217], v[0:15]
	s_waitcnt lgkmcnt(0)
	v_mfma_f32_32x32x16_bf16 v[64:79], v[132:135], v[80:83], 0
	v_mfma_f32_32x32x16_bf16 v[64:79], v[136:139], v[84:87], v[64:79]
	v_mfma_f32_32x32x16_bf16 v[64:79], v[140:143], v[88:91], v[64:79]
	v_mfma_f32_32x32x16_bf16 v[64:79], v[174:177], v[92:95], v[64:79]
	v_mfma_f32_32x32x16_bf16 v[64:79], v[178:181], v[96:99], v[64:79]
	v_mfma_f32_32x32x16_bf16 v[64:79], v[182:185], v[100:103], v[64:79]
	s_waitcnt lgkmcnt(0)
	v_mfma_f32_32x32x16_bf16 v[64:79], v[218:221], v[104:107], v[64:79]
	v_mfma_f32_32x32x16_bf16 v[64:79], v[222:225], v[108:111], v[64:79]
	v_mfma_f32_32x32x16_bf16 v[64:79], v[226:229], v[112:115], v[64:79]
	v_mfma_f32_32x32x16_bf16 v[64:79], v[230:233], v[116:119], v[64:79]
	v_mfma_f32_32x32x16_bf16 v[64:79], v[234:237], v[120:123], v[64:79]
	v_mfma_f32_32x32x16_bf16 v[64:79], v[238:241], v[124:127], v[64:79]
	ds_read_b128 v[132:135], v161 offset:49152
	ds_read_b128 v[136:139], v162 offset:49152
	ds_read_b128 v[140:143], v163 offset:49152
	ds_read_b128 v[174:177], v164 offset:49152
	ds_read_b128 v[178:181], v165 offset:49152
	ds_read_b128 v[182:185], v166 offset:49152
	ds_read_b64_tr_b16 v[186:187], v144 offset:0x2000
	ds_read_b64_tr_b16 v[188:189], v144 offset:0x2800
	ds_read_b64_tr_b16 v[190:191], v144 offset:0x3000
	ds_read_b64_tr_b16 v[192:193], v144 offset:0x3800
	ds_read_b64_tr_b16 v[194:195], v144 offset:0x2200
	ds_read_b64_tr_b16 v[196:197], v144 offset:0x2a00
	ds_read_b64_tr_b16 v[198:199], v144 offset:0x3200
	ds_read_b64_tr_b16 v[200:201], v144 offset:0x3a00
	ds_read_b64_tr_b16 v[202:203], v144 offset:0x2400
	ds_read_b64_tr_b16 v[204:205], v144 offset:0x2c00
	ds_read_b64_tr_b16 v[206:207], v144 offset:0x3400
	ds_read_b64_tr_b16 v[208:209], v144 offset:0x3c00
	ds_read_b64_tr_b16 v[210:211], v144 offset:0x2600
	ds_read_b64_tr_b16 v[212:213], v144 offset:0x2e00
	ds_read_b64_tr_b16 v[214:215], v144 offset:0x3600
	ds_read_b64_tr_b16 v[216:217], v144 offset:0x3e00
	s_nop 5
	v_exp_f32_e32 v64, v64
	v_exp_f32_e32 v65, v65
	v_exp_f32_e32 v66, v66
	v_exp_f32_e32 v67, v67
	v_exp_f32_e32 v68, v68
	v_add_f32_e32 v144, 0, v64
	v_exp_f32_e32 v69, v69
	v_add_f32_e32 v144, v65, v144
	v_exp_f32_e32 v70, v70
	v_add_f32_e32 v144, v66, v144
	v_exp_f32_e32 v71, v71
	v_add_f32_e32 v144, v67, v144
	v_exp_f32_e32 v72, v72
	v_add_f32_e32 v144, v68, v144
	v_exp_f32_e32 v73, v73
	v_add_f32_e32 v144, v69, v144
	v_exp_f32_e32 v74, v74
	v_add_f32_e32 v144, v70, v144
	v_exp_f32_e32 v75, v75
	v_add_f32_e32 v144, v71, v144
	v_exp_f32_e32 v76, v76
	v_add_f32_e32 v144, v72, v144
	v_exp_f32_e32 v77, v77
	v_add_f32_e32 v144, v73, v144
	v_exp_f32_e32 v78, v78
	v_add_f32_e32 v144, v74, v144
	v_exp_f32_e32 v79, v79
	v_add_f32_e32 v144, v75, v144
	v_add_f32_e32 v144, v76, v144
	v_add_f32_e32 v144, v77, v144
	v_add_f32_e32 v144, v78, v144
	v_add_f32_e32 v144, v79, v144
	v_add_f32_e32 v144, v145, v144
	v_cvt_pk_bf16_f32 v64, v64, v65
	v_cvt_pk_bf16_f32 v65, v66, v67
	v_cvt_pk_bf16_f32 v66, v68, v69
	v_cvt_pk_bf16_f32 v67, v70, v71
	v_cvt_pk_bf16_f32 v68, v72, v73
	v_cvt_pk_bf16_f32 v69, v74, v75
	v_cvt_pk_bf16_f32 v70, v76, v77
	v_cvt_pk_bf16_f32 v71, v78, v79
	s_nop 0
	v_permlane32_swap_b32_e32 v64, v66
	v_permlane32_swap_b32_e32 v65, v67
	v_permlane32_swap_b32_e32 v68, v70
	v_permlane32_swap_b32_e32 v69, v71
	s_waitcnt lgkmcnt(0)
	ds_read_b128 v[218:221], v167 offset:49152
	ds_read_b128 v[222:225], v168 offset:49152
	ds_read_b128 v[226:229], v169 offset:49152
	ds_read_b128 v[230:233], v170 offset:49152
	ds_read_b128 v[234:237], v171 offset:49152
	ds_read_b128 v[238:241], v172 offset:49152
	s_cmp_lt_u32 s33, 0x100
	s_cbranch_scc1 .Lstg_mla_m61_5
	s_waitcnt vmcnt(0)
	s_barrier

.Lstg_mla_t62_6:
	ds_read_b128 v[132:135], v161 offset:61440
	ds_read_b128 v[136:139], v162 offset:61440
	ds_read_b128 v[140:143], v163 offset:61440
	ds_read_b128 v[174:177], v164 offset:61440
	ds_read_b128 v[162:165], v165 offset:61440
	ds_read_b128 v[178:181], v166 offset:61440
	v_add_u32_e32 v145, 0x8000, v130
	ds_read_b64_tr_b16 v[182:183], v145 offset:0
	ds_read_b64_tr_b16 v[184:185], v145 offset:0x800
	ds_read_b64_tr_b16 v[186:187], v145 offset:0x1000
	ds_read_b64_tr_b16 v[188:189], v145 offset:0x1800
	ds_read_b64_tr_b16 v[190:191], v145 offset:0x200
	ds_read_b64_tr_b16 v[192:193], v145 offset:0xa00
	ds_read_b64_tr_b16 v[194:195], v145 offset:0x1200
	ds_read_b64_tr_b16 v[196:197], v145 offset:0x1a00
	ds_read_b64_tr_b16 v[198:199], v145 offset:0x400
	ds_read_b64_tr_b16 v[200:201], v145 offset:0xc00
	ds_read_b64_tr_b16 v[202:203], v145 offset:0x1400
	ds_read_b64_tr_b16 v[204:205], v145 offset:0x1c00
	ds_read_b64_tr_b16 v[206:207], v145 offset:0x600
	ds_read_b64_tr_b16 v[208:209], v145 offset:0xe00
	ds_read_b64_tr_b16 v[210:211], v145 offset:0x1600
	ds_read_b64_tr_b16 v[212:213], v145 offset:0x1e00
	s_nop 3
	v_exp_f32_e32 v64, v64
	v_exp_f32_e32 v65, v65
	v_exp_f32_e32 v66, v66
	v_exp_f32_e32 v67, v67
	v_exp_f32_e32 v68, v68
	v_add_f32_e32 v161, 0, v64
	v_exp_f32_e32 v69, v69
	v_add_f32_e32 v161, v65, v161
	v_exp_f32_e32 v70, v70
	v_add_f32_e32 v161, v66, v161
	v_exp_f32_e32 v71, v71
	v_add_f32_e32 v161, v67, v161
	v_exp_f32_e32 v72, v72
	v_add_f32_e32 v161, v68, v161
	v_exp_f32_e32 v73, v73
	v_add_f32_e32 v161, v69, v161
	v_exp_f32_e32 v74, v74
	v_add_f32_e32 v161, v70, v161
	v_exp_f32_e32 v75, v75
	v_add_f32_e32 v161, v71, v161
	v_exp_f32_e32 v76, v76
	v_add_f32_e32 v161, v72, v161
	v_exp_f32_e32 v77, v77
	v_add_f32_e32 v161, v73, v161
	v_exp_f32_e32 v78, v78
	v_add_f32_e32 v161, v74, v161
	v_exp_f32_e32 v79, v79
	v_add_f32_e32 v161, v75, v161
	v_add_f32_e32 v161, v76, v161
	v_add_f32_e32 v161, v77, v161
	v_add_f32_e32 v161, v78, v161
	v_add_f32_e32 v161, v79, v161
	v_add_f32_e32 v144, v144, v161
	v_cvt_pk_bf16_f32 v64, v64, v65
	v_cvt_pk_bf16_f32 v65, v66, v67
	v_cvt_pk_bf16_f32 v66, v68, v69
	v_cvt_pk_bf16_f32 v67, v70, v71
	v_cvt_pk_bf16_f32 v68, v72, v73
	v_cvt_pk_bf16_f32 v69, v74, v75
	v_cvt_pk_bf16_f32 v70, v76, v77
	v_cvt_pk_bf16_f32 v71, v78, v79
	s_nop 0
	v_permlane32_swap_b32_e32 v64, v66
	v_permlane32_swap_b32_e32 v65, v67
	v_permlane32_swap_b32_e32 v68, v70
	v_permlane32_swap_b32_e32 v69, v71
	s_waitcnt lgkmcnt(0)
	ds_read_b128 v[214:217], v167 offset:61440
	ds_read_b128 v[218:221], v168 offset:61440
	ds_read_b128 v[166:169], v169 offset:61440
	ds_read_b128 v[222:225], v170 offset:61440
	ds_read_b128 v[226:229], v171 offset:61440
	ds_read_b128 v[170:173], v172 offset:61440
	v_mfma_f32_32x32x16_bf16 v[48:63], v[64:67], v[182:185], v[48:63]
	v_mfma_f32_32x32x16_bf16 v[32:47], v[64:67], v[190:193], v[32:47]
	v_mfma_f32_32x32x16_bf16 v[16:31], v[64:67], v[198:201], v[16:31]
	v_mfma_f32_32x32x16_bf16 v[0:15], v[64:67], v[206:209], v[0:15]
	v_mfma_f32_32x32x16_bf16 v[48:63], v[68:71], v[186:189], v[48:63]
	v_mfma_f32_32x32x16_bf16 v[32:47], v[68:71], v[194:197], v[32:47]
	v_mfma_f32_32x32x16_bf16 v[16:31], v[68:71], v[202:205], v[16:31]
	v_mfma_f32_32x32x16_bf16 v[0:15], v[68:71], v[210:213], v[0:15]
	s_waitcnt lgkmcnt(0)
	v_mfma_f32_32x32x16_bf16 v[64:79], v[132:135], v[80:83], 0
	v_mfma_f32_32x32x16_bf16 v[64:79], v[136:139], v[84:87], v[64:79]
	v_mfma_f32_32x32x16_bf16 v[64:79], v[140:143], v[88:91], v[64:79]
	v_mfma_f32_32x32x16_bf16 v[64:79], v[174:177], v[92:95], v[64:79]
	v_mfma_f32_32x32x16_bf16 v[64:79], v[162:165], v[96:99], v[64:79]
	v_mfma_f32_32x32x16_bf16 v[64:79], v[178:181], v[100:103], v[64:79]
	s_waitcnt lgkmcnt(0)
	v_mfma_f32_32x32x16_bf16 v[64:79], v[214:217], v[104:107], v[64:79]
	v_mfma_f32_32x32x16_bf16 v[64:79], v[218:221], v[108:111], v[64:79]
	v_mfma_f32_32x32x16_bf16 v[64:79], v[166:169], v[112:115], v[64:79]
	v_mfma_f32_32x32x16_bf16 v[64:79], v[222:225], v[116:119], v[64:79]
	v_mfma_f32_32x32x16_bf16 v[64:79], v[226:229], v[120:123], v[64:79]
	v_mfma_f32_32x32x16_bf16 v[64:79], v[170:173], v[124:127], v[64:79]
	v_add_u32_e32 v158, 0x12000, v158
	v_add_u32_e32 v132, v158, v151
	v_add_u32_e32 v136, v158, v149
	v_add_u32_e32 v140, v158, v148
	v_add_u32_e32 v161, v158, v147
	ds_read_b128 v[132:135], v132
	ds_read_b128 v[136:139], v136
	ds_read_b128 v[140:143], v140
	ds_read_b128 v[162:165], v161
	v_add_u32_e32 v161, v158, v146
	v_add_u32_e32 v170, v158, v150
	ds_read_b128 v[166:169], v161
	ds_read_b128 v[170:173], v170
	ds_read_b64_tr_b16 v[174:175], v145 offset:0x2000
	ds_read_b64_tr_b16 v[176:177], v145 offset:0x2800
	ds_read_b64_tr_b16 v[178:179], v145 offset:0x3000
	ds_read_b64_tr_b16 v[180:181], v145 offset:0x3800
	ds_read_b64_tr_b16 v[182:183], v145 offset:0x2200
	ds_read_b64_tr_b16 v[184:185], v145 offset:0x2a00
	ds_read_b64_tr_b16 v[186:187], v145 offset:0x3200
	ds_read_b64_tr_b16 v[188:189], v145 offset:0x3a00
	ds_read_b64_tr_b16 v[190:191], v145 offset:0x2400
	ds_read_b64_tr_b16 v[192:193], v145 offset:0x2c00
	ds_read_b64_tr_b16 v[194:195], v145 offset:0x3400
	ds_read_b64_tr_b16 v[196:197], v145 offset:0x3c00
	ds_read_b64_tr_b16 v[198:199], v145 offset:0x2600
	ds_read_b64_tr_b16 v[200:201], v145 offset:0x2e00
	ds_read_b64_tr_b16 v[202:203], v145 offset:0x3600
	ds_read_b64_tr_b16 v[204:205], v145 offset:0x3e00
	v_exp_f32_e32 v64, v64
	v_exp_f32_e32 v65, v65
	v_exp_f32_e32 v66, v66
	v_exp_f32_e32 v67, v67
	v_exp_f32_e32 v68, v68
	v_add_f32_e32 v145, 0, v64
	v_exp_f32_e32 v69, v69
	v_add_f32_e32 v145, v65, v145
	v_exp_f32_e32 v70, v70
	v_add_f32_e32 v145, v66, v145
	v_exp_f32_e32 v71, v71
	v_add_f32_e32 v145, v67, v145
	v_exp_f32_e32 v72, v72
	v_add_f32_e32 v145, v68, v145
	v_exp_f32_e32 v73, v73
	v_add_f32_e32 v145, v69, v145
	v_exp_f32_e32 v74, v74
	v_add_f32_e32 v145, v70, v145
	v_exp_f32_e32 v75, v75
	v_add_f32_e32 v145, v71, v145
	v_exp_f32_e32 v76, v76
	v_add_f32_e32 v145, v72, v145
	v_exp_f32_e32 v77, v77
	v_add_f32_e32 v145, v73, v145
	v_exp_f32_e32 v78, v78
	v_add_f32_e32 v145, v74, v145
	v_exp_f32_e32 v79, v79
	v_add_f32_e32 v145, v75, v145
	v_add_f32_e32 v145, v76, v145
	v_add_f32_e32 v145, v77, v145
	v_add_f32_e32 v145, v78, v145
	v_add_f32_e32 v145, v79, v145
	v_add_f32_e32 v161, v144, v145
	v_cvt_pk_bf16_f32 v64, v64, v65
	v_cvt_pk_bf16_f32 v65, v66, v67
	v_cvt_pk_bf16_f32 v66, v68, v69
	v_cvt_pk_bf16_f32 v67, v70, v71
	v_cvt_pk_bf16_f32 v68, v72, v73
	v_cvt_pk_bf16_f32 v69, v74, v75
	v_cvt_pk_bf16_f32 v70, v76, v77
	v_cvt_pk_bf16_f32 v71, v78, v79
	s_nop 0
	v_permlane32_swap_b32_e32 v64, v66
	v_permlane32_swap_b32_e32 v65, v67
	v_permlane32_swap_b32_e32 v68, v70
	v_permlane32_swap_b32_e32 v69, v71
	s_waitcnt lgkmcnt(0)
	v_add_u32_e32 v72, v158, v152
	v_add_u32_e32 v73, v158, v153
	ds_read_b128 v[206:209], v72
	ds_read_b128 v[210:213], v73
	v_add_u32_e32 v72, v158, v154
	v_add_u32_e32 v73, v158, v155
	ds_read_b128 v[214:217], v72
	ds_read_b128 v[218:221], v73
	v_add_u32_e32 v72, v158, v156
	v_add_u32_e32 v73, v158, v157
	ds_read_b128 v[222:225], v72
	ds_read_b128 v[226:229], v73
	s_cmp_lt_u32 s33, 0x100
	s_cbranch_scc1 .Lstg_mla_m62_7
	s_waitcnt vmcnt(0)
	s_barrier

.Lstg_mla_t63_8:
	v_add_u32_e32 v158, s82, v159
	v_add_u32_e32 v132, v158, v151
	v_add_u32_e32 v136, v158, v149
	v_add_u32_e32 v140, v158, v148
	v_add_u32_e32 v144, v158, v147
	ds_read_b128 v[132:135], v132
	ds_read_b128 v[136:139], v136
	ds_read_b128 v[140:143], v140
	ds_read_b128 v[162:165], v144
	v_add_u32_e32 v144, v158, v146
	v_add_u32_e32 v148, v158, v150
	ds_read_b128 v[144:147], v144
	ds_read_b128 v[148:151], v148
	ds_read_b64_tr_b16 v[166:167], v130 offset:0
	ds_read_b64_tr_b16 v[168:169], v130 offset:0x800
	ds_read_b64_tr_b16 v[170:171], v130 offset:0x1000
	ds_read_b64_tr_b16 v[172:173], v130 offset:0x1800
	ds_read_b64_tr_b16 v[174:175], v130 offset:0x200
	ds_read_b64_tr_b16 v[176:177], v130 offset:0xa00
	ds_read_b64_tr_b16 v[178:179], v130 offset:0x1200
	ds_read_b64_tr_b16 v[180:181], v130 offset:0x1a00
	ds_read_b64_tr_b16 v[182:183], v130 offset:0x400
	ds_read_b64_tr_b16 v[184:185], v130 offset:0xc00
	ds_read_b64_tr_b16 v[186:187], v130 offset:0x1400
	ds_read_b64_tr_b16 v[188:189], v130 offset:0x1c00
	ds_read_b64_tr_b16 v[190:191], v130 offset:0x600
	ds_read_b64_tr_b16 v[192:193], v130 offset:0xe00
	ds_read_b64_tr_b16 v[194:195], v130 offset:0x1600
	ds_read_b64_tr_b16 v[196:197], v130 offset:0x1e00
	v_exp_f32_e32 v64, v64
	v_exp_f32_e32 v65, v65
	v_exp_f32_e32 v66, v66
	v_exp_f32_e32 v67, v67
	v_exp_f32_e32 v68, v68
	v_add_f32_e32 v159, 0, v64
	v_exp_f32_e32 v69, v69
	v_add_f32_e32 v159, v65, v159
	v_exp_f32_e32 v70, v70
	v_add_f32_e32 v159, v66, v159
	v_exp_f32_e32 v71, v71
	v_add_f32_e32 v159, v67, v159
	v_exp_f32_e32 v72, v72
	v_add_f32_e32 v159, v68, v159
	v_exp_f32_e32 v73, v73
	v_add_f32_e32 v159, v69, v159
	v_exp_f32_e32 v74, v74
	v_add_f32_e32 v159, v70, v159
	v_exp_f32_e32 v75, v75
	v_add_f32_e32 v159, v71, v159
	v_exp_f32_e32 v76, v76
	v_add_f32_e32 v159, v72, v159
	v_exp_f32_e32 v77, v77
	v_add_f32_e32 v159, v73, v159
	v_exp_f32_e32 v78, v78
	v_add_f32_e32 v159, v74, v159
	v_exp_f32_e32 v79, v79
	v_add_f32_e32 v159, v75, v159
	v_add_f32_e32 v159, v76, v159
	v_add_f32_e32 v159, v77, v159
	v_add_f32_e32 v159, v78, v159
	v_add_f32_e32 v159, v79, v159
	v_add_f32_e32 v161, v161, v159
	v_cvt_pk_bf16_f32 v64, v64, v65
	v_cvt_pk_bf16_f32 v65, v66, v67
	v_cvt_pk_bf16_f32 v66, v68, v69
	v_cvt_pk_bf16_f32 v67, v70, v71
	v_cvt_pk_bf16_f32 v68, v72, v73
	v_cvt_pk_bf16_f32 v69, v74, v75
	v_cvt_pk_bf16_f32 v70, v76, v77
	v_cvt_pk_bf16_f32 v71, v78, v79
	s_nop 0
	v_permlane32_swap_b32_e32 v64, v66
	v_permlane32_swap_b32_e32 v65, v67
	v_permlane32_swap_b32_e32 v68, v70
	v_permlane32_swap_b32_e32 v69, v71
	s_waitcnt lgkmcnt(0)
	v_add_u32_e32 v72, v158, v152
	v_add_u32_e32 v73, v158, v153
	ds_read_b128 v[198:201], v72
	ds_read_b128 v[202:205], v73
	v_add_u32_e32 v72, v158, v154
	v_add_u32_e32 v73, v158, v155
	ds_read_b128 v[152:155], v72
	ds_read_b128 v[206:209], v73
	v_add_u32_e32 v72, v158, v156
	v_add_u32_e32 v73, v158, v157
	ds_read_b128 v[156:159], v72
	ds_read_b128 v[210:213], v73
	v_mfma_f32_32x32x16_bf16 v[48:63], v[64:67], v[166:169], v[48:63]
	v_mfma_f32_32x32x16_bf16 v[32:47], v[64:67], v[174:177], v[32:47]
	v_mfma_f32_32x32x16_bf16 v[16:31], v[64:67], v[182:185], v[16:31]
	v_mfma_f32_32x32x16_bf16 v[0:15], v[64:67], v[190:193], v[0:15]
	v_mfma_f32_32x32x16_bf16 v[48:63], v[68:71], v[170:173], v[48:63]
	v_mfma_f32_32x32x16_bf16 v[32:47], v[68:71], v[178:181], v[32:47]
	v_mfma_f32_32x32x16_bf16 v[16:31], v[68:71], v[186:189], v[16:31]
	v_mfma_f32_32x32x16_bf16 v[0:15], v[68:71], v[194:197], v[0:15]
	s_waitcnt lgkmcnt(0)
; template <int TAG = 0> DI int fresh_tid(int wv) { int l; asm volatile("v_mbcnt_lo_u32_b32 %0, -1, 0\n\tv_mbcnt_hi_u32_b32 %0, -1, %0 ; site %1" : "=v"(l) : "n"(TAG)); return wv * 64 + l; }
; DI float swap_sum(float v) { auto rr = __builtin_amdgcn_permlane32_swap(__float_as_uint(v), __float_as_uint(v), false, false); return __uint_as_float(rr[0]) + __uint_as_float(rr[1]); }
; template <int DQK, int MODE, int LDQ, int LDK, int LDV> ...
;     ...
;     __builtin_amdgcn_s_setprio(0);
;     ...
;     l_reg = swap_sum(l_reg);
;     { const int lane2 = fresh_tid<110 + MODE>(wv) & 63, r32 = lane2 & 31, hi = lane2 >> 5;
;     if (hi == 0) li_l[r32] = l_reg;
	v_mfma_f32_32x32x16_bf16 v[64:79], v[132:135], v[80:83], 0
	v_mfma_f32_32x32x16_bf16 v[64:79], v[136:139], v[84:87], v[64:79]
	v_mfma_f32_32x32x16_bf16 v[64:79], v[140:143], v[88:91], v[64:79]
	v_mfma_f32_32x32x16_bf16 v[64:79], v[162:165], v[92:95], v[64:79]
	v_mfma_f32_32x32x16_bf16 v[64:79], v[144:147], v[96:99], v[64:79]
	v_mfma_f32_32x32x16_bf16 v[64:79], v[148:151], v[100:103], v[64:79]
	s_waitcnt lgkmcnt(0)
	v_mfma_f32_32x32x16_bf16 v[64:79], v[198:201], v[104:107], v[64:79]
	v_mfma_f32_32x32x16_bf16 v[64:79], v[202:205], v[108:111], v[64:79]
	v_mfma_f32_32x32x16_bf16 v[64:79], v[152:155], v[112:115], v[64:79]
	v_mfma_f32_32x32x16_bf16 v[64:79], v[206:209], v[116:119], v[64:79]
	v_mfma_f32_32x32x16_bf16 v[64:79], v[156:159], v[120:123], v[64:79]
	v_mfma_f32_32x32x16_bf16 v[64:79], v[210:213], v[124:127], v[64:79]
	ds_read_b64_tr_b16 v[80:81], v130 offset:0x2000
	ds_read_b64_tr_b16 v[82:83], v130 offset:0x2800
	ds_read_b64_tr_b16 v[84:85], v130 offset:0x3000
	ds_read_b64_tr_b16 v[86:87], v130 offset:0x3800
	ds_read_b64_tr_b16 v[88:89], v130 offset:0x2200
	ds_read_b64_tr_b16 v[90:91], v130 offset:0x2a00
	ds_read_b64_tr_b16 v[92:93], v130 offset:0x3200
	ds_read_b64_tr_b16 v[94:95], v130 offset:0x3a00
	ds_read_b64_tr_b16 v[96:97], v130 offset:0x2400
	ds_read_b64_tr_b16 v[98:99], v130 offset:0x2c00
	ds_read_b64_tr_b16 v[100:101], v130 offset:0x3400
	ds_read_b64_tr_b16 v[102:103], v130 offset:0x3c00
	ds_read_b64_tr_b16 v[104:105], v130 offset:0x2600
	ds_read_b64_tr_b16 v[106:107], v130 offset:0x2e00
	ds_read_b64_tr_b16 v[108:109], v130 offset:0x3600
	ds_read_b64_tr_b16 v[110:111], v130 offset:0x3e00
	s_nop 11
	v_exp_f32_e32 v112, v64
	v_exp_f32_e32 v65, v65
	v_exp_f32_e32 v113, v66
	v_exp_f32_e32 v67, v67
	v_exp_f32_e32 v68, v68
	v_add_f32_e32 v64, 0, v112
	v_exp_f32_e32 v69, v69
	v_add_f32_e32 v64, v65, v64
	v_exp_f32_e32 v70, v70
	v_add_f32_e32 v64, v113, v64
	v_exp_f32_e32 v71, v71
	v_add_f32_e32 v64, v67, v64
	v_exp_f32_e32 v72, v72
	v_add_f32_e32 v64, v68, v64
	v_exp_f32_e32 v73, v73
	v_add_f32_e32 v64, v69, v64
	v_exp_f32_e32 v74, v74
	v_add_f32_e32 v64, v70, v64
	v_exp_f32_e32 v75, v75
	v_add_f32_e32 v64, v71, v64
	v_exp_f32_e32 v76, v76
	v_add_f32_e32 v64, v72, v64
	v_exp_f32_e32 v77, v77
	v_add_f32_e32 v64, v73, v64
	v_exp_f32_e32 v78, v78
	v_add_f32_e32 v64, v74, v64
	v_exp_f32_e32 v79, v79
	v_add_f32_e32 v64, v75, v64
	v_add_f32_e32 v64, v76, v64
	v_add_f32_e32 v64, v77, v64
	v_add_f32_e32 v64, v78, v64
	v_add_f32_e32 v64, v79, v64
	v_add_f32_e32 v64, v161, v64
	v_cvt_pk_bf16_f32 v66, v112, v65
	v_cvt_pk_bf16_f32 v67, v113, v67
	v_cvt_pk_bf16_f32 v68, v68, v69
	v_cvt_pk_bf16_f32 v69, v70, v71
	v_cvt_pk_bf16_f32 v70, v72, v73
	v_cvt_pk_bf16_f32 v71, v74, v75
	v_cvt_pk_bf16_f32 v72, v76, v77
	v_cvt_pk_bf16_f32 v73, v78, v79
	s_nop 0
	v_permlane32_swap_b32_e32 v66, v68
	v_permlane32_swap_b32_e32 v67, v69
	v_permlane32_swap_b32_e32 v70, v72
	v_permlane32_swap_b32_e32 v71, v73
	s_waitcnt lgkmcnt(0)
	v_mfma_f32_32x32x16_bf16 v[48:63], v[66:69], v[80:83], v[48:63]
	v_mfma_f32_32x32x16_bf16 v[32:47], v[66:69], v[88:91], v[32:47]
	v_mfma_f32_32x32x16_bf16 v[16:31], v[66:69], v[96:99], v[16:31]
	v_mfma_f32_32x32x16_bf16 v[0:15], v[66:69], v[104:107], v[0:15]
	v_mfma_f32_32x32x16_bf16 v[48:63], v[70:73], v[84:87], v[48:63]
	v_mfma_f32_32x32x16_bf16 v[32:47], v[70:73], v[92:95], v[32:47]
	v_mfma_f32_32x32x16_bf16 v[16:31], v[70:73], v[100:103], v[16:31]
	v_mfma_f32_32x32x16_bf16 v[0:15], v[70:73], v[108:111], v[0:15]
	s_setprio 0
	v_mbcnt_lo_u32_b32 v66, -1, 0
	v_mbcnt_hi_u32_b32 v66, -1, v66
	v_mov_b32_e32 v67, v64
	v_and_b32_e32 v65, 31, v66
	v_bfe_u32 v66, v66, 5, 1
	v_permlane32_swap_b32_e32 v64, v67
	v_cmp_eq_u32_e32 vcc, 0, v66
	s_and_saveexec_b64 s[2:3], vcc
	s_cbranch_execz .LBB0_1910
	v_lshl_add_u32 v68, v65, 2, s4
	v_add_f32_e32 v64, v64, v67
	ds_write_b32 v68, v64
	s_branch .LBB0_1910
